# S13 plus GEMM main loops: merged the back-to-back s_setprio 0/1 flip inside each 32-MFMA block and dropped the redundant lgkmcnt(0) after the barrier
# speedup vs baseline: 1.0024x; 1.0007x over previous
; #define PG8_STAGE(bufoff, gbase, voff) do { _Pragma("unroll") for (int _i = 0; _i < 2; ++_i) \
;         __builtin_amdgcn_global_load_lds((const unsigned*)((const char*)(gbase) + (voff)[_i]), (LAS unsigned*)(lds + (bufoff) + ldsw + _i * 8192), 16, 0, 0); } while (0)
; #define PG8_LDA(dst, b, h) do { _Pragma("unroll") for (int m = 0; m < 4; ++m) _Pragma("unroll") for (int k = 0; k < 2; ++k) dst[m][k] = *(const LAS bf16x8*)(lds + PG8_SA(b, h) + aoff + m * 2048 + k * 1024); } while (0)
; #define PG8_LDB(dst, b, h) do { _Pragma("unroll") for (int n = 0; n < 2; ++n) _Pragma("unroll") for (int k = 0; k < 2; ++k) dst[n][k] = *(const LAS bf16x8*)(lds + PG8_SB(b, h) + boff + n * 2048 + k * 1024); } while (0)
; #define PG8_MMA(ai, bj, At, Bt) do { __builtin_amdgcn_s_setprio(1); _Pragma("unroll") for (int m = 0; m < 4; ++m) _Pragma("unroll") for (int n = 0; n < 2; ++n) _Pragma("unroll") for (int k = 0; k < 2; ++k) \
;         acc[ai][bj][m][n] = __builtin_amdgcn_mfma_f32_16x16x32_bf16(Bt[n][k], At[m][k], acc[ai][bj][m][n], 0, 0, 0); __builtin_amdgcn_s_setprio(0); } while (0)
; #define PG8_WAIT_V(n) asm volatile("s_waitcnt vmcnt(" #n ")" ::: "memory")
; template <int K, int LDA, int LDB, class Epi, class Sched>
; __device__ __forceinline__ void gemm_phase(LAS unsigned char* lds, const Gemm g, const Sched& S, const Epi& E, int wv) {
;     ...
;             PG8_LDB(B0, 0, 0); PG8_LDB(B1, 0, 1); PG8_SCHED; PG8_LDA(At, 0, 0); PG8_STAGE(PG8_SA(1, 1), a1 + hstepA, voffA);
;             PG8_WAIT_V(8); PG8_WAIT_L(0); PG8_BAR; PG8_MMA(0, 0, At, B0); PG8_MMA(0, 1, At, B1); PG8_BAR; PG8_SCHED;
;             PG8_LDA(At, 0, 1); PG8_STAGE(PG8_SB(0, 0), b2, voffB); PG8_STAGE(PG8_SB(0, 1), b2 + hstepB, voffB); PG8_STAGE(PG8_SA(0, 0), a2, voffA);
;             PG8_WAIT_V(8); PG8_WAIT_L(0); PG8_BAR; PG8_MMA(1, 0, At, B0); PG8_MMA(1, 1, At, B1); PG8_BAR; PG8_SCHED;
;             PG8_LDB(B0, 1, 0); PG8_LDB(B1, 1, 1); PG8_SCHED; PG8_LDA(At, 1, 0); PG8_STAGE(PG8_SA(0, 1), a2 + hstepA, voffA);
;             PG8_WAIT_V(8); PG8_WAIT_L(0); PG8_BAR; PG8_MMA(0, 0, At, B0); PG8_MMA(0, 1, At, B1); PG8_BAR; PG8_SCHED;
;             PG8_LDA(At, 1, 1); PG8_STAGE(PG8_SB(1, 0), b3, voffB); PG8_STAGE(PG8_SB(1, 1), b3 + hstepB, voffB); PG8_STAGE(PG8_SA(1, 0), a3, voffA);
;             PG8_WAIT_V(8); PG8_WAIT_L(0); PG8_BAR; PG8_MMA(1, 0, At, B0); PG8_MMA(1, 1, At, B1); PG8_BAR; PG8_SCHED;
.LBB0_273:
	s_waitcnt lgkmcnt(0)
	ds_read_b128 v[152:155], v163
	ds_read_b128 v[156:159], v163 offset:1024
	ds_read_b128 v[166:169], v163 offset:2048
	ds_read_b128 v[170:173], v163 offset:3072
	ds_read_b128 v[174:177], v164
	ds_read_b128 v[178:181], v164 offset:1024
	ds_read_b128 v[182:185], v164 offset:2048
	ds_read_b128 v[186:189], v164 offset:3072
	s_add_u32 s14, s74, 0xfff80080
	s_addc_u32 s15, s75, -1
	s_cmp_eq_u32 s89, 28
	s_cselect_b32 s79, s65, s15
	s_cselect_b32 s78, s71, s14
	s_cselect_b32 s77, s63, s88
	s_cselect_b32 s76, s80, s84
	s_add_i32 m0, s41, 0xc000
	ds_read_b128 v[190:193], v165
	ds_read_b128 v[194:197], v165 offset:1024
	ds_read_b128 v[198:201], v165 offset:2048
	ds_read_b128 v[202:205], v165 offset:3072
	ds_read_b128 v[206:209], v165 offset:4096
	ds_read_b128 v[210:213], v165 offset:5120
	ds_read_b128 v[214:217], v165 offset:6144
	ds_read_b128 v[218:221], v165 offset:7168
	global_load_lds_dwordx4 v144, s[74:75]
	s_add_i32 m0, s41, 0xe000
	s_nop 0
	global_load_lds_dwordx4 v146, s[74:75]
	s_waitcnt vmcnt(8)
	s_waitcnt lgkmcnt(0)
	s_barrier
	s_setprio 1
	v_mfma_f32_16x16x32_bf16 v[60:63], v[152:155], v[190:193], v[60:63]
	v_mfma_f32_16x16x32_bf16 v[56:59], v[166:169], v[190:193], v[56:59]
	v_mfma_f32_16x16x32_bf16 v[52:55], v[152:155], v[198:201], v[52:55]
	v_mfma_f32_16x16x32_bf16 v[48:51], v[166:169], v[198:201], v[48:51]
	v_mfma_f32_16x16x32_bf16 v[44:47], v[152:155], v[206:209], v[44:47]
	v_mfma_f32_16x16x32_bf16 v[40:43], v[166:169], v[206:209], v[40:43]
	v_mfma_f32_16x16x32_bf16 v[36:39], v[152:155], v[214:217], v[36:39]
	v_mfma_f32_16x16x32_bf16 v[32:35], v[166:169], v[214:217], v[32:35]
	v_mfma_f32_16x16x32_bf16 v[60:63], v[156:159], v[194:197], v[60:63]
	v_mfma_f32_16x16x32_bf16 v[56:59], v[170:173], v[194:197], v[56:59]
	v_mfma_f32_16x16x32_bf16 v[52:55], v[156:159], v[202:205], v[52:55]
	v_mfma_f32_16x16x32_bf16 v[48:51], v[170:173], v[202:205], v[48:51]
	v_mfma_f32_16x16x32_bf16 v[44:47], v[156:159], v[210:213], v[44:47]
	v_mfma_f32_16x16x32_bf16 v[40:43], v[170:173], v[210:213], v[40:43]
	v_mfma_f32_16x16x32_bf16 v[36:39], v[156:159], v[218:221], v[36:39]
	v_mfma_f32_16x16x32_bf16 v[32:35], v[170:173], v[218:221], v[32:35]
	v_mfma_f32_16x16x32_bf16 v[124:127], v[174:177], v[190:193], v[124:127]
	v_mfma_f32_16x16x32_bf16 v[120:123], v[182:185], v[190:193], v[120:123]
	v_mfma_f32_16x16x32_bf16 v[116:119], v[174:177], v[198:201], v[116:119]
	v_mfma_f32_16x16x32_bf16 v[112:115], v[182:185], v[198:201], v[112:115]
	v_mfma_f32_16x16x32_bf16 v[108:111], v[174:177], v[206:209], v[108:111]
	v_mfma_f32_16x16x32_bf16 v[104:107], v[182:185], v[206:209], v[104:107]
	v_mfma_f32_16x16x32_bf16 v[100:103], v[174:177], v[214:217], v[100:103]
	v_mfma_f32_16x16x32_bf16 v[96:99], v[182:185], v[214:217], v[96:99]
	v_mfma_f32_16x16x32_bf16 v[124:127], v[178:181], v[194:197], v[124:127]
	v_mfma_f32_16x16x32_bf16 v[120:123], v[186:189], v[194:197], v[120:123]
	v_mfma_f32_16x16x32_bf16 v[116:119], v[178:181], v[202:205], v[116:119]
	v_mfma_f32_16x16x32_bf16 v[112:115], v[186:189], v[202:205], v[112:115]
	v_mfma_f32_16x16x32_bf16 v[108:111], v[178:181], v[210:213], v[108:111]
	v_mfma_f32_16x16x32_bf16 v[104:107], v[186:189], v[210:213], v[104:107]
	v_mfma_f32_16x16x32_bf16 v[100:103], v[178:181], v[218:221], v[100:103]
	v_mfma_f32_16x16x32_bf16 v[96:99], v[186:189], v[218:221], v[96:99]
	s_setprio 0
	s_barrier
	s_add_i32 s14, s82, s24
	s_mov_b32 m0, s14
	ds_read_b128 v[190:193], v165 offset:16384
	ds_read_b128 v[194:197], v165 offset:17408
	ds_read_b128 v[198:201], v165 offset:18432
	ds_read_b128 v[202:205], v165 offset:19456
	ds_read_b128 v[206:209], v165 offset:20480
	ds_read_b128 v[210:213], v165 offset:21504
	ds_read_b128 v[214:217], v165 offset:22528
	ds_read_b128 v[218:221], v165 offset:23552
	global_load_lds_dwordx4 v130, s[76:77]
	s_add_i32 m0, s14, 0x2000
	s_add_u32 s14, s76, 0x80000
	s_addc_u32 s15, s77, 0
	s_add_i32 s34, s83, s24
	global_load_lds_dwordx4 v134, s[76:77]
	s_mov_b32 m0, s34
	s_nop 0
	global_load_lds_dwordx4 v130, s[14:15]
	s_add_i32 m0, s34, 0x2000
	s_nop 0
	global_load_lds_dwordx4 v134, s[14:15]
	s_mov_b32 m0, s41
	s_nop 0
	global_load_lds_dwordx4 v128, s[78:79]
	s_mov_b32 m0, s43
	s_nop 0
	global_load_lds_dwordx4 v132, s[78:79]
	s_waitcnt vmcnt(8)
	s_waitcnt lgkmcnt(0)
	s_barrier
	s_setprio 1
	v_mfma_f32_16x16x32_bf16 v[28:31], v[152:155], v[190:193], v[28:31]
	v_mfma_f32_16x16x32_bf16 v[24:27], v[166:169], v[190:193], v[24:27]
	v_mfma_f32_16x16x32_bf16 v[20:23], v[152:155], v[198:201], v[20:23]
	v_mfma_f32_16x16x32_bf16 v[16:19], v[166:169], v[198:201], v[16:19]
	v_mfma_f32_16x16x32_bf16 v[12:15], v[152:155], v[206:209], v[12:15]
	v_mfma_f32_16x16x32_bf16 v[8:11], v[166:169], v[206:209], v[8:11]
	v_mfma_f32_16x16x32_bf16 v[4:7], v[152:155], v[214:217], v[4:7]
	v_mfma_f32_16x16x32_bf16 v[0:3], v[166:169], v[214:217], v[0:3]
	v_mfma_f32_16x16x32_bf16 v[28:31], v[156:159], v[194:197], v[28:31]
	v_mfma_f32_16x16x32_bf16 v[24:27], v[170:173], v[194:197], v[24:27]
	v_mfma_f32_16x16x32_bf16 v[20:23], v[156:159], v[202:205], v[20:23]
	v_mfma_f32_16x16x32_bf16 v[16:19], v[170:173], v[202:205], v[16:19]
	v_mfma_f32_16x16x32_bf16 v[12:15], v[156:159], v[210:213], v[12:15]
	v_mfma_f32_16x16x32_bf16 v[8:11], v[170:173], v[210:213], v[8:11]
	v_mfma_f32_16x16x32_bf16 v[4:7], v[156:159], v[218:221], v[4:7]
	v_mfma_f32_16x16x32_bf16 v[0:3], v[170:173], v[218:221], v[0:3]
	v_mfma_f32_16x16x32_bf16 v[92:95], v[174:177], v[190:193], v[92:95]
	v_mfma_f32_16x16x32_bf16 v[88:91], v[182:185], v[190:193], v[88:91]
	v_mfma_f32_16x16x32_bf16 v[84:87], v[174:177], v[198:201], v[84:87]
	v_mfma_f32_16x16x32_bf16 v[80:83], v[182:185], v[198:201], v[80:83]
	v_mfma_f32_16x16x32_bf16 v[76:79], v[174:177], v[206:209], v[76:79]
	v_mfma_f32_16x16x32_bf16 v[72:75], v[182:185], v[206:209], v[72:75]
	v_mfma_f32_16x16x32_bf16 v[68:71], v[174:177], v[214:217], v[68:71]
	v_mfma_f32_16x16x32_bf16 v[64:67], v[182:185], v[214:217], v[64:67]
	v_mfma_f32_16x16x32_bf16 v[92:95], v[178:181], v[194:197], v[92:95]
	v_mfma_f32_16x16x32_bf16 v[88:91], v[186:189], v[194:197], v[88:91]
	v_mfma_f32_16x16x32_bf16 v[84:87], v[178:181], v[202:205], v[84:87]
	v_mfma_f32_16x16x32_bf16 v[80:83], v[186:189], v[202:205], v[80:83]
	v_mfma_f32_16x16x32_bf16 v[76:79], v[178:181], v[210:213], v[76:79]
	v_mfma_f32_16x16x32_bf16 v[72:75], v[186:189], v[210:213], v[72:75]
	v_mfma_f32_16x16x32_bf16 v[68:71], v[178:181], v[218:221], v[68:71]
	v_mfma_f32_16x16x32_bf16 v[64:67], v[186:189], v[218:221], v[64:67]
	s_setprio 0
	s_barrier
; #define PG8_STAGE(bufoff, gbase, voff) do { _Pragma("unroll") for (int _i = 0; _i < 2; ++_i) \
;         __builtin_amdgcn_global_load_lds((const unsigned*)((const char*)(gbase) + (voff)[_i]), (LAS unsigned*)(lds + (bufoff) + ldsw + _i * 8192), 16, 0, 0); } while (0)
; #define PG8_LDA(dst, b, h) do { _Pragma("unroll") for (int m = 0; m < 4; ++m) _Pragma("unroll") for (int k = 0; k < 2; ++k) dst[m][k] = *(const LAS bf16x8*)(lds + PG8_SA(b, h) + aoff + m * 2048 + k * 1024); } while (0)
; #define PG8_LDB(dst, b, h) do { _Pragma("unroll") for (int n = 0; n < 2; ++n) _Pragma("unroll") for (int k = 0; k < 2; ++k) dst[n][k] = *(const LAS bf16x8*)(lds + PG8_SB(b, h) + boff + n * 2048 + k * 1024); } while (0)
; #define PG8_MMA(ai, bj, At, Bt) do { __builtin_amdgcn_s_setprio(1); _Pragma("unroll") for (int m = 0; m < 4; ++m) _Pragma("unroll") for (int n = 0; n < 2; ++n) _Pragma("unroll") for (int k = 0; k < 2; ++k) \
;         acc[ai][bj][m][n] = __builtin_amdgcn_mfma_f32_16x16x32_bf16(Bt[n][k], At[m][k], acc[ai][bj][m][n], 0, 0, 0); __builtin_amdgcn_s_setprio(0); } while (0)
; #define PG8_WAIT_V(n) asm volatile("s_waitcnt vmcnt(" #n ")" ::: "memory")
; #define PG8_WAIT_L(n) asm volatile("s_waitcnt lgkmcnt(" #n ")" ::: "memory")
; #define PG8_BAR __builtin_amdgcn_s_barrier()
; #define PG8_SCHED __builtin_amdgcn_sched_barrier(0)
; template <int K, int LDA, int LDB, class Epi, class Sched>
; __device__ __forceinline__ void gemm_phase(LAS unsigned char* lds, const Gemm g, const Sched& S, const Epi& E, int wv) {
;     ...
;             PG8_LDB(B0, 1, 0); PG8_LDB(B1, 1, 1); PG8_SCHED; PG8_LDA(At, 1, 0); PG8_STAGE(PG8_SA(0, 1), a2 + hstepA, voffA);
;             PG8_WAIT_V(8); PG8_WAIT_L(0); PG8_BAR; PG8_MMA(0, 0, At, B0); PG8_MMA(0, 1, At, B1); PG8_BAR; PG8_SCHED;
;             PG8_LDA(At, 1, 1); PG8_STAGE(PG8_SB(1, 0), b3, voffB); PG8_STAGE(PG8_SB(1, 1), b3 + hstepB, voffB); PG8_STAGE(PG8_SA(1, 0), a3, voffA);
;             PG8_WAIT_V(8); PG8_WAIT_L(0); PG8_BAR; PG8_MMA(1, 0, At, B0); PG8_MMA(1, 1, At, B1); PG8_BAR; PG8_SCHED;
;         }
;         if (wr == 0) PG8_BAR;
	s_add_i32 s34, 0, 0x18000
	v_add_u32_e32 v136, s34, v161
	s_add_i32 s35, 0, 0x1c000
	ds_read_b128 v[152:155], v136
	ds_read_b128 v[156:159], v136 offset:1024
	ds_read_b128 v[166:169], v136 offset:2048
	ds_read_b128 v[170:173], v136 offset:3072
	v_add_u32_e32 v136, s35, v161
	ds_read_b128 v[174:177], v136
	ds_read_b128 v[178:181], v136 offset:1024
	ds_read_b128 v[182:185], v136 offset:2048
	ds_read_b128 v[186:189], v136 offset:3072
	s_add_u32 s14, s78, 0x80000
	s_addc_u32 s15, s79, 0
	s_mov_b32 m0, s51
	ds_read_b128 v[190:193], v165 offset:32768
	ds_read_b128 v[194:197], v165 offset:33792
	ds_read_b128 v[198:201], v165 offset:34816
	ds_read_b128 v[202:205], v165 offset:35840
	ds_read_b128 v[206:209], v165 offset:36864
	ds_read_b128 v[210:213], v165 offset:37888
	ds_read_b128 v[214:217], v165 offset:38912
	ds_read_b128 v[218:221], v165 offset:39936
	global_load_lds_dwordx4 v128, s[14:15]
	s_mov_b32 m0, s59
	s_nop 0
	global_load_lds_dwordx4 v132, s[14:15]
	s_waitcnt vmcnt(8)
	s_waitcnt lgkmcnt(0)
	s_barrier
	s_setprio 1
	v_mfma_f32_16x16x32_bf16 v[60:63], v[152:155], v[190:193], v[60:63]
	v_mfma_f32_16x16x32_bf16 v[56:59], v[166:169], v[190:193], v[56:59]
	v_mfma_f32_16x16x32_bf16 v[52:55], v[152:155], v[198:201], v[52:55]
	v_mfma_f32_16x16x32_bf16 v[48:51], v[166:169], v[198:201], v[48:51]
	v_mfma_f32_16x16x32_bf16 v[44:47], v[152:155], v[206:209], v[44:47]
	v_mfma_f32_16x16x32_bf16 v[40:43], v[166:169], v[206:209], v[40:43]
	v_mfma_f32_16x16x32_bf16 v[36:39], v[152:155], v[214:217], v[36:39]
	v_mfma_f32_16x16x32_bf16 v[32:35], v[166:169], v[214:217], v[32:35]
	v_mfma_f32_16x16x32_bf16 v[60:63], v[156:159], v[194:197], v[60:63]
	v_mfma_f32_16x16x32_bf16 v[56:59], v[170:173], v[194:197], v[56:59]
	v_mfma_f32_16x16x32_bf16 v[52:55], v[156:159], v[202:205], v[52:55]
	v_mfma_f32_16x16x32_bf16 v[48:51], v[170:173], v[202:205], v[48:51]
	v_mfma_f32_16x16x32_bf16 v[44:47], v[156:159], v[210:213], v[44:47]
	v_mfma_f32_16x16x32_bf16 v[40:43], v[170:173], v[210:213], v[40:43]
	v_mfma_f32_16x16x32_bf16 v[36:39], v[156:159], v[218:221], v[36:39]
	v_mfma_f32_16x16x32_bf16 v[32:35], v[170:173], v[218:221], v[32:35]
	v_mfma_f32_16x16x32_bf16 v[124:127], v[174:177], v[190:193], v[124:127]
	v_mfma_f32_16x16x32_bf16 v[120:123], v[182:185], v[190:193], v[120:123]
	v_mfma_f32_16x16x32_bf16 v[116:119], v[174:177], v[198:201], v[116:119]
	v_mfma_f32_16x16x32_bf16 v[112:115], v[182:185], v[198:201], v[112:115]
	v_mfma_f32_16x16x32_bf16 v[108:111], v[174:177], v[206:209], v[108:111]
	v_mfma_f32_16x16x32_bf16 v[104:107], v[182:185], v[206:209], v[104:107]
	v_mfma_f32_16x16x32_bf16 v[100:103], v[174:177], v[214:217], v[100:103]
	v_mfma_f32_16x16x32_bf16 v[96:99], v[182:185], v[214:217], v[96:99]
	v_mfma_f32_16x16x32_bf16 v[124:127], v[178:181], v[194:197], v[124:127]
	v_mfma_f32_16x16x32_bf16 v[120:123], v[186:189], v[194:197], v[120:123]
	v_mfma_f32_16x16x32_bf16 v[116:119], v[178:181], v[202:205], v[116:119]
	v_mfma_f32_16x16x32_bf16 v[112:115], v[186:189], v[202:205], v[112:115]
	v_mfma_f32_16x16x32_bf16 v[108:111], v[178:181], v[210:213], v[108:111]
	v_mfma_f32_16x16x32_bf16 v[104:107], v[186:189], v[210:213], v[104:107]
	v_mfma_f32_16x16x32_bf16 v[100:103], v[178:181], v[218:221], v[100:103]
	v_mfma_f32_16x16x32_bf16 v[96:99], v[186:189], v[218:221], v[96:99]
	s_setprio 0
	s_barrier
	s_add_i32 s14, s34, s24
	s_mov_b32 m0, s14
	ds_read_b128 v[190:193], v165 offset:49152
	ds_read_b128 v[194:197], v165 offset:50176
	ds_read_b128 v[198:201], v165 offset:51200
	ds_read_b128 v[202:205], v165 offset:52224
	ds_read_b128 v[206:209], v165 offset:53248
	ds_read_b128 v[210:213], v165 offset:54272
	ds_read_b128 v[214:217], v165 offset:55296
	ds_read_b128 v[218:221], v165 offset:56320
	s_add_u32 s98, s76, s10
	s_addc_u32 s99, s77, s11
	global_load_lds_dwordx4 v130, s[98:99]
	s_add_i32 m0, s14, 0x2000
	s_add_u32 s14, s76, 0x80080
	s_addc_u32 s15, s77, 0
	s_add_i32 s34, s35, s24
	global_load_lds_dwordx4 v134, s[98:99]
	s_mov_b32 m0, s34
	s_nop 0
	global_load_lds_dwordx4 v130, s[14:15]
	s_add_i32 m0, s34, 0x2000
	s_nop 0
	global_load_lds_dwordx4 v134, s[14:15]
	s_mov_b32 m0, s61
	s_nop 0
	s_add_u32 s100, s78, s10
	s_addc_u32 s101, s79, s11
	global_load_lds_dwordx4 v128, s[100:101]
	s_mov_b32 m0, s73
	s_nop 0
	global_load_lds_dwordx4 v132, s[100:101]
	s_waitcnt vmcnt(8)
	s_waitcnt lgkmcnt(0)
	s_barrier
	s_setprio 1
	v_mfma_f32_16x16x32_bf16 v[28:31], v[152:155], v[190:193], v[28:31]
	v_mfma_f32_16x16x32_bf16 v[24:27], v[166:169], v[190:193], v[24:27]
	v_mfma_f32_16x16x32_bf16 v[20:23], v[152:155], v[198:201], v[20:23]
	v_mfma_f32_16x16x32_bf16 v[16:19], v[166:169], v[198:201], v[16:19]
	v_mfma_f32_16x16x32_bf16 v[12:15], v[152:155], v[206:209], v[12:15]
	v_mfma_f32_16x16x32_bf16 v[8:11], v[166:169], v[206:209], v[8:11]
	v_mfma_f32_16x16x32_bf16 v[4:7], v[152:155], v[214:217], v[4:7]
	v_mfma_f32_16x16x32_bf16 v[0:3], v[166:169], v[214:217], v[0:3]
	v_mfma_f32_16x16x32_bf16 v[28:31], v[156:159], v[194:197], v[28:31]
	v_mfma_f32_16x16x32_bf16 v[24:27], v[170:173], v[194:197], v[24:27]
	v_mfma_f32_16x16x32_bf16 v[20:23], v[156:159], v[202:205], v[20:23]
	v_mfma_f32_16x16x32_bf16 v[16:19], v[170:173], v[202:205], v[16:19]
	v_mfma_f32_16x16x32_bf16 v[12:15], v[156:159], v[210:213], v[12:15]
	v_mfma_f32_16x16x32_bf16 v[8:11], v[170:173], v[210:213], v[8:11]
	v_mfma_f32_16x16x32_bf16 v[4:7], v[156:159], v[218:221], v[4:7]
	v_mfma_f32_16x16x32_bf16 v[0:3], v[170:173], v[218:221], v[0:3]
	v_mfma_f32_16x16x32_bf16 v[92:95], v[174:177], v[190:193], v[92:95]
	v_mfma_f32_16x16x32_bf16 v[88:91], v[182:185], v[190:193], v[88:91]
	v_mfma_f32_16x16x32_bf16 v[84:87], v[174:177], v[198:201], v[84:87]
	v_mfma_f32_16x16x32_bf16 v[80:83], v[182:185], v[198:201], v[80:83]
	v_mfma_f32_16x16x32_bf16 v[76:79], v[174:177], v[206:209], v[76:79]
	v_mfma_f32_16x16x32_bf16 v[72:75], v[182:185], v[206:209], v[72:75]
	v_mfma_f32_16x16x32_bf16 v[68:71], v[174:177], v[214:217], v[68:71]
	v_mfma_f32_16x16x32_bf16 v[64:67], v[182:185], v[214:217], v[64:67]
	v_mfma_f32_16x16x32_bf16 v[92:95], v[178:181], v[194:197], v[92:95]
	v_mfma_f32_16x16x32_bf16 v[88:91], v[186:189], v[194:197], v[88:91]
	v_mfma_f32_16x16x32_bf16 v[84:87], v[178:181], v[202:205], v[84:87]
	v_mfma_f32_16x16x32_bf16 v[80:83], v[186:189], v[202:205], v[80:83]
	v_mfma_f32_16x16x32_bf16 v[76:79], v[178:181], v[210:213], v[76:79]
	v_mfma_f32_16x16x32_bf16 v[72:75], v[186:189], v[210:213], v[72:75]
	v_mfma_f32_16x16x32_bf16 v[68:71], v[178:181], v[218:221], v[68:71]
	v_mfma_f32_16x16x32_bf16 v[64:67], v[186:189], v[218:221], v[64:67]
	s_setprio 0
	s_barrier
	s_add_i32 s89, s89, 2
	s_add_u32 s74, s74, 0x100
	s_addc_u32 s75, s75, 0
	s_add_u32 s84, s84, 0x100
	s_addc_u32 s88, s88, 0
	s_cmp_gt_u32 s89, 29
	s_cbranch_scc0 .LBB0_273
	s_and_b64 vcc, exec, s[28:29]
	s_cbranch_vccz .LBB0_276
	s_barrier

; #define PG8_STAGE(bufoff, gbase, voff) do { _Pragma("unroll") for (int _i = 0; _i < 2; ++_i) \
;         __builtin_amdgcn_global_load_lds((const unsigned*)((const char*)(gbase) + (voff)[_i]), (LAS unsigned*)(lds + (bufoff) + ldsw + _i * 8192), 16, 0, 0); } while (0)
; #define PG8_LDA(dst, b, h) do { _Pragma("unroll") for (int m = 0; m < 4; ++m) _Pragma("unroll") for (int k = 0; k < 2; ++k) dst[m][k] = *(const LAS bf16x8*)(lds + PG8_SA(b, h) + aoff + m * 2048 + k * 1024); } while (0)
; #define PG8_LDB(dst, b, h) do { _Pragma("unroll") for (int n = 0; n < 2; ++n) _Pragma("unroll") for (int k = 0; k < 2; ++k) dst[n][k] = *(const LAS bf16x8*)(lds + PG8_SB(b, h) + boff + n * 2048 + k * 1024); } while (0)
; #define PG8_MMA(ai, bj, At, Bt) do { __builtin_amdgcn_s_setprio(1); _Pragma("unroll") for (int m = 0; m < 4; ++m) _Pragma("unroll") for (int n = 0; n < 2; ++n) _Pragma("unroll") for (int k = 0; k < 2; ++k) \
;         acc[ai][bj][m][n] = __builtin_amdgcn_mfma_f32_16x16x32_bf16(Bt[n][k], At[m][k], acc[ai][bj][m][n], 0, 0, 0); __builtin_amdgcn_s_setprio(0); } while (0)
; #define PG8_WAIT_V(n) asm volatile("s_waitcnt vmcnt(" #n ")" ::: "memory")
; template <int K, int LDA, int LDB, class Epi, class Sched>
; __device__ __forceinline__ void gemm_phase(LAS unsigned char* lds, const Gemm g, const Sched& S, const Epi& E, int wv) {
;     ...
;             PG8_LDB(B0, 0, 0); PG8_LDB(B1, 0, 1); PG8_SCHED; PG8_LDA(At, 0, 0); PG8_STAGE(PG8_SA(1, 1), a1 + hstepA, voffA);
;             PG8_WAIT_V(8); PG8_WAIT_L(0); PG8_BAR; PG8_MMA(0, 0, At, B0); PG8_MMA(0, 1, At, B1); PG8_BAR; PG8_SCHED;
;             PG8_LDA(At, 0, 1); PG8_STAGE(PG8_SB(0, 0), b2, voffB); PG8_STAGE(PG8_SB(0, 1), b2 + hstepB, voffB); PG8_STAGE(PG8_SA(0, 0), a2, voffA);
;             PG8_WAIT_V(8); PG8_WAIT_L(0); PG8_BAR; PG8_MMA(1, 0, At, B0); PG8_MMA(1, 1, At, B1); PG8_BAR; PG8_SCHED;
;             PG8_LDB(B0, 1, 0); PG8_LDB(B1, 1, 1); PG8_SCHED; PG8_LDA(At, 1, 0); PG8_STAGE(PG8_SA(0, 1), a2 + hstepA, voffA);
;             PG8_WAIT_V(8); PG8_WAIT_L(0); PG8_BAR; PG8_MMA(0, 0, At, B0); PG8_MMA(0, 1, At, B1); PG8_BAR; PG8_SCHED;
;             PG8_LDA(At, 1, 1); PG8_STAGE(PG8_SB(1, 0), b3, voffB); PG8_STAGE(PG8_SB(1, 1), b3 + hstepB, voffB); PG8_STAGE(PG8_SA(1, 0), a3, voffA);
;             PG8_WAIT_V(8); PG8_WAIT_L(0); PG8_BAR; PG8_MMA(1, 0, At, B0); PG8_MMA(1, 1, At, B1); PG8_BAR; PG8_SCHED;
.LBB0_465:
	ds_read_b128 v[128:131], v201
	ds_read_b128 v[132:135], v201 offset:1024
	ds_read_b128 v[136:139], v201 offset:2048
	ds_read_b128 v[140:143], v201 offset:3072
	ds_read_b128 v[144:147], v205
	ds_read_b128 v[148:151], v205 offset:1024
	ds_read_b128 v[152:155], v205 offset:2048
	ds_read_b128 v[156:159], v205 offset:3072
	s_add_u32 s12, s66, 0x100
	s_addc_u32 s13, s67, 0
	s_cmp_eq_u32 s8, 4
	s_cselect_b32 s71, s61, s13
	s_cselect_b32 s70, s60, s12
	s_cselect_b32 s69, s59, s89
	s_cselect_b32 s68, s65, s84
	s_add_i32 m0, s72, 0xc000
	ds_read_b128 v[186:189], v209
	ds_read_b128 v[194:197], v209 offset:1024
	ds_read_b128 v[214:217], v209 offset:2048
	ds_read_b128 v[218:221], v209 offset:3072
	ds_read_b128 v[224:227], v209 offset:4096
	ds_read_b128 v[228:231], v209 offset:5120
	ds_read_b128 v[232:235], v209 offset:6144
	ds_read_b128 v[236:239], v209 offset:7168
	global_load_lds_dwordx4 v170, s[66:67]
	s_add_i32 m0, s72, 0xe000
	s_nop 0
	global_load_lds_dwordx4 v172, s[66:67]
	s_waitcnt vmcnt(8)
	s_waitcnt lgkmcnt(0)
	s_barrier
	s_setprio 1
	v_mfma_f32_16x16x32_bf16 v[124:127], v[128:131], v[186:189], v[124:127]
	v_mfma_f32_16x16x32_bf16 v[120:123], v[136:139], v[186:189], v[120:123]
	v_mfma_f32_16x16x32_bf16 v[108:111], v[128:131], v[214:217], v[108:111]
	v_mfma_f32_16x16x32_bf16 v[104:107], v[136:139], v[214:217], v[104:107]
	v_mfma_f32_16x16x32_bf16 v[92:95], v[128:131], v[224:227], v[92:95]
	v_mfma_f32_16x16x32_bf16 v[88:91], v[136:139], v[224:227], v[88:91]
	v_mfma_f32_16x16x32_bf16 v[76:79], v[128:131], v[232:235], v[76:79]
	v_mfma_f32_16x16x32_bf16 v[72:75], v[136:139], v[232:235], v[72:75]
	v_mfma_f32_16x16x32_bf16 v[124:127], v[132:135], v[194:197], v[124:127]
	v_mfma_f32_16x16x32_bf16 v[120:123], v[140:143], v[194:197], v[120:123]
	v_mfma_f32_16x16x32_bf16 v[108:111], v[132:135], v[218:221], v[108:111]
	v_mfma_f32_16x16x32_bf16 v[104:107], v[140:143], v[218:221], v[104:107]
	v_mfma_f32_16x16x32_bf16 v[92:95], v[132:135], v[228:231], v[92:95]
	v_mfma_f32_16x16x32_bf16 v[88:91], v[140:143], v[228:231], v[88:91]
	v_mfma_f32_16x16x32_bf16 v[76:79], v[132:135], v[236:239], v[76:79]
	v_mfma_f32_16x16x32_bf16 v[72:75], v[140:143], v[236:239], v[72:75]
	v_mfma_f32_16x16x32_bf16 v[116:119], v[144:147], v[186:189], v[116:119]
	v_mfma_f32_16x16x32_bf16 v[112:115], v[152:155], v[186:189], v[112:115]
	v_mfma_f32_16x16x32_bf16 v[100:103], v[144:147], v[214:217], v[100:103]
	v_mfma_f32_16x16x32_bf16 v[96:99], v[152:155], v[214:217], v[96:99]
	v_mfma_f32_16x16x32_bf16 v[84:87], v[144:147], v[224:227], v[84:87]
	v_mfma_f32_16x16x32_bf16 v[80:83], v[152:155], v[224:227], v[80:83]
	v_mfma_f32_16x16x32_bf16 v[68:71], v[144:147], v[232:235], v[68:71]
	v_mfma_f32_16x16x32_bf16 v[64:67], v[152:155], v[232:235], v[64:67]
	v_mfma_f32_16x16x32_bf16 v[116:119], v[148:151], v[194:197], v[116:119]
	v_mfma_f32_16x16x32_bf16 v[112:115], v[156:159], v[194:197], v[112:115]
	v_mfma_f32_16x16x32_bf16 v[100:103], v[148:151], v[218:221], v[100:103]
	v_mfma_f32_16x16x32_bf16 v[96:99], v[156:159], v[218:221], v[96:99]
	v_mfma_f32_16x16x32_bf16 v[84:87], v[148:151], v[228:231], v[84:87]
	v_mfma_f32_16x16x32_bf16 v[80:83], v[156:159], v[228:231], v[80:83]
	v_mfma_f32_16x16x32_bf16 v[68:71], v[148:151], v[236:239], v[68:71]
	v_mfma_f32_16x16x32_bf16 v[64:67], v[156:159], v[236:239], v[64:67]
	s_setprio 0
	s_barrier
	s_add_i32 s9, s81, s24
	s_mov_b32 m0, s9
	ds_read_b128 v[186:189], v209 offset:16384
	ds_read_b128 v[194:197], v209 offset:17408
	ds_read_b128 v[214:217], v209 offset:18432
	ds_read_b128 v[218:221], v209 offset:19456
	ds_read_b128 v[224:227], v209 offset:20480
	ds_read_b128 v[228:231], v209 offset:21504
	ds_read_b128 v[232:235], v209 offset:22528
	ds_read_b128 v[236:239], v209 offset:23552
	global_load_lds_dwordx4 v162, s[68:69]
	s_add_i32 m0, s9, 0x2000
	s_add_u32 s14, s68, 0x20000
	s_addc_u32 s15, s69, 0
	s_add_i32 s9, s82, s24
	global_load_lds_dwordx4 v166, s[68:69]
	s_mov_b32 m0, s9
	s_nop 0
	global_load_lds_dwordx4 v162, s[14:15]
	s_add_i32 m0, s9, 0x2000
	s_nop 0
	global_load_lds_dwordx4 v166, s[14:15]
	s_mov_b32 m0, s72
	s_nop 0
	global_load_lds_dwordx4 v160, s[70:71]
	s_mov_b32 m0, s73
	s_nop 0
	global_load_lds_dwordx4 v164, s[70:71]
	s_waitcnt vmcnt(8)
	s_waitcnt lgkmcnt(0)
	s_barrier
	s_setprio 1
	v_mfma_f32_16x16x32_bf16 v[60:63], v[128:131], v[186:189], v[60:63]
	v_mfma_f32_16x16x32_bf16 v[56:59], v[136:139], v[186:189], v[56:59]
	v_mfma_f32_16x16x32_bf16 v[44:47], v[128:131], v[214:217], v[44:47]
	v_mfma_f32_16x16x32_bf16 v[40:43], v[136:139], v[214:217], v[40:43]
	v_mfma_f32_16x16x32_bf16 v[28:31], v[128:131], v[224:227], v[28:31]
	v_mfma_f32_16x16x32_bf16 v[24:27], v[136:139], v[224:227], v[24:27]
	v_mfma_f32_16x16x32_bf16 v[12:15], v[128:131], v[232:235], v[12:15]
	v_mfma_f32_16x16x32_bf16 v[8:11], v[136:139], v[232:235], v[8:11]
	v_mfma_f32_16x16x32_bf16 v[60:63], v[132:135], v[194:197], v[60:63]
	v_mfma_f32_16x16x32_bf16 v[56:59], v[140:143], v[194:197], v[56:59]
	v_mfma_f32_16x16x32_bf16 v[44:47], v[132:135], v[218:221], v[44:47]
	v_mfma_f32_16x16x32_bf16 v[40:43], v[140:143], v[218:221], v[40:43]
	v_mfma_f32_16x16x32_bf16 v[28:31], v[132:135], v[228:231], v[28:31]
	v_mfma_f32_16x16x32_bf16 v[24:27], v[140:143], v[228:231], v[24:27]
	v_mfma_f32_16x16x32_bf16 v[12:15], v[132:135], v[236:239], v[12:15]
	v_mfma_f32_16x16x32_bf16 v[8:11], v[140:143], v[236:239], v[8:11]
	v_mfma_f32_16x16x32_bf16 v[52:55], v[144:147], v[186:189], v[52:55]
	v_mfma_f32_16x16x32_bf16 v[48:51], v[152:155], v[186:189], v[48:51]
	v_mfma_f32_16x16x32_bf16 v[36:39], v[144:147], v[214:217], v[36:39]
	v_mfma_f32_16x16x32_bf16 v[32:35], v[152:155], v[214:217], v[32:35]
	v_mfma_f32_16x16x32_bf16 v[20:23], v[144:147], v[224:227], v[20:23]
	v_mfma_f32_16x16x32_bf16 v[16:19], v[152:155], v[224:227], v[16:19]
	v_mfma_f32_16x16x32_bf16 v[4:7], v[144:147], v[232:235], v[4:7]
	v_mfma_f32_16x16x32_bf16 v[0:3], v[152:155], v[232:235], v[0:3]
	v_mfma_f32_16x16x32_bf16 v[52:55], v[148:151], v[194:197], v[52:55]
	v_mfma_f32_16x16x32_bf16 v[48:51], v[156:159], v[194:197], v[48:51]
	v_mfma_f32_16x16x32_bf16 v[36:39], v[148:151], v[218:221], v[36:39]
	v_mfma_f32_16x16x32_bf16 v[32:35], v[156:159], v[218:221], v[32:35]
	v_mfma_f32_16x16x32_bf16 v[20:23], v[148:151], v[228:231], v[20:23]
	v_mfma_f32_16x16x32_bf16 v[16:19], v[156:159], v[228:231], v[16:19]
	v_mfma_f32_16x16x32_bf16 v[4:7], v[148:151], v[236:239], v[4:7]
	v_mfma_f32_16x16x32_bf16 v[0:3], v[156:159], v[236:239], v[0:3]
	s_setprio 0
	s_barrier
; #define PG8_STAGE(bufoff, gbase, voff) do { _Pragma("unroll") for (int _i = 0; _i < 2; ++_i) \
;         __builtin_amdgcn_global_load_lds((const unsigned*)((const char*)(gbase) + (voff)[_i]), (LAS unsigned*)(lds + (bufoff) + ldsw + _i * 8192), 16, 0, 0); } while (0)
; #define PG8_LDA(dst, b, h) do { _Pragma("unroll") for (int m = 0; m < 4; ++m) _Pragma("unroll") for (int k = 0; k < 2; ++k) dst[m][k] = *(const LAS bf16x8*)(lds + PG8_SA(b, h) + aoff + m * 2048 + k * 1024); } while (0)
; #define PG8_LDB(dst, b, h) do { _Pragma("unroll") for (int n = 0; n < 2; ++n) _Pragma("unroll") for (int k = 0; k < 2; ++k) dst[n][k] = *(const LAS bf16x8*)(lds + PG8_SB(b, h) + boff + n * 2048 + k * 1024); } while (0)
; #define PG8_MMA(ai, bj, At, Bt) do { __builtin_amdgcn_s_setprio(1); _Pragma("unroll") for (int m = 0; m < 4; ++m) _Pragma("unroll") for (int n = 0; n < 2; ++n) _Pragma("unroll") for (int k = 0; k < 2; ++k) \
;         acc[ai][bj][m][n] = __builtin_amdgcn_mfma_f32_16x16x32_bf16(Bt[n][k], At[m][k], acc[ai][bj][m][n], 0, 0, 0); __builtin_amdgcn_s_setprio(0); } while (0)
; #define PG8_WAIT_V(n) asm volatile("s_waitcnt vmcnt(" #n ")" ::: "memory")
; #define PG8_WAIT_L(n) asm volatile("s_waitcnt lgkmcnt(" #n ")" ::: "memory")
; #define PG8_BAR __builtin_amdgcn_s_barrier()
; #define PG8_SCHED __builtin_amdgcn_sched_barrier(0)
; template <int K, int LDA, int LDB, class Epi, class Sched>
; __device__ __forceinline__ void gemm_phase(LAS unsigned char* lds, const Gemm g, const Sched& S, const Epi& E, int wv) {
;     ...
;             PG8_LDB(B0, 1, 0); PG8_LDB(B1, 1, 1); PG8_SCHED; PG8_LDA(At, 1, 0); PG8_STAGE(PG8_SA(0, 1), a2 + hstepA, voffA);
;             PG8_WAIT_V(8); PG8_WAIT_L(0); PG8_BAR; PG8_MMA(0, 0, At, B0); PG8_MMA(0, 1, At, B1); PG8_BAR; PG8_SCHED;
;             PG8_LDA(At, 1, 1); PG8_STAGE(PG8_SB(1, 0), b3, voffB); PG8_STAGE(PG8_SB(1, 1), b3 + hstepB, voffB); PG8_STAGE(PG8_SA(1, 0), a3, voffA);
;             PG8_WAIT_V(8); PG8_WAIT_L(0); PG8_BAR; PG8_MMA(1, 0, At, B0); PG8_MMA(1, 1, At, B1); PG8_BAR; PG8_SCHED;
;         }
;         if (wr == 0) PG8_BAR;
	s_add_i32 s9, 0, 0x18000
	s_add_i32 s34, 0, 0x1c000
	v_add_u32_e32 v140, s9, v185
	v_add_u32_e32 v156, s34, v185
	ds_read_b128 v[128:131], v140
	ds_read_b128 v[132:135], v140 offset:1024
	ds_read_b128 v[136:139], v140 offset:2048
	ds_read_b128 v[140:143], v140 offset:3072
	ds_read_b128 v[144:147], v156
	ds_read_b128 v[148:151], v156 offset:1024
	ds_read_b128 v[152:155], v156 offset:2048
	ds_read_b128 v[156:159], v156 offset:3072
	s_add_u32 s14, s70, 0x120000
	s_addc_u32 s15, s71, 0
	s_mov_b32 m0, s74
	ds_read_b128 v[186:189], v209 offset:32768
	ds_read_b128 v[194:197], v209 offset:33792
	ds_read_b128 v[214:217], v209 offset:34816
	ds_read_b128 v[218:221], v209 offset:35840
	ds_read_b128 v[224:227], v209 offset:36864
	ds_read_b128 v[228:231], v209 offset:37888
	ds_read_b128 v[232:235], v209 offset:38912
	ds_read_b128 v[236:239], v209 offset:39936
	global_load_lds_dwordx4 v160, s[14:15]
	s_mov_b32 m0, s75
	s_nop 0
	global_load_lds_dwordx4 v164, s[14:15]
	s_waitcnt vmcnt(8)
	s_waitcnt lgkmcnt(0)
	s_barrier
	s_setprio 1
	v_mfma_f32_16x16x32_bf16 v[124:127], v[128:131], v[186:189], v[124:127]
	v_mfma_f32_16x16x32_bf16 v[120:123], v[136:139], v[186:189], v[120:123]
	v_mfma_f32_16x16x32_bf16 v[108:111], v[128:131], v[214:217], v[108:111]
	v_mfma_f32_16x16x32_bf16 v[104:107], v[136:139], v[214:217], v[104:107]
	v_mfma_f32_16x16x32_bf16 v[92:95], v[128:131], v[224:227], v[92:95]
	v_mfma_f32_16x16x32_bf16 v[88:91], v[136:139], v[224:227], v[88:91]
	v_mfma_f32_16x16x32_bf16 v[76:79], v[128:131], v[232:235], v[76:79]
	v_mfma_f32_16x16x32_bf16 v[72:75], v[136:139], v[232:235], v[72:75]
	v_mfma_f32_16x16x32_bf16 v[124:127], v[132:135], v[194:197], v[124:127]
	v_mfma_f32_16x16x32_bf16 v[120:123], v[140:143], v[194:197], v[120:123]
	v_mfma_f32_16x16x32_bf16 v[108:111], v[132:135], v[218:221], v[108:111]
	v_mfma_f32_16x16x32_bf16 v[104:107], v[140:143], v[218:221], v[104:107]
	v_mfma_f32_16x16x32_bf16 v[92:95], v[132:135], v[228:231], v[92:95]
	v_mfma_f32_16x16x32_bf16 v[88:91], v[140:143], v[228:231], v[88:91]
	v_mfma_f32_16x16x32_bf16 v[76:79], v[132:135], v[236:239], v[76:79]
	v_mfma_f32_16x16x32_bf16 v[72:75], v[140:143], v[236:239], v[72:75]
	v_mfma_f32_16x16x32_bf16 v[116:119], v[144:147], v[186:189], v[116:119]
	v_mfma_f32_16x16x32_bf16 v[112:115], v[152:155], v[186:189], v[112:115]
	v_mfma_f32_16x16x32_bf16 v[100:103], v[144:147], v[214:217], v[100:103]
	v_mfma_f32_16x16x32_bf16 v[96:99], v[152:155], v[214:217], v[96:99]
	v_mfma_f32_16x16x32_bf16 v[84:87], v[144:147], v[224:227], v[84:87]
	v_mfma_f32_16x16x32_bf16 v[80:83], v[152:155], v[224:227], v[80:83]
	v_mfma_f32_16x16x32_bf16 v[68:71], v[144:147], v[232:235], v[68:71]
	v_mfma_f32_16x16x32_bf16 v[64:67], v[152:155], v[232:235], v[64:67]
	v_mfma_f32_16x16x32_bf16 v[116:119], v[148:151], v[194:197], v[116:119]
	v_mfma_f32_16x16x32_bf16 v[112:115], v[156:159], v[194:197], v[112:115]
	v_mfma_f32_16x16x32_bf16 v[100:103], v[148:151], v[218:221], v[100:103]
	v_mfma_f32_16x16x32_bf16 v[96:99], v[156:159], v[218:221], v[96:99]
	v_mfma_f32_16x16x32_bf16 v[84:87], v[148:151], v[228:231], v[84:87]
	v_mfma_f32_16x16x32_bf16 v[80:83], v[156:159], v[228:231], v[80:83]
	v_mfma_f32_16x16x32_bf16 v[68:71], v[148:151], v[236:239], v[68:71]
	v_mfma_f32_16x16x32_bf16 v[64:67], v[156:159], v[236:239], v[64:67]
	s_setprio 0
	s_barrier
	s_add_i32 s9, s9, s24
	s_mov_b32 m0, s9
	ds_read_b128 v[186:189], v209 offset:49152
	ds_read_b128 v[194:197], v209 offset:50176
	ds_read_b128 v[214:217], v209 offset:51200
	ds_read_b128 v[218:221], v209 offset:52224
	ds_read_b128 v[224:227], v209 offset:53248
	ds_read_b128 v[228:231], v209 offset:54272
	ds_read_b128 v[232:235], v209 offset:55296
	ds_read_b128 v[236:239], v209 offset:56320
	s_add_u32 s98, s68, s56
	s_addc_u32 s99, s69, s57
	global_load_lds_dwordx4 v162, s[98:99]
	s_add_i32 m0, s9, 0x2000
	s_add_u32 s14, s68, 0x20080
	s_addc_u32 s15, s69, 0
	s_add_i32 s9, s34, s24
	global_load_lds_dwordx4 v166, s[98:99]
	s_mov_b32 m0, s9
	s_nop 0
	global_load_lds_dwordx4 v162, s[14:15]
	s_add_i32 m0, s9, 0x2000
	s_nop 0
	global_load_lds_dwordx4 v166, s[14:15]
	s_mov_b32 m0, s78
	s_nop 0
	s_add_u32 s100, s70, s56
	s_addc_u32 s101, s71, s57
	global_load_lds_dwordx4 v160, s[100:101]
	s_mov_b32 m0, s79
	s_nop 0
	global_load_lds_dwordx4 v164, s[100:101]
	s_waitcnt vmcnt(8)
	s_waitcnt lgkmcnt(0)
	s_barrier
	s_setprio 1
	v_mfma_f32_16x16x32_bf16 v[60:63], v[128:131], v[186:189], v[60:63]
	v_mfma_f32_16x16x32_bf16 v[56:59], v[136:139], v[186:189], v[56:59]
	v_mfma_f32_16x16x32_bf16 v[44:47], v[128:131], v[214:217], v[44:47]
	v_mfma_f32_16x16x32_bf16 v[40:43], v[136:139], v[214:217], v[40:43]
	v_mfma_f32_16x16x32_bf16 v[28:31], v[128:131], v[224:227], v[28:31]
	v_mfma_f32_16x16x32_bf16 v[24:27], v[136:139], v[224:227], v[24:27]
	v_mfma_f32_16x16x32_bf16 v[12:15], v[128:131], v[232:235], v[12:15]
	v_mfma_f32_16x16x32_bf16 v[8:11], v[136:139], v[232:235], v[8:11]
	v_mfma_f32_16x16x32_bf16 v[60:63], v[132:135], v[194:197], v[60:63]
	v_mfma_f32_16x16x32_bf16 v[56:59], v[140:143], v[194:197], v[56:59]
	v_mfma_f32_16x16x32_bf16 v[44:47], v[132:135], v[218:221], v[44:47]
	v_mfma_f32_16x16x32_bf16 v[40:43], v[140:143], v[218:221], v[40:43]
	v_mfma_f32_16x16x32_bf16 v[28:31], v[132:135], v[228:231], v[28:31]
	v_mfma_f32_16x16x32_bf16 v[24:27], v[140:143], v[228:231], v[24:27]
	v_mfma_f32_16x16x32_bf16 v[12:15], v[132:135], v[236:239], v[12:15]
	v_mfma_f32_16x16x32_bf16 v[8:11], v[140:143], v[236:239], v[8:11]
	v_mfma_f32_16x16x32_bf16 v[52:55], v[144:147], v[186:189], v[52:55]
	v_mfma_f32_16x16x32_bf16 v[48:51], v[152:155], v[186:189], v[48:51]
	v_mfma_f32_16x16x32_bf16 v[36:39], v[144:147], v[214:217], v[36:39]
	v_mfma_f32_16x16x32_bf16 v[32:35], v[152:155], v[214:217], v[32:35]
	v_mfma_f32_16x16x32_bf16 v[20:23], v[144:147], v[224:227], v[20:23]
	v_mfma_f32_16x16x32_bf16 v[16:19], v[152:155], v[224:227], v[16:19]
	v_mfma_f32_16x16x32_bf16 v[4:7], v[144:147], v[232:235], v[4:7]
	v_mfma_f32_16x16x32_bf16 v[0:3], v[152:155], v[232:235], v[0:3]
	v_mfma_f32_16x16x32_bf16 v[52:55], v[148:151], v[194:197], v[52:55]
	v_mfma_f32_16x16x32_bf16 v[48:51], v[156:159], v[194:197], v[48:51]
	v_mfma_f32_16x16x32_bf16 v[36:39], v[148:151], v[218:221], v[36:39]
	v_mfma_f32_16x16x32_bf16 v[32:35], v[156:159], v[218:221], v[32:35]
	v_mfma_f32_16x16x32_bf16 v[20:23], v[148:151], v[228:231], v[20:23]
	v_mfma_f32_16x16x32_bf16 v[16:19], v[156:159], v[228:231], v[16:19]
	v_mfma_f32_16x16x32_bf16 v[4:7], v[148:151], v[236:239], v[4:7]
	v_mfma_f32_16x16x32_bf16 v[0:3], v[156:159], v[236:239], v[0:3]
	s_setprio 0
	s_barrier
	s_add_i32 s8, s8, 2
	s_add_u32 s84, s84, 0x100
	s_addc_u32 s89, s89, 0
	s_cmp_gt_u32 s8, 5
	s_mov_b64 s[66:67], s[12:13]
	s_cbranch_scc0 .LBB0_465
	s_and_b64 vcc, exec, s[28:29]
	s_cbranch_vccz .LBB0_468
	s_barrier

; #define PG8_STAGE(bufoff, gbase, voff) do { _Pragma("unroll") for (int _i = 0; _i < 2; ++_i) \
;         __builtin_amdgcn_global_load_lds((const unsigned*)((const char*)(gbase) + (voff)[_i]), (LAS unsigned*)(lds + (bufoff) + ldsw + _i * 8192), 16, 0, 0); } while (0)
; #define PG8_LDA(dst, b, h) do { _Pragma("unroll") for (int m = 0; m < 4; ++m) _Pragma("unroll") for (int k = 0; k < 2; ++k) dst[m][k] = *(const LAS bf16x8*)(lds + PG8_SA(b, h) + aoff + m * 2048 + k * 1024); } while (0)
; #define PG8_LDB(dst, b, h) do { _Pragma("unroll") for (int n = 0; n < 2; ++n) _Pragma("unroll") for (int k = 0; k < 2; ++k) dst[n][k] = *(const LAS bf16x8*)(lds + PG8_SB(b, h) + boff + n * 2048 + k * 1024); } while (0)
; #define PG8_MMA(ai, bj, At, Bt) do { __builtin_amdgcn_s_setprio(1); _Pragma("unroll") for (int m = 0; m < 4; ++m) _Pragma("unroll") for (int n = 0; n < 2; ++n) _Pragma("unroll") for (int k = 0; k < 2; ++k) \
;         acc[ai][bj][m][n] = __builtin_amdgcn_mfma_f32_16x16x32_bf16(Bt[n][k], At[m][k], acc[ai][bj][m][n], 0, 0, 0); __builtin_amdgcn_s_setprio(0); } while (0)
; #define PG8_WAIT_V(n) asm volatile("s_waitcnt vmcnt(" #n ")" ::: "memory")
; #define PG8_BAR __builtin_amdgcn_s_barrier()
; template <int K, int LDA, int LDB, class Epi, class Sched>
; __device__ __forceinline__ void gemm_phase(LAS unsigned char* lds, const Gemm g, const Sched& S, const Epi& E, int wv) {
;     ...
;         for (int t = 0; t < nt; t += 2) {
;             const bool last = (t == nt - 2);
;             const char* a1 = cA + (size_t)(t + 1) * kstep;
;             const char* a2 = last ? nA : cA + (size_t)(t + 2) * kstep; const char* b2 = last ? nB : cB + (size_t)(t + 2) * kstep;
;             const char* a3 = a2 + kstep; const char* b3 = b2 + kstep;
;             PG8_LDB(B0, 0, 0); PG8_LDB(B1, 0, 1); PG8_SCHED; PG8_LDA(At, 0, 0); PG8_STAGE(PG8_SA(1, 1), a1 + hstepA, voffA);
;             PG8_WAIT_V(8); PG8_WAIT_L(0); PG8_BAR; PG8_MMA(0, 0, At, B0); PG8_MMA(0, 1, At, B1); PG8_BAR; PG8_SCHED;
;             PG8_LDA(At, 0, 1); PG8_STAGE(PG8_SB(0, 0), b2, voffB); PG8_STAGE(PG8_SB(0, 1), b2 + hstepB, voffB); PG8_STAGE(PG8_SA(0, 0), a2, voffA);
;             PG8_WAIT_V(8); PG8_WAIT_L(0); PG8_BAR; PG8_MMA(1, 0, At, B0); PG8_MMA(1, 1, At, B1); PG8_BAR; PG8_SCHED;
;             PG8_LDB(B0, 1, 0); PG8_LDB(B1, 1, 1); PG8_SCHED; PG8_LDA(At, 1, 0); PG8_STAGE(PG8_SA(0, 1), a2 + hstepA, voffA);
.LBB0_519:
	s_add_u32 s14, s68, s72
	s_addc_u32 s15, s69, s73
	s_add_u32 s34, s14, 0x100
	s_addc_u32 s35, s15, 0
	s_and_b64 s[8:9], s[70:71], exec
	s_cselect_b32 s75, s63, s35
	s_cselect_b32 s74, s62, s34
	s_add_u32 s8, s66, s72
	s_addc_u32 s9, s67, s73
	s_add_u32 s34, s8, 0x100
	s_addc_u32 s35, s9, 0
	s_and_b64 s[8:9], s[70:71], exec
	s_cselect_b32 s77, s61, s35
	s_cselect_b32 s76, s84, s34
	s_add_u32 s80, s14, 0x120080
	ds_read_b128 v[144:147], v157
	ds_read_b128 v[164:167], v157 offset:1024
	ds_read_b128 v[168:171], v157 offset:2048
	ds_read_b128 v[172:175], v157 offset:3072
	ds_read_b128 v[176:179], v160
	ds_read_b128 v[180:183], v160 offset:1024
	ds_read_b128 v[184:187], v160 offset:2048
	ds_read_b128 v[188:191], v160 offset:3072
	s_addc_u32 s81, s15, 0
	s_add_i32 s15, s93, s24
	s_add_i32 m0, s86, 0xc000
	s_add_i32 s35, s86, 0xe000
	s_add_i32 s34, s15, 0x2000
	s_add_u32 s78, s76, 0x10000
	s_addc_u32 s79, s77, 0
	s_add_i32 s51, s94, s24
	s_add_i32 s50, s51, 0x2000
	s_add_i32 vcc_hi, 0, 0x18000
	s_add_i32 vcc_lo, 0, 0x1c000
	s_add_u32 s72, s74, 0x120000
	s_addc_u32 s73, s75, 0
	s_add_i32 s9, vcc_hi, s24
	s_add_i32 s14, s9, 0x2000
	s_add_u32 s70, s76, 0x10080
	s_addc_u32 s71, s77, 0
	s_add_i32 s8, vcc_lo, s24
	s_add_i32 s85, s8, 0x2000
	ds_read_b128 v[192:195], v161
	ds_read_b128 v[196:199], v161 offset:1024
	ds_read_b128 v[200:203], v161 offset:2048
	ds_read_b128 v[204:207], v161 offset:3072
	ds_read_b128 v[208:211], v161 offset:4096
	ds_read_b128 v[212:215], v161 offset:5120
	ds_read_b128 v[216:219], v161 offset:6144
	ds_read_b128 v[224:227], v161 offset:7168
	global_load_lds_dwordx4 v134, s[80:81]
	s_mov_b32 m0, s35
	s_nop 0
	global_load_lds_dwordx4 v130, s[80:81]
	s_waitcnt vmcnt(8)
	s_waitcnt lgkmcnt(0)
	s_barrier
	s_setprio 1
	v_mfma_f32_16x16x32_bf16 v[124:127], v[144:147], v[192:195], v[124:127]
	v_mfma_f32_16x16x32_bf16 v[120:123], v[168:171], v[192:195], v[120:123]
	v_mfma_f32_16x16x32_bf16 v[112:115], v[144:147], v[200:203], v[112:115]
	v_mfma_f32_16x16x32_bf16 v[104:107], v[168:171], v[200:203], v[104:107]
	v_mfma_f32_16x16x32_bf16 v[96:99], v[144:147], v[208:211], v[96:99]
	v_mfma_f32_16x16x32_bf16 v[88:91], v[168:171], v[208:211], v[88:91]
	v_mfma_f32_16x16x32_bf16 v[80:83], v[144:147], v[216:219], v[80:83]
	v_mfma_f32_16x16x32_bf16 v[72:75], v[168:171], v[216:219], v[72:75]
	v_mfma_f32_16x16x32_bf16 v[124:127], v[164:167], v[196:199], v[124:127]
	v_mfma_f32_16x16x32_bf16 v[120:123], v[172:175], v[196:199], v[120:123]
	v_mfma_f32_16x16x32_bf16 v[112:115], v[164:167], v[204:207], v[112:115]
	v_mfma_f32_16x16x32_bf16 v[104:107], v[172:175], v[204:207], v[104:107]
	v_mfma_f32_16x16x32_bf16 v[96:99], v[164:167], v[212:215], v[96:99]
	v_mfma_f32_16x16x32_bf16 v[88:91], v[172:175], v[212:215], v[88:91]
	v_mfma_f32_16x16x32_bf16 v[80:83], v[164:167], v[224:227], v[80:83]
	v_mfma_f32_16x16x32_bf16 v[72:75], v[172:175], v[224:227], v[72:75]
	v_mfma_f32_16x16x32_bf16 v[116:119], v[176:179], v[192:195], v[116:119]
	v_mfma_f32_16x16x32_bf16 v[108:111], v[184:187], v[192:195], v[108:111]
	v_mfma_f32_16x16x32_bf16 v[100:103], v[176:179], v[200:203], v[100:103]
	v_mfma_f32_16x16x32_bf16 v[92:95], v[184:187], v[200:203], v[92:95]
	v_mfma_f32_16x16x32_bf16 v[84:87], v[176:179], v[208:211], v[84:87]
	v_mfma_f32_16x16x32_bf16 v[76:79], v[184:187], v[208:211], v[76:79]
	v_mfma_f32_16x16x32_bf16 v[68:71], v[176:179], v[216:219], v[68:71]
	v_mfma_f32_16x16x32_bf16 v[64:67], v[184:187], v[216:219], v[64:67]
	v_mfma_f32_16x16x32_bf16 v[116:119], v[180:183], v[196:199], v[116:119]
	v_mfma_f32_16x16x32_bf16 v[108:111], v[188:191], v[196:199], v[108:111]
	v_mfma_f32_16x16x32_bf16 v[100:103], v[180:183], v[204:207], v[100:103]
	v_mfma_f32_16x16x32_bf16 v[92:95], v[188:191], v[204:207], v[92:95]
	v_mfma_f32_16x16x32_bf16 v[84:87], v[180:183], v[212:215], v[84:87]
	v_mfma_f32_16x16x32_bf16 v[76:79], v[188:191], v[212:215], v[76:79]
	v_mfma_f32_16x16x32_bf16 v[68:71], v[180:183], v[224:227], v[68:71]
	v_mfma_f32_16x16x32_bf16 v[64:67], v[188:191], v[224:227], v[64:67]
	s_setprio 0
	s_barrier
	s_mov_b32 m0, s15
	ds_read_b128 v[192:195], v161 offset:16384
	ds_read_b128 v[196:199], v161 offset:17408
	ds_read_b128 v[200:203], v161 offset:18432
	ds_read_b128 v[204:207], v161 offset:19456
	ds_read_b128 v[208:211], v161 offset:20480
	ds_read_b128 v[212:215], v161 offset:21504
	ds_read_b128 v[216:219], v161 offset:22528
	ds_read_b128 v[224:227], v161 offset:23552
	global_load_lds_dwordx4 v132, s[76:77]
	s_mov_b32 m0, s34
	s_nop 0
	global_load_lds_dwordx4 v128, s[76:77]
	s_mov_b32 m0, s51
	s_nop 0
	global_load_lds_dwordx4 v132, s[78:79]
	s_mov_b32 m0, s50
	s_nop 0
	global_load_lds_dwordx4 v128, s[78:79]
	s_mov_b32 m0, s86
	s_nop 0
	global_load_lds_dwordx4 v134, s[74:75]
	s_mov_b32 m0, s87
	s_nop 0
	global_load_lds_dwordx4 v130, s[74:75]
	s_waitcnt vmcnt(8)
	s_waitcnt lgkmcnt(0)
	s_barrier
; #define PG8_STAGE(bufoff, gbase, voff) do { _Pragma("unroll") for (int _i = 0; _i < 2; ++_i) \
;         __builtin_amdgcn_global_load_lds((const unsigned*)((const char*)(gbase) + (voff)[_i]), (LAS unsigned*)(lds + (bufoff) + ldsw + _i * 8192), 16, 0, 0); } while (0)
; #define PG8_LDA(dst, b, h) do { _Pragma("unroll") for (int m = 0; m < 4; ++m) _Pragma("unroll") for (int k = 0; k < 2; ++k) dst[m][k] = *(const LAS bf16x8*)(lds + PG8_SA(b, h) + aoff + m * 2048 + k * 1024); } while (0)
; #define PG8_LDB(dst, b, h) do { _Pragma("unroll") for (int n = 0; n < 2; ++n) _Pragma("unroll") for (int k = 0; k < 2; ++k) dst[n][k] = *(const LAS bf16x8*)(lds + PG8_SB(b, h) + boff + n * 2048 + k * 1024); } while (0)
; #define PG8_MMA(ai, bj, At, Bt) do { __builtin_amdgcn_s_setprio(1); _Pragma("unroll") for (int m = 0; m < 4; ++m) _Pragma("unroll") for (int n = 0; n < 2; ++n) _Pragma("unroll") for (int k = 0; k < 2; ++k) \
;         acc[ai][bj][m][n] = __builtin_amdgcn_mfma_f32_16x16x32_bf16(Bt[n][k], At[m][k], acc[ai][bj][m][n], 0, 0, 0); __builtin_amdgcn_s_setprio(0); } while (0)
; #define PG8_WAIT_V(n) asm volatile("s_waitcnt vmcnt(" #n ")" ::: "memory")
; #define PG8_WAIT_L(n) asm volatile("s_waitcnt lgkmcnt(" #n ")" ::: "memory")
; #define PG8_BAR __builtin_amdgcn_s_barrier()
; #define PG8_SCHED __builtin_amdgcn_sched_barrier(0)
; template <int K, int LDA, int LDB, class Epi, class Sched>
; __device__ __forceinline__ void gemm_phase(LAS unsigned char* lds, const Gemm g, const Sched& S, const Epi& E, int wv) {
;     ...
;             PG8_WAIT_V(8); PG8_WAIT_L(0); PG8_BAR; PG8_MMA(1, 0, At, B0); PG8_MMA(1, 1, At, B1); PG8_BAR; PG8_SCHED;
;             PG8_LDB(B0, 1, 0); PG8_LDB(B1, 1, 1); PG8_SCHED; PG8_LDA(At, 1, 0); PG8_STAGE(PG8_SA(0, 1), a2 + hstepA, voffA);
;             PG8_WAIT_V(8); PG8_WAIT_L(0); PG8_BAR; PG8_MMA(0, 0, At, B0); PG8_MMA(0, 1, At, B1); PG8_BAR; PG8_SCHED;
;             PG8_LDA(At, 1, 1); PG8_STAGE(PG8_SB(1, 0), b3, voffB); PG8_STAGE(PG8_SB(1, 1), b3 + hstepB, voffB); PG8_STAGE(PG8_SA(1, 0), a3, voffA);
	s_setprio 1
	v_mfma_f32_16x16x32_bf16 v[60:63], v[144:147], v[192:195], v[60:63]
	v_mfma_f32_16x16x32_bf16 v[56:59], v[168:171], v[192:195], v[56:59]
	v_mfma_f32_16x16x32_bf16 v[48:51], v[144:147], v[200:203], v[48:51]
	v_mfma_f32_16x16x32_bf16 v[40:43], v[168:171], v[200:203], v[40:43]
	v_mfma_f32_16x16x32_bf16 v[32:35], v[144:147], v[208:211], v[32:35]
	v_mfma_f32_16x16x32_bf16 v[24:27], v[168:171], v[208:211], v[24:27]
	v_mfma_f32_16x16x32_bf16 v[16:19], v[144:147], v[216:219], v[16:19]
	v_mfma_f32_16x16x32_bf16 v[8:11], v[168:171], v[216:219], v[8:11]
	v_mfma_f32_16x16x32_bf16 v[60:63], v[164:167], v[196:199], v[60:63]
	v_mfma_f32_16x16x32_bf16 v[56:59], v[172:175], v[196:199], v[56:59]
	v_mfma_f32_16x16x32_bf16 v[48:51], v[164:167], v[204:207], v[48:51]
	v_mfma_f32_16x16x32_bf16 v[40:43], v[172:175], v[204:207], v[40:43]
	v_mfma_f32_16x16x32_bf16 v[32:35], v[164:167], v[212:215], v[32:35]
	v_mfma_f32_16x16x32_bf16 v[24:27], v[172:175], v[212:215], v[24:27]
	v_mfma_f32_16x16x32_bf16 v[16:19], v[164:167], v[224:227], v[16:19]
	v_mfma_f32_16x16x32_bf16 v[8:11], v[172:175], v[224:227], v[8:11]
	v_mfma_f32_16x16x32_bf16 v[52:55], v[176:179], v[192:195], v[52:55]
	v_mfma_f32_16x16x32_bf16 v[44:47], v[184:187], v[192:195], v[44:47]
	v_mfma_f32_16x16x32_bf16 v[36:39], v[176:179], v[200:203], v[36:39]
	v_mfma_f32_16x16x32_bf16 v[28:31], v[184:187], v[200:203], v[28:31]
	v_mfma_f32_16x16x32_bf16 v[20:23], v[176:179], v[208:211], v[20:23]
	v_mfma_f32_16x16x32_bf16 v[12:15], v[184:187], v[208:211], v[12:15]
	v_mfma_f32_16x16x32_bf16 v[4:7], v[176:179], v[216:219], v[4:7]
	v_mfma_f32_16x16x32_bf16 v[0:3], v[184:187], v[216:219], v[0:3]
	v_mfma_f32_16x16x32_bf16 v[52:55], v[180:183], v[196:199], v[52:55]
	v_mfma_f32_16x16x32_bf16 v[44:47], v[188:191], v[196:199], v[44:47]
	v_mfma_f32_16x16x32_bf16 v[36:39], v[180:183], v[204:207], v[36:39]
	v_mfma_f32_16x16x32_bf16 v[28:31], v[188:191], v[204:207], v[28:31]
	v_mfma_f32_16x16x32_bf16 v[20:23], v[180:183], v[212:215], v[20:23]
	v_mfma_f32_16x16x32_bf16 v[12:15], v[188:191], v[212:215], v[12:15]
	v_mfma_f32_16x16x32_bf16 v[4:7], v[180:183], v[224:227], v[4:7]
	v_mfma_f32_16x16x32_bf16 v[0:3], v[188:191], v[224:227], v[0:3]
	s_setprio 0
	s_barrier
	v_add_u32_e32 v142, vcc_hi, v149
	ds_read_b128 v[144:147], v142
	ds_read_b128 v[164:167], v142 offset:1024
	ds_read_b128 v[168:171], v142 offset:2048
	ds_read_b128 v[172:175], v142 offset:3072
	v_add_u32_e32 v142, vcc_lo, v149
	ds_read_b128 v[176:179], v142
	ds_read_b128 v[180:183], v142 offset:1024
	ds_read_b128 v[184:187], v142 offset:2048
	ds_read_b128 v[188:191], v142 offset:3072
	s_mov_b32 m0, s88
	ds_read_b128 v[192:195], v161 offset:32768
	ds_read_b128 v[196:199], v161 offset:33792
	ds_read_b128 v[200:203], v161 offset:34816
	ds_read_b128 v[204:207], v161 offset:35840
	ds_read_b128 v[208:211], v161 offset:36864
	ds_read_b128 v[212:215], v161 offset:37888
	ds_read_b128 v[216:219], v161 offset:38912
	ds_read_b128 v[224:227], v161 offset:39936
	global_load_lds_dwordx4 v134, s[72:73]
	s_mov_b32 m0, s89
	s_nop 0
	global_load_lds_dwordx4 v130, s[72:73]
	s_waitcnt vmcnt(8)
	s_waitcnt lgkmcnt(0)
	s_barrier
	s_setprio 1
	v_mfma_f32_16x16x32_bf16 v[124:127], v[144:147], v[192:195], v[124:127]
	v_mfma_f32_16x16x32_bf16 v[120:123], v[168:171], v[192:195], v[120:123]
	v_mfma_f32_16x16x32_bf16 v[112:115], v[144:147], v[200:203], v[112:115]
	v_mfma_f32_16x16x32_bf16 v[104:107], v[168:171], v[200:203], v[104:107]
	v_mfma_f32_16x16x32_bf16 v[96:99], v[144:147], v[208:211], v[96:99]
	v_mfma_f32_16x16x32_bf16 v[88:91], v[168:171], v[208:211], v[88:91]
	v_mfma_f32_16x16x32_bf16 v[80:83], v[144:147], v[216:219], v[80:83]
	v_mfma_f32_16x16x32_bf16 v[72:75], v[168:171], v[216:219], v[72:75]
	v_mfma_f32_16x16x32_bf16 v[124:127], v[164:167], v[196:199], v[124:127]
	v_mfma_f32_16x16x32_bf16 v[120:123], v[172:175], v[196:199], v[120:123]
	v_mfma_f32_16x16x32_bf16 v[112:115], v[164:167], v[204:207], v[112:115]
	v_mfma_f32_16x16x32_bf16 v[104:107], v[172:175], v[204:207], v[104:107]
	v_mfma_f32_16x16x32_bf16 v[96:99], v[164:167], v[212:215], v[96:99]
	v_mfma_f32_16x16x32_bf16 v[88:91], v[172:175], v[212:215], v[88:91]
	v_mfma_f32_16x16x32_bf16 v[80:83], v[164:167], v[224:227], v[80:83]
	v_mfma_f32_16x16x32_bf16 v[72:75], v[172:175], v[224:227], v[72:75]
	v_mfma_f32_16x16x32_bf16 v[116:119], v[176:179], v[192:195], v[116:119]
	v_mfma_f32_16x16x32_bf16 v[108:111], v[184:187], v[192:195], v[108:111]
	v_mfma_f32_16x16x32_bf16 v[100:103], v[176:179], v[200:203], v[100:103]
	v_mfma_f32_16x16x32_bf16 v[92:95], v[184:187], v[200:203], v[92:95]
	v_mfma_f32_16x16x32_bf16 v[84:87], v[176:179], v[208:211], v[84:87]
	v_mfma_f32_16x16x32_bf16 v[76:79], v[184:187], v[208:211], v[76:79]
	v_mfma_f32_16x16x32_bf16 v[68:71], v[176:179], v[216:219], v[68:71]
	v_mfma_f32_16x16x32_bf16 v[64:67], v[184:187], v[216:219], v[64:67]
	v_mfma_f32_16x16x32_bf16 v[116:119], v[180:183], v[196:199], v[116:119]
	v_mfma_f32_16x16x32_bf16 v[108:111], v[188:191], v[196:199], v[108:111]
	v_mfma_f32_16x16x32_bf16 v[100:103], v[180:183], v[204:207], v[100:103]
	v_mfma_f32_16x16x32_bf16 v[92:95], v[188:191], v[204:207], v[92:95]
	v_mfma_f32_16x16x32_bf16 v[84:87], v[180:183], v[212:215], v[84:87]
	v_mfma_f32_16x16x32_bf16 v[76:79], v[188:191], v[212:215], v[76:79]
	v_mfma_f32_16x16x32_bf16 v[68:71], v[180:183], v[224:227], v[68:71]
	v_mfma_f32_16x16x32_bf16 v[64:67], v[188:191], v[224:227], v[64:67]
	s_setprio 0
	s_barrier
; #define PG8_STAGE(bufoff, gbase, voff) do { _Pragma("unroll") for (int _i = 0; _i < 2; ++_i) \
;         __builtin_amdgcn_global_load_lds((const unsigned*)((const char*)(gbase) + (voff)[_i]), (LAS unsigned*)(lds + (bufoff) + ldsw + _i * 8192), 16, 0, 0); } while (0)
; #define PG8_LDA(dst, b, h) do { _Pragma("unroll") for (int m = 0; m < 4; ++m) _Pragma("unroll") for (int k = 0; k < 2; ++k) dst[m][k] = *(const LAS bf16x8*)(lds + PG8_SA(b, h) + aoff + m * 2048 + k * 1024); } while (0)
; #define PG8_MMA(ai, bj, At, Bt) do { __builtin_amdgcn_s_setprio(1); _Pragma("unroll") for (int m = 0; m < 4; ++m) _Pragma("unroll") for (int n = 0; n < 2; ++n) _Pragma("unroll") for (int k = 0; k < 2; ++k) \
;         acc[ai][bj][m][n] = __builtin_amdgcn_mfma_f32_16x16x32_bf16(Bt[n][k], At[m][k], acc[ai][bj][m][n], 0, 0, 0); __builtin_amdgcn_s_setprio(0); } while (0)
; #define PG8_WAIT_V(n) asm volatile("s_waitcnt vmcnt(" #n ")" ::: "memory")
; #define PG8_WAIT_L(n) asm volatile("s_waitcnt lgkmcnt(" #n ")" ::: "memory")
; #define PG8_BAR __builtin_amdgcn_s_barrier()
; #define PG8_SCHED __builtin_amdgcn_sched_barrier(0)
; template <int K, int LDA, int LDB, class Epi, class Sched>
; __device__ __forceinline__ void gemm_phase(LAS unsigned char* lds, const Gemm g, const Sched& S, const Epi& E, int wv) {
;     ...
;             PG8_LDA(At, 1, 1); PG8_STAGE(PG8_SB(1, 0), b3, voffB); PG8_STAGE(PG8_SB(1, 1), b3 + hstepB, voffB); PG8_STAGE(PG8_SA(1, 0), a3, voffA);
;             PG8_WAIT_V(8); PG8_WAIT_L(0); PG8_BAR; PG8_MMA(1, 0, At, B0); PG8_MMA(1, 1, At, B1); PG8_BAR; PG8_SCHED;
;     ...
;         if (!has_next) break;
; #pragma unroll
;         for (int a = 0; a < 2; ++a)
; #pragma unroll
;             for (int b = 0; b < 2; ++b)
; #pragma unroll
;                 for (int m = 0; m < 4; ++m)
; #pragma unroll
;                     for (int n = 0; n < 2; ++n) acc[a][b][m][n] = (f32x4){0.f, 0.f, 0.f, 0.f};
;         cur = nxt; cA = nA; cB = nB; ++ui;
;         if (wr == 1) PG8_BAR;
	s_mov_b32 m0, s9
	ds_read_b128 v[192:195], v161 offset:49152
	ds_read_b128 v[196:199], v161 offset:50176
	ds_read_b128 v[200:203], v161 offset:51200
	ds_read_b128 v[204:207], v161 offset:52224
	ds_read_b128 v[208:211], v161 offset:53248
	ds_read_b128 v[212:215], v161 offset:54272
	ds_read_b128 v[216:219], v161 offset:55296
	ds_read_b128 v[224:227], v161 offset:56320
	s_add_u32 s98, s76, s56
	s_addc_u32 s99, s77, s57
	global_load_lds_dwordx4 v132, s[98:99]
	s_mov_b32 m0, s14
	s_nop 0
	global_load_lds_dwordx4 v128, s[98:99]
	s_mov_b32 m0, s8
	s_nop 0
	global_load_lds_dwordx4 v132, s[70:71]
	s_mov_b32 m0, s85
	s_nop 0
	global_load_lds_dwordx4 v128, s[70:71]
	s_mov_b32 m0, s91
	s_nop 0
	s_add_u32 s100, s74, s56
	s_addc_u32 s101, s75, s57
	global_load_lds_dwordx4 v134, s[100:101]
	s_mov_b32 m0, s92
	s_nop 0
	global_load_lds_dwordx4 v130, s[100:101]
	s_waitcnt vmcnt(8)
	s_waitcnt lgkmcnt(0)
	s_barrier
	s_setprio 1
	v_mfma_f32_16x16x32_bf16 v[60:63], v[144:147], v[192:195], v[60:63]
	v_mfma_f32_16x16x32_bf16 v[56:59], v[168:171], v[192:195], v[56:59]
	v_mfma_f32_16x16x32_bf16 v[48:51], v[144:147], v[200:203], v[48:51]
	v_mfma_f32_16x16x32_bf16 v[40:43], v[168:171], v[200:203], v[40:43]
	v_mfma_f32_16x16x32_bf16 v[32:35], v[144:147], v[208:211], v[32:35]
	v_mfma_f32_16x16x32_bf16 v[24:27], v[168:171], v[208:211], v[24:27]
	v_mfma_f32_16x16x32_bf16 v[16:19], v[144:147], v[216:219], v[16:19]
	v_mfma_f32_16x16x32_bf16 v[8:11], v[168:171], v[216:219], v[8:11]
	v_mfma_f32_16x16x32_bf16 v[60:63], v[164:167], v[196:199], v[60:63]
	v_mfma_f32_16x16x32_bf16 v[56:59], v[172:175], v[196:199], v[56:59]
	v_mfma_f32_16x16x32_bf16 v[48:51], v[164:167], v[204:207], v[48:51]
	v_mfma_f32_16x16x32_bf16 v[40:43], v[172:175], v[204:207], v[40:43]
	v_mfma_f32_16x16x32_bf16 v[32:35], v[164:167], v[212:215], v[32:35]
	v_mfma_f32_16x16x32_bf16 v[24:27], v[172:175], v[212:215], v[24:27]
	v_mfma_f32_16x16x32_bf16 v[16:19], v[164:167], v[224:227], v[16:19]
	v_mfma_f32_16x16x32_bf16 v[8:11], v[172:175], v[224:227], v[8:11]
	v_mfma_f32_16x16x32_bf16 v[52:55], v[176:179], v[192:195], v[52:55]
	v_mfma_f32_16x16x32_bf16 v[44:47], v[184:187], v[192:195], v[44:47]
	v_mfma_f32_16x16x32_bf16 v[36:39], v[176:179], v[200:203], v[36:39]
	v_mfma_f32_16x16x32_bf16 v[28:31], v[184:187], v[200:203], v[28:31]
	v_mfma_f32_16x16x32_bf16 v[20:23], v[176:179], v[208:211], v[20:23]
	v_mfma_f32_16x16x32_bf16 v[12:15], v[184:187], v[208:211], v[12:15]
	v_mfma_f32_16x16x32_bf16 v[4:7], v[176:179], v[216:219], v[4:7]
	v_mfma_f32_16x16x32_bf16 v[0:3], v[184:187], v[216:219], v[0:3]
	v_mfma_f32_16x16x32_bf16 v[52:55], v[180:183], v[196:199], v[52:55]
	v_mfma_f32_16x16x32_bf16 v[44:47], v[188:191], v[196:199], v[44:47]
	v_mfma_f32_16x16x32_bf16 v[36:39], v[180:183], v[204:207], v[36:39]
	v_mfma_f32_16x16x32_bf16 v[28:31], v[188:191], v[204:207], v[28:31]
	v_mfma_f32_16x16x32_bf16 v[20:23], v[180:183], v[212:215], v[20:23]
	v_mfma_f32_16x16x32_bf16 v[12:15], v[188:191], v[212:215], v[12:15]
	v_mfma_f32_16x16x32_bf16 v[4:7], v[180:183], v[224:227], v[4:7]
	v_mfma_f32_16x16x32_bf16 v[0:3], v[188:191], v[224:227], v[0:3]
	s_setprio 0
	s_barrier
	s_andn2_b64 vcc, exec, s[12:13]
	s_mov_b64 s[70:71], -1
	s_mov_b64 s[12:13], 0
	s_mov_b64 s[72:73], 0x100
	s_cbranch_vccz .LBB0_519
	s_and_b64 vcc, exec, s[28:29]
	s_cbranch_vccz .LBB0_522
	s_barrier

; #define PG8_STAGE(bufoff, gbase, voff) do { _Pragma("unroll") for (int _i = 0; _i < 2; ++_i) \
;         __builtin_amdgcn_global_load_lds((const unsigned*)((const char*)(gbase) + (voff)[_i]), (LAS unsigned*)(lds + (bufoff) + ldsw + _i * 8192), 16, 0, 0); } while (0)
; #define PG8_LDA(dst, b, h) do { _Pragma("unroll") for (int m = 0; m < 4; ++m) _Pragma("unroll") for (int k = 0; k < 2; ++k) dst[m][k] = *(const LAS bf16x8*)(lds + PG8_SA(b, h) + aoff + m * 2048 + k * 1024); } while (0)
; #define PG8_LDB(dst, b, h) do { _Pragma("unroll") for (int n = 0; n < 2; ++n) _Pragma("unroll") for (int k = 0; k < 2; ++k) dst[n][k] = *(const LAS bf16x8*)(lds + PG8_SB(b, h) + boff + n * 2048 + k * 1024); } while (0)
; #define PG8_MMA(ai, bj, At, Bt) do { __builtin_amdgcn_s_setprio(1); _Pragma("unroll") for (int m = 0; m < 4; ++m) _Pragma("unroll") for (int n = 0; n < 2; ++n) _Pragma("unroll") for (int k = 0; k < 2; ++k) \
;         acc[ai][bj][m][n] = __builtin_amdgcn_mfma_f32_16x16x32_bf16(Bt[n][k], At[m][k], acc[ai][bj][m][n], 0, 0, 0); __builtin_amdgcn_s_setprio(0); } while (0)
; #define PG8_WAIT_V(n) asm volatile("s_waitcnt vmcnt(" #n ")" ::: "memory")
; #define PG8_BAR __builtin_amdgcn_s_barrier()
; template <int K, int LDA, int LDB, class Epi, class Sched>
; __device__ __forceinline__ void gemm_phase(LAS unsigned char* lds, const Gemm g, const Sched& S, const Epi& E, int wv) {
;     ...
;         for (int t = 0; t < nt; t += 2) {
;             const bool last = (t == nt - 2);
;             const char* a1 = cA + (size_t)(t + 1) * kstep;
;             const char* a2 = last ? nA : cA + (size_t)(t + 2) * kstep; const char* b2 = last ? nB : cB + (size_t)(t + 2) * kstep;
;             const char* a3 = a2 + kstep; const char* b3 = b2 + kstep;
;             PG8_LDB(B0, 0, 0); PG8_LDB(B1, 0, 1); PG8_SCHED; PG8_LDA(At, 0, 0); PG8_STAGE(PG8_SA(1, 1), a1 + hstepA, voffA);
;             PG8_WAIT_V(8); PG8_WAIT_L(0); PG8_BAR; PG8_MMA(0, 0, At, B0); PG8_MMA(0, 1, At, B1); PG8_BAR; PG8_SCHED;
;             PG8_LDA(At, 0, 1); PG8_STAGE(PG8_SB(0, 0), b2, voffB); PG8_STAGE(PG8_SB(0, 1), b2 + hstepB, voffB); PG8_STAGE(PG8_SA(0, 0), a2, voffA);
;             PG8_WAIT_V(8); PG8_WAIT_L(0); PG8_BAR; PG8_MMA(1, 0, At, B0); PG8_MMA(1, 1, At, B1); PG8_BAR; PG8_SCHED;
;             PG8_LDB(B0, 1, 0); PG8_LDB(B1, 1, 1); PG8_SCHED; PG8_LDA(At, 1, 0); PG8_STAGE(PG8_SA(0, 1), a2 + hstepA, voffA);
.LBB0_541:
	s_add_u32 s14, s70, s74
	s_addc_u32 s15, s71, s75
	s_add_u32 s34, s14, 0x100
	s_addc_u32 s35, s15, 0
	s_and_b64 s[8:9], s[72:73], exec
	s_cselect_b32 s77, s61, s35
	s_cselect_b32 s76, s96, s34
	s_add_u32 s8, s68, s74
	s_addc_u32 s9, s69, s75
	s_add_u32 s34, s8, 0x100
	s_addc_u32 s35, s9, 0
	s_and_b64 s[8:9], s[72:73], exec
	s_cselect_b32 s79, s63, s35
	s_cselect_b32 s78, s62, s34
	s_add_u32 s82, s14, 0x10080
	ds_read_b128 v[128:131], v165
	ds_read_b128 v[144:147], v165 offset:1024
	ds_read_b128 v[148:151], v165 offset:2048
	ds_read_b128 v[152:155], v165 offset:3072
	ds_read_b128 v[156:159], v166
	ds_read_b128 v[170:173], v166 offset:1024
	ds_read_b128 v[174:177], v166 offset:2048
	ds_read_b128 v[178:181], v166 offset:3072
	s_addc_u32 s83, s15, 0
	s_add_i32 s50, s92, s24
	s_add_i32 m0, s67, 0xc000
	s_add_i32 s34, s67, 0xe000
	s_add_i32 s14, s50, 0x2000
	s_add_u32 s80, s78, 0x120000
	s_addc_u32 s81, s79, 0
	s_add_i32 s85, s93, s24
	s_add_i32 s15, s85, 0x2000
	s_add_i32 vcc_hi, 0, 0x18000
	s_add_i32 vcc_lo, 0, 0x1c000
	s_add_u32 s74, s76, 0x10000
	s_addc_u32 s75, s77, 0
	s_add_i32 s97, vcc_hi, s24
	s_add_i32 s9, s97, 0x2000
	s_add_u32 s72, s78, 0x120080
	s_addc_u32 s73, s79, 0
	s_add_i32 s84, vcc_lo, s24
	s_add_i32 s8, s84, 0x2000
	ds_read_b128 v[182:185], v167
	ds_read_b128 v[186:189], v167 offset:1024
	ds_read_b128 v[190:193], v167 offset:2048
	ds_read_b128 v[194:197], v167 offset:3072
	ds_read_b128 v[198:201], v167 offset:4096
	ds_read_b128 v[202:205], v167 offset:5120
	ds_read_b128 v[206:209], v167 offset:6144
	ds_read_b128 v[210:213], v167 offset:7168
	global_load_lds_dwordx4 v138, s[82:83]
	s_mov_b32 m0, s34
	s_nop 0
	global_load_lds_dwordx4 v134, s[82:83]
	s_waitcnt vmcnt(8)
	s_waitcnt lgkmcnt(0)
	s_barrier
	s_setprio 1
	v_mfma_f32_16x16x32_bf16 v[124:127], v[128:131], v[182:185], v[124:127]
	v_mfma_f32_16x16x32_bf16 v[120:123], v[148:151], v[182:185], v[120:123]
	v_mfma_f32_16x16x32_bf16 v[112:115], v[128:131], v[190:193], v[112:115]
	v_mfma_f32_16x16x32_bf16 v[104:107], v[148:151], v[190:193], v[104:107]
	v_mfma_f32_16x16x32_bf16 v[96:99], v[128:131], v[198:201], v[96:99]
	v_mfma_f32_16x16x32_bf16 v[88:91], v[148:151], v[198:201], v[88:91]
	v_mfma_f32_16x16x32_bf16 v[80:83], v[128:131], v[206:209], v[80:83]
	v_mfma_f32_16x16x32_bf16 v[72:75], v[148:151], v[206:209], v[72:75]
	v_mfma_f32_16x16x32_bf16 v[124:127], v[144:147], v[186:189], v[124:127]
	v_mfma_f32_16x16x32_bf16 v[120:123], v[152:155], v[186:189], v[120:123]
	v_mfma_f32_16x16x32_bf16 v[112:115], v[144:147], v[194:197], v[112:115]
	v_mfma_f32_16x16x32_bf16 v[104:107], v[152:155], v[194:197], v[104:107]
	v_mfma_f32_16x16x32_bf16 v[96:99], v[144:147], v[202:205], v[96:99]
	v_mfma_f32_16x16x32_bf16 v[88:91], v[152:155], v[202:205], v[88:91]
	v_mfma_f32_16x16x32_bf16 v[80:83], v[144:147], v[210:213], v[80:83]
	v_mfma_f32_16x16x32_bf16 v[72:75], v[152:155], v[210:213], v[72:75]
	v_mfma_f32_16x16x32_bf16 v[116:119], v[156:159], v[182:185], v[116:119]
	v_mfma_f32_16x16x32_bf16 v[108:111], v[174:177], v[182:185], v[108:111]
	v_mfma_f32_16x16x32_bf16 v[100:103], v[156:159], v[190:193], v[100:103]
	v_mfma_f32_16x16x32_bf16 v[92:95], v[174:177], v[190:193], v[92:95]
	v_mfma_f32_16x16x32_bf16 v[84:87], v[156:159], v[198:201], v[84:87]
	v_mfma_f32_16x16x32_bf16 v[76:79], v[174:177], v[198:201], v[76:79]
	v_mfma_f32_16x16x32_bf16 v[68:71], v[156:159], v[206:209], v[68:71]
	v_mfma_f32_16x16x32_bf16 v[64:67], v[174:177], v[206:209], v[64:67]
	v_mfma_f32_16x16x32_bf16 v[116:119], v[170:173], v[186:189], v[116:119]
	v_mfma_f32_16x16x32_bf16 v[108:111], v[178:181], v[186:189], v[108:111]
	v_mfma_f32_16x16x32_bf16 v[100:103], v[170:173], v[194:197], v[100:103]
	v_mfma_f32_16x16x32_bf16 v[92:95], v[178:181], v[194:197], v[92:95]
	v_mfma_f32_16x16x32_bf16 v[84:87], v[170:173], v[202:205], v[84:87]
	v_mfma_f32_16x16x32_bf16 v[76:79], v[178:181], v[202:205], v[76:79]
	v_mfma_f32_16x16x32_bf16 v[68:71], v[170:173], v[210:213], v[68:71]
	v_mfma_f32_16x16x32_bf16 v[64:67], v[178:181], v[210:213], v[64:67]
	s_setprio 0
	s_barrier
	s_mov_b32 m0, s50
	ds_read_b128 v[182:185], v167 offset:16384
	ds_read_b128 v[186:189], v167 offset:17408
	ds_read_b128 v[190:193], v167 offset:18432
	ds_read_b128 v[194:197], v167 offset:19456
	ds_read_b128 v[198:201], v167 offset:20480
	ds_read_b128 v[202:205], v167 offset:21504
	ds_read_b128 v[206:209], v167 offset:22528
	ds_read_b128 v[210:213], v167 offset:23552
	global_load_lds_dwordx4 v136, s[78:79]
	s_mov_b32 m0, s14
	s_nop 0
	global_load_lds_dwordx4 v132, s[78:79]
	s_mov_b32 m0, s85
	s_nop 0
	global_load_lds_dwordx4 v136, s[80:81]
	s_mov_b32 m0, s15
	s_nop 0
	global_load_lds_dwordx4 v132, s[80:81]
	s_mov_b32 m0, s67
	s_nop 0
	global_load_lds_dwordx4 v138, s[76:77]
	s_mov_b32 m0, s86
	s_nop 0
	global_load_lds_dwordx4 v134, s[76:77]
	s_waitcnt vmcnt(8)
	s_waitcnt lgkmcnt(0)
	s_barrier
; #define PG8_STAGE(bufoff, gbase, voff) do { _Pragma("unroll") for (int _i = 0; _i < 2; ++_i) \
;         __builtin_amdgcn_global_load_lds((const unsigned*)((const char*)(gbase) + (voff)[_i]), (LAS unsigned*)(lds + (bufoff) + ldsw + _i * 8192), 16, 0, 0); } while (0)
; #define PG8_LDA(dst, b, h) do { _Pragma("unroll") for (int m = 0; m < 4; ++m) _Pragma("unroll") for (int k = 0; k < 2; ++k) dst[m][k] = *(const LAS bf16x8*)(lds + PG8_SA(b, h) + aoff + m * 2048 + k * 1024); } while (0)
; #define PG8_LDB(dst, b, h) do { _Pragma("unroll") for (int n = 0; n < 2; ++n) _Pragma("unroll") for (int k = 0; k < 2; ++k) dst[n][k] = *(const LAS bf16x8*)(lds + PG8_SB(b, h) + boff + n * 2048 + k * 1024); } while (0)
; #define PG8_MMA(ai, bj, At, Bt) do { __builtin_amdgcn_s_setprio(1); _Pragma("unroll") for (int m = 0; m < 4; ++m) _Pragma("unroll") for (int n = 0; n < 2; ++n) _Pragma("unroll") for (int k = 0; k < 2; ++k) \
;         acc[ai][bj][m][n] = __builtin_amdgcn_mfma_f32_16x16x32_bf16(Bt[n][k], At[m][k], acc[ai][bj][m][n], 0, 0, 0); __builtin_amdgcn_s_setprio(0); } while (0)
; #define PG8_WAIT_V(n) asm volatile("s_waitcnt vmcnt(" #n ")" ::: "memory")
; #define PG8_WAIT_L(n) asm volatile("s_waitcnt lgkmcnt(" #n ")" ::: "memory")
; #define PG8_BAR __builtin_amdgcn_s_barrier()
; #define PG8_SCHED __builtin_amdgcn_sched_barrier(0)
; template <int K, int LDA, int LDB, class Epi, class Sched>
; __device__ __forceinline__ void gemm_phase(LAS unsigned char* lds, const Gemm g, const Sched& S, const Epi& E, int wv) {
;     ...
;             PG8_WAIT_V(8); PG8_WAIT_L(0); PG8_BAR; PG8_MMA(1, 0, At, B0); PG8_MMA(1, 1, At, B1); PG8_BAR; PG8_SCHED;
;             PG8_LDB(B0, 1, 0); PG8_LDB(B1, 1, 1); PG8_SCHED; PG8_LDA(At, 1, 0); PG8_STAGE(PG8_SA(0, 1), a2 + hstepA, voffA);
;             PG8_WAIT_V(8); PG8_WAIT_L(0); PG8_BAR; PG8_MMA(0, 0, At, B0); PG8_MMA(0, 1, At, B1); PG8_BAR; PG8_SCHED;
;             PG8_LDA(At, 1, 1); PG8_STAGE(PG8_SB(1, 0), b3, voffB); PG8_STAGE(PG8_SB(1, 1), b3 + hstepB, voffB); PG8_STAGE(PG8_SA(1, 0), a3, voffA);
	s_setprio 1
	v_mfma_f32_16x16x32_bf16 v[60:63], v[128:131], v[182:185], v[60:63]
	v_mfma_f32_16x16x32_bf16 v[56:59], v[148:151], v[182:185], v[56:59]
	v_mfma_f32_16x16x32_bf16 v[48:51], v[128:131], v[190:193], v[48:51]
	v_mfma_f32_16x16x32_bf16 v[40:43], v[148:151], v[190:193], v[40:43]
	v_mfma_f32_16x16x32_bf16 v[32:35], v[128:131], v[198:201], v[32:35]
	v_mfma_f32_16x16x32_bf16 v[24:27], v[148:151], v[198:201], v[24:27]
	v_mfma_f32_16x16x32_bf16 v[16:19], v[128:131], v[206:209], v[16:19]
	v_mfma_f32_16x16x32_bf16 v[8:11], v[148:151], v[206:209], v[8:11]
	v_mfma_f32_16x16x32_bf16 v[60:63], v[144:147], v[186:189], v[60:63]
	v_mfma_f32_16x16x32_bf16 v[56:59], v[152:155], v[186:189], v[56:59]
	v_mfma_f32_16x16x32_bf16 v[48:51], v[144:147], v[194:197], v[48:51]
	v_mfma_f32_16x16x32_bf16 v[40:43], v[152:155], v[194:197], v[40:43]
	v_mfma_f32_16x16x32_bf16 v[32:35], v[144:147], v[202:205], v[32:35]
	v_mfma_f32_16x16x32_bf16 v[24:27], v[152:155], v[202:205], v[24:27]
	v_mfma_f32_16x16x32_bf16 v[16:19], v[144:147], v[210:213], v[16:19]
	v_mfma_f32_16x16x32_bf16 v[8:11], v[152:155], v[210:213], v[8:11]
	v_mfma_f32_16x16x32_bf16 v[52:55], v[156:159], v[182:185], v[52:55]
	v_mfma_f32_16x16x32_bf16 v[44:47], v[174:177], v[182:185], v[44:47]
	v_mfma_f32_16x16x32_bf16 v[36:39], v[156:159], v[190:193], v[36:39]
	v_mfma_f32_16x16x32_bf16 v[28:31], v[174:177], v[190:193], v[28:31]
	v_mfma_f32_16x16x32_bf16 v[20:23], v[156:159], v[198:201], v[20:23]
	v_mfma_f32_16x16x32_bf16 v[12:15], v[174:177], v[198:201], v[12:15]
	v_mfma_f32_16x16x32_bf16 v[4:7], v[156:159], v[206:209], v[4:7]
	v_mfma_f32_16x16x32_bf16 v[0:3], v[174:177], v[206:209], v[0:3]
	v_mfma_f32_16x16x32_bf16 v[52:55], v[170:173], v[186:189], v[52:55]
	v_mfma_f32_16x16x32_bf16 v[44:47], v[178:181], v[186:189], v[44:47]
	v_mfma_f32_16x16x32_bf16 v[36:39], v[170:173], v[194:197], v[36:39]
	v_mfma_f32_16x16x32_bf16 v[28:31], v[178:181], v[194:197], v[28:31]
	v_mfma_f32_16x16x32_bf16 v[20:23], v[170:173], v[202:205], v[20:23]
	v_mfma_f32_16x16x32_bf16 v[12:15], v[178:181], v[202:205], v[12:15]
	v_mfma_f32_16x16x32_bf16 v[4:7], v[170:173], v[210:213], v[4:7]
	v_mfma_f32_16x16x32_bf16 v[0:3], v[178:181], v[210:213], v[0:3]
	s_setprio 0
	s_barrier
	v_add_u32_e32 v152, vcc_hi, v163
	v_add_u32_e32 v169, vcc_lo, v163
	ds_read_b128 v[128:131], v152
	ds_read_b128 v[144:147], v152 offset:1024
	ds_read_b128 v[148:151], v152 offset:2048
	ds_read_b128 v[152:155], v152 offset:3072
	ds_read_b128 v[156:159], v169
	ds_read_b128 v[170:173], v169 offset:1024
	ds_read_b128 v[174:177], v169 offset:2048
	ds_read_b128 v[178:181], v169 offset:3072
	s_mov_b32 m0, s87
	ds_read_b128 v[182:185], v167 offset:32768
	ds_read_b128 v[186:189], v167 offset:33792
	ds_read_b128 v[190:193], v167 offset:34816
	ds_read_b128 v[194:197], v167 offset:35840
	ds_read_b128 v[198:201], v167 offset:36864
	ds_read_b128 v[202:205], v167 offset:37888
	ds_read_b128 v[206:209], v167 offset:38912
	ds_read_b128 v[210:213], v167 offset:39936
	global_load_lds_dwordx4 v138, s[74:75]
	s_mov_b32 m0, s88
	s_nop 0
	global_load_lds_dwordx4 v134, s[74:75]
	s_waitcnt vmcnt(8)
	s_waitcnt lgkmcnt(0)
	s_barrier
	s_setprio 1
	v_mfma_f32_16x16x32_bf16 v[124:127], v[128:131], v[182:185], v[124:127]
	v_mfma_f32_16x16x32_bf16 v[120:123], v[148:151], v[182:185], v[120:123]
	v_mfma_f32_16x16x32_bf16 v[112:115], v[128:131], v[190:193], v[112:115]
	v_mfma_f32_16x16x32_bf16 v[104:107], v[148:151], v[190:193], v[104:107]
	v_mfma_f32_16x16x32_bf16 v[96:99], v[128:131], v[198:201], v[96:99]
	v_mfma_f32_16x16x32_bf16 v[88:91], v[148:151], v[198:201], v[88:91]
	v_mfma_f32_16x16x32_bf16 v[80:83], v[128:131], v[206:209], v[80:83]
	v_mfma_f32_16x16x32_bf16 v[72:75], v[148:151], v[206:209], v[72:75]
	v_mfma_f32_16x16x32_bf16 v[124:127], v[144:147], v[186:189], v[124:127]
	v_mfma_f32_16x16x32_bf16 v[120:123], v[152:155], v[186:189], v[120:123]
	v_mfma_f32_16x16x32_bf16 v[112:115], v[144:147], v[194:197], v[112:115]
	v_mfma_f32_16x16x32_bf16 v[104:107], v[152:155], v[194:197], v[104:107]
	v_mfma_f32_16x16x32_bf16 v[96:99], v[144:147], v[202:205], v[96:99]
	v_mfma_f32_16x16x32_bf16 v[88:91], v[152:155], v[202:205], v[88:91]
	v_mfma_f32_16x16x32_bf16 v[80:83], v[144:147], v[210:213], v[80:83]
	v_mfma_f32_16x16x32_bf16 v[72:75], v[152:155], v[210:213], v[72:75]
	v_mfma_f32_16x16x32_bf16 v[116:119], v[156:159], v[182:185], v[116:119]
	v_mfma_f32_16x16x32_bf16 v[108:111], v[174:177], v[182:185], v[108:111]
	v_mfma_f32_16x16x32_bf16 v[100:103], v[156:159], v[190:193], v[100:103]
	v_mfma_f32_16x16x32_bf16 v[92:95], v[174:177], v[190:193], v[92:95]
	v_mfma_f32_16x16x32_bf16 v[84:87], v[156:159], v[198:201], v[84:87]
	v_mfma_f32_16x16x32_bf16 v[76:79], v[174:177], v[198:201], v[76:79]
	v_mfma_f32_16x16x32_bf16 v[68:71], v[156:159], v[206:209], v[68:71]
	v_mfma_f32_16x16x32_bf16 v[64:67], v[174:177], v[206:209], v[64:67]
	v_mfma_f32_16x16x32_bf16 v[116:119], v[170:173], v[186:189], v[116:119]
	v_mfma_f32_16x16x32_bf16 v[108:111], v[178:181], v[186:189], v[108:111]
	v_mfma_f32_16x16x32_bf16 v[100:103], v[170:173], v[194:197], v[100:103]
	v_mfma_f32_16x16x32_bf16 v[92:95], v[178:181], v[194:197], v[92:95]
	v_mfma_f32_16x16x32_bf16 v[84:87], v[170:173], v[202:205], v[84:87]
	v_mfma_f32_16x16x32_bf16 v[76:79], v[178:181], v[202:205], v[76:79]
	v_mfma_f32_16x16x32_bf16 v[68:71], v[170:173], v[210:213], v[68:71]
	v_mfma_f32_16x16x32_bf16 v[64:67], v[178:181], v[210:213], v[64:67]
	s_setprio 0
	s_barrier
; #define PG8_STAGE(bufoff, gbase, voff) do { _Pragma("unroll") for (int _i = 0; _i < 2; ++_i) \
;         __builtin_amdgcn_global_load_lds((const unsigned*)((const char*)(gbase) + (voff)[_i]), (LAS unsigned*)(lds + (bufoff) + ldsw + _i * 8192), 16, 0, 0); } while (0)
; #define PG8_LDA(dst, b, h) do { _Pragma("unroll") for (int m = 0; m < 4; ++m) _Pragma("unroll") for (int k = 0; k < 2; ++k) dst[m][k] = *(const LAS bf16x8*)(lds + PG8_SA(b, h) + aoff + m * 2048 + k * 1024); } while (0)
; #define PG8_MMA(ai, bj, At, Bt) do { __builtin_amdgcn_s_setprio(1); _Pragma("unroll") for (int m = 0; m < 4; ++m) _Pragma("unroll") for (int n = 0; n < 2; ++n) _Pragma("unroll") for (int k = 0; k < 2; ++k) \
;         acc[ai][bj][m][n] = __builtin_amdgcn_mfma_f32_16x16x32_bf16(Bt[n][k], At[m][k], acc[ai][bj][m][n], 0, 0, 0); __builtin_amdgcn_s_setprio(0); } while (0)
; #define PG8_WAIT_V(n) asm volatile("s_waitcnt vmcnt(" #n ")" ::: "memory")
; #define PG8_WAIT_L(n) asm volatile("s_waitcnt lgkmcnt(" #n ")" ::: "memory")
; #define PG8_BAR __builtin_amdgcn_s_barrier()
; #define PG8_SCHED __builtin_amdgcn_sched_barrier(0)
; template <int K, int LDA, int LDB, class Epi, class Sched>
; __device__ __forceinline__ void gemm_phase(LAS unsigned char* lds, const Gemm g, const Sched& S, const Epi& E, int wv) {
;     ...
;             PG8_LDA(At, 1, 1); PG8_STAGE(PG8_SB(1, 0), b3, voffB); PG8_STAGE(PG8_SB(1, 1), b3 + hstepB, voffB); PG8_STAGE(PG8_SA(1, 0), a3, voffA);
;             PG8_WAIT_V(8); PG8_WAIT_L(0); PG8_BAR; PG8_MMA(1, 0, At, B0); PG8_MMA(1, 1, At, B1); PG8_BAR; PG8_SCHED;
;     ...
;         if (!has_next) break;
; #pragma unroll
;         for (int a = 0; a < 2; ++a)
; #pragma unroll
;             for (int b = 0; b < 2; ++b)
; #pragma unroll
;                 for (int m = 0; m < 4; ++m)
; #pragma unroll
;                     for (int n = 0; n < 2; ++n) acc[a][b][m][n] = (f32x4){0.f, 0.f, 0.f, 0.f};
;         cur = nxt; cA = nA; cB = nB; ++ui;
;         if (wr == 1) PG8_BAR;
	s_mov_b32 m0, s97
	ds_read_b128 v[182:185], v167 offset:49152
	ds_read_b128 v[186:189], v167 offset:50176
	ds_read_b128 v[190:193], v167 offset:51200
	ds_read_b128 v[194:197], v167 offset:52224
	ds_read_b128 v[198:201], v167 offset:53248
	ds_read_b128 v[202:205], v167 offset:54272
	ds_read_b128 v[206:209], v167 offset:55296
	ds_read_b128 v[210:213], v167 offset:56320
	s_add_u32 s98, s78, s58
	s_addc_u32 s99, s79, s59
	global_load_lds_dwordx4 v136, s[98:99]
	s_mov_b32 m0, s9
	s_nop 0
	global_load_lds_dwordx4 v132, s[98:99]
	s_mov_b32 m0, s84
	s_nop 0
	global_load_lds_dwordx4 v136, s[72:73]
	s_mov_b32 m0, s8
	s_nop 0
	global_load_lds_dwordx4 v132, s[72:73]
	s_mov_b32 m0, s90
	s_nop 0
	s_add_u32 s100, s76, s58
	s_addc_u32 s101, s77, s59
	global_load_lds_dwordx4 v138, s[100:101]
	s_mov_b32 m0, s91
	s_nop 0
	global_load_lds_dwordx4 v134, s[100:101]
	s_waitcnt vmcnt(8)
	s_waitcnt lgkmcnt(0)
	s_barrier
	s_setprio 1
	v_mfma_f32_16x16x32_bf16 v[60:63], v[128:131], v[182:185], v[60:63]
	v_mfma_f32_16x16x32_bf16 v[56:59], v[148:151], v[182:185], v[56:59]
	v_mfma_f32_16x16x32_bf16 v[48:51], v[128:131], v[190:193], v[48:51]
	v_mfma_f32_16x16x32_bf16 v[40:43], v[148:151], v[190:193], v[40:43]
	v_mfma_f32_16x16x32_bf16 v[32:35], v[128:131], v[198:201], v[32:35]
	v_mfma_f32_16x16x32_bf16 v[24:27], v[148:151], v[198:201], v[24:27]
	v_mfma_f32_16x16x32_bf16 v[16:19], v[128:131], v[206:209], v[16:19]
	v_mfma_f32_16x16x32_bf16 v[8:11], v[148:151], v[206:209], v[8:11]
	v_mfma_f32_16x16x32_bf16 v[60:63], v[144:147], v[186:189], v[60:63]
	v_mfma_f32_16x16x32_bf16 v[56:59], v[152:155], v[186:189], v[56:59]
	v_mfma_f32_16x16x32_bf16 v[48:51], v[144:147], v[194:197], v[48:51]
	v_mfma_f32_16x16x32_bf16 v[40:43], v[152:155], v[194:197], v[40:43]
	v_mfma_f32_16x16x32_bf16 v[32:35], v[144:147], v[202:205], v[32:35]
	v_mfma_f32_16x16x32_bf16 v[24:27], v[152:155], v[202:205], v[24:27]
	v_mfma_f32_16x16x32_bf16 v[16:19], v[144:147], v[210:213], v[16:19]
	v_mfma_f32_16x16x32_bf16 v[8:11], v[152:155], v[210:213], v[8:11]
	v_mfma_f32_16x16x32_bf16 v[52:55], v[156:159], v[182:185], v[52:55]
	v_mfma_f32_16x16x32_bf16 v[44:47], v[174:177], v[182:185], v[44:47]
	v_mfma_f32_16x16x32_bf16 v[36:39], v[156:159], v[190:193], v[36:39]
	v_mfma_f32_16x16x32_bf16 v[28:31], v[174:177], v[190:193], v[28:31]
	v_mfma_f32_16x16x32_bf16 v[20:23], v[156:159], v[198:201], v[20:23]
	v_mfma_f32_16x16x32_bf16 v[12:15], v[174:177], v[198:201], v[12:15]
	v_mfma_f32_16x16x32_bf16 v[4:7], v[156:159], v[206:209], v[4:7]
	v_mfma_f32_16x16x32_bf16 v[0:3], v[174:177], v[206:209], v[0:3]
	v_mfma_f32_16x16x32_bf16 v[52:55], v[170:173], v[186:189], v[52:55]
	v_mfma_f32_16x16x32_bf16 v[44:47], v[178:181], v[186:189], v[44:47]
	v_mfma_f32_16x16x32_bf16 v[36:39], v[170:173], v[194:197], v[36:39]
	v_mfma_f32_16x16x32_bf16 v[28:31], v[178:181], v[194:197], v[28:31]
	v_mfma_f32_16x16x32_bf16 v[20:23], v[170:173], v[202:205], v[20:23]
	v_mfma_f32_16x16x32_bf16 v[12:15], v[178:181], v[202:205], v[12:15]
	v_mfma_f32_16x16x32_bf16 v[4:7], v[170:173], v[210:213], v[4:7]
	v_mfma_f32_16x16x32_bf16 v[0:3], v[178:181], v[210:213], v[0:3]
	s_setprio 0
	s_barrier
	s_andn2_b64 vcc, exec, s[16:17]
	s_mov_b64 s[72:73], -1
	s_mov_b64 s[16:17], 0
	s_mov_b64 s[74:75], 0x100
	s_cbranch_vccz .LBB0_541
	s_and_b64 vcc, exec, s[28:29]
	s_cbranch_vccz .LBB0_544
	s_barrier

; #define PG8_STAGE(bufoff, gbase, voff) do { _Pragma("unroll") for (int _i = 0; _i < 2; ++_i) \
;         __builtin_amdgcn_global_load_lds((const unsigned*)((const char*)(gbase) + (voff)[_i]), (LAS unsigned*)(lds + (bufoff) + ldsw + _i * 8192), 16, 0, 0); } while (0)
; #define PG8_LDA(dst, b, h) do { _Pragma("unroll") for (int m = 0; m < 4; ++m) _Pragma("unroll") for (int k = 0; k < 2; ++k) dst[m][k] = *(const LAS bf16x8*)(lds + PG8_SA(b, h) + aoff + m * 2048 + k * 1024); } while (0)
; #define PG8_LDB(dst, b, h) do { _Pragma("unroll") for (int n = 0; n < 2; ++n) _Pragma("unroll") for (int k = 0; k < 2; ++k) dst[n][k] = *(const LAS bf16x8*)(lds + PG8_SB(b, h) + boff + n * 2048 + k * 1024); } while (0)
; #define PG8_MMA(ai, bj, At, Bt) do { __builtin_amdgcn_s_setprio(1); _Pragma("unroll") for (int m = 0; m < 4; ++m) _Pragma("unroll") for (int n = 0; n < 2; ++n) _Pragma("unroll") for (int k = 0; k < 2; ++k) \
;         acc[ai][bj][m][n] = __builtin_amdgcn_mfma_f32_16x16x32_bf16(Bt[n][k], At[m][k], acc[ai][bj][m][n], 0, 0, 0); __builtin_amdgcn_s_setprio(0); } while (0)
; #define PG8_WAIT_V(n) asm volatile("s_waitcnt vmcnt(" #n ")" ::: "memory")
; template <int K, int LDA, int LDB, class Epi, class Sched>
; __device__ __forceinline__ void gemm_phase(LAS unsigned char* lds, const Gemm g, const Sched& S, const Epi& E, int wv) {
;     ...
;             PG8_LDB(B0, 0, 0); PG8_LDB(B1, 0, 1); PG8_SCHED; PG8_LDA(At, 0, 0); PG8_STAGE(PG8_SA(1, 1), a1 + hstepA, voffA);
;             PG8_WAIT_V(8); PG8_WAIT_L(0); PG8_BAR; PG8_MMA(0, 0, At, B0); PG8_MMA(0, 1, At, B1); PG8_BAR; PG8_SCHED;
;             PG8_LDA(At, 0, 1); PG8_STAGE(PG8_SB(0, 0), b2, voffB); PG8_STAGE(PG8_SB(0, 1), b2 + hstepB, voffB); PG8_STAGE(PG8_SA(0, 0), a2, voffA);
;             PG8_WAIT_V(8); PG8_WAIT_L(0); PG8_BAR; PG8_MMA(1, 0, At, B0); PG8_MMA(1, 1, At, B1); PG8_BAR; PG8_SCHED;
;             PG8_LDB(B0, 1, 0); PG8_LDB(B1, 1, 1); PG8_SCHED; PG8_LDA(At, 1, 0); PG8_STAGE(PG8_SA(0, 1), a2 + hstepA, voffA);
;             PG8_WAIT_V(8); PG8_WAIT_L(0); PG8_BAR; PG8_MMA(0, 0, At, B0); PG8_MMA(0, 1, At, B1); PG8_BAR; PG8_SCHED;
;             PG8_LDA(At, 1, 1); PG8_STAGE(PG8_SB(1, 0), b3, voffB); PG8_STAGE(PG8_SB(1, 1), b3 + hstepB, voffB); PG8_STAGE(PG8_SA(1, 0), a3, voffA);
;             PG8_WAIT_V(8); PG8_WAIT_L(0); PG8_BAR; PG8_MMA(1, 0, At, B0); PG8_MMA(1, 1, At, B1); PG8_BAR; PG8_SCHED;
.LBB0_700:
	ds_read_b128 v[144:147], v185
	ds_read_b128 v[148:151], v185 offset:1024
	ds_read_b128 v[152:155], v185 offset:2048
	ds_read_b128 v[156:159], v185 offset:3072
	ds_read_b128 v[160:163], v186
	ds_read_b128 v[164:167], v186 offset:1024
	ds_read_b128 v[168:171], v186 offset:2048
	ds_read_b128 v[172:175], v186 offset:3072
	s_add_u32 s8, s66, 0xfff80080
	s_addc_u32 s9, s67, -1
	s_cmp_eq_u32 s82, 28
	s_cselect_b32 s71, s59, s9
	s_cselect_b32 s70, s78, s8
	s_cselect_b32 s69, s57, s81
	s_cselect_b32 s68, s79, s80
	s_add_i32 m0, s44, 0xc000
	ds_read_b128 v[176:179], v187
	ds_read_b128 v[188:191], v187 offset:1024
	ds_read_b128 v[192:195], v187 offset:2048
	ds_read_b128 v[196:199], v187 offset:3072
	ds_read_b128 v[200:203], v187 offset:4096
	ds_read_b128 v[204:207], v187 offset:5120
	ds_read_b128 v[208:211], v187 offset:6144
	ds_read_b128 v[212:215], v187 offset:7168
	global_load_lds_dwordx4 v136, s[66:67]
	s_add_i32 m0, s44, 0xe000
	s_nop 0
	global_load_lds_dwordx4 v138, s[66:67]
	s_waitcnt vmcnt(8)
	s_waitcnt lgkmcnt(0)
	s_barrier
	s_setprio 1
	v_mfma_f32_16x16x32_bf16 v[124:127], v[144:147], v[176:179], v[124:127]
	v_mfma_f32_16x16x32_bf16 v[120:123], v[152:155], v[176:179], v[120:123]
	v_mfma_f32_16x16x32_bf16 v[112:115], v[144:147], v[192:195], v[112:115]
	v_mfma_f32_16x16x32_bf16 v[104:107], v[152:155], v[192:195], v[104:107]
	v_mfma_f32_16x16x32_bf16 v[92:95], v[144:147], v[200:203], v[92:95]
	v_mfma_f32_16x16x32_bf16 v[88:91], v[152:155], v[200:203], v[88:91]
	v_mfma_f32_16x16x32_bf16 v[80:83], v[144:147], v[208:211], v[80:83]
	v_mfma_f32_16x16x32_bf16 v[72:75], v[152:155], v[208:211], v[72:75]
	v_mfma_f32_16x16x32_bf16 v[124:127], v[148:151], v[188:191], v[124:127]
	v_mfma_f32_16x16x32_bf16 v[120:123], v[156:159], v[188:191], v[120:123]
	v_mfma_f32_16x16x32_bf16 v[112:115], v[148:151], v[196:199], v[112:115]
	v_mfma_f32_16x16x32_bf16 v[104:107], v[156:159], v[196:199], v[104:107]
	v_mfma_f32_16x16x32_bf16 v[92:95], v[148:151], v[204:207], v[92:95]
	v_mfma_f32_16x16x32_bf16 v[88:91], v[156:159], v[204:207], v[88:91]
	v_mfma_f32_16x16x32_bf16 v[80:83], v[148:151], v[212:215], v[80:83]
	v_mfma_f32_16x16x32_bf16 v[72:75], v[156:159], v[212:215], v[72:75]
	v_mfma_f32_16x16x32_bf16 v[116:119], v[160:163], v[176:179], v[116:119]
	v_mfma_f32_16x16x32_bf16 v[108:111], v[168:171], v[176:179], v[108:111]
	v_mfma_f32_16x16x32_bf16 v[100:103], v[160:163], v[192:195], v[100:103]
	v_mfma_f32_16x16x32_bf16 v[96:99], v[168:171], v[192:195], v[96:99]
	v_mfma_f32_16x16x32_bf16 v[84:87], v[160:163], v[200:203], v[84:87]
	v_mfma_f32_16x16x32_bf16 v[76:79], v[168:171], v[200:203], v[76:79]
	v_mfma_f32_16x16x32_bf16 v[68:71], v[160:163], v[208:211], v[68:71]
	v_mfma_f32_16x16x32_bf16 v[64:67], v[168:171], v[208:211], v[64:67]
	v_mfma_f32_16x16x32_bf16 v[116:119], v[164:167], v[188:191], v[116:119]
	v_mfma_f32_16x16x32_bf16 v[108:111], v[172:175], v[188:191], v[108:111]
	v_mfma_f32_16x16x32_bf16 v[100:103], v[164:167], v[196:199], v[100:103]
	v_mfma_f32_16x16x32_bf16 v[96:99], v[172:175], v[196:199], v[96:99]
	v_mfma_f32_16x16x32_bf16 v[84:87], v[164:167], v[204:207], v[84:87]
	v_mfma_f32_16x16x32_bf16 v[76:79], v[172:175], v[204:207], v[76:79]
	v_mfma_f32_16x16x32_bf16 v[68:71], v[164:167], v[212:215], v[68:71]
	v_mfma_f32_16x16x32_bf16 v[64:67], v[172:175], v[212:215], v[64:67]
	s_setprio 0
	s_barrier
	s_add_i32 s8, s75, s24
	s_mov_b32 m0, s8
	ds_read_b128 v[176:179], v187 offset:16384
	ds_read_b128 v[188:191], v187 offset:17408
	ds_read_b128 v[192:195], v187 offset:18432
	ds_read_b128 v[196:199], v187 offset:19456
	ds_read_b128 v[200:203], v187 offset:20480
	ds_read_b128 v[204:207], v187 offset:21504
	ds_read_b128 v[208:211], v187 offset:22528
	ds_read_b128 v[212:215], v187 offset:23552
	global_load_lds_dwordx4 v132, s[68:69]
	s_add_i32 m0, s8, 0x2000
	s_add_u32 s8, s68, 0x80000
	s_addc_u32 s9, s69, 0
	s_add_i32 s14, s76, s24
	global_load_lds_dwordx4 v128, s[68:69]
	s_mov_b32 m0, s14
	s_nop 0
	global_load_lds_dwordx4 v132, s[8:9]
	s_add_i32 m0, s14, 0x2000
	s_nop 0
	global_load_lds_dwordx4 v128, s[8:9]
	s_mov_b32 m0, s44
	s_nop 0
	global_load_lds_dwordx4 v134, s[70:71]
	s_mov_b32 m0, s45
	s_nop 0
	global_load_lds_dwordx4 v130, s[70:71]
	s_waitcnt vmcnt(8)
	s_waitcnt lgkmcnt(0)
	s_barrier
	s_setprio 1
	v_mfma_f32_16x16x32_bf16 v[60:63], v[144:147], v[176:179], v[60:63]
	v_mfma_f32_16x16x32_bf16 v[56:59], v[152:155], v[176:179], v[56:59]
	v_mfma_f32_16x16x32_bf16 v[48:51], v[144:147], v[192:195], v[48:51]
	v_mfma_f32_16x16x32_bf16 v[40:43], v[152:155], v[192:195], v[40:43]
	v_mfma_f32_16x16x32_bf16 v[28:31], v[144:147], v[200:203], v[28:31]
	v_mfma_f32_16x16x32_bf16 v[24:27], v[152:155], v[200:203], v[24:27]
	v_mfma_f32_16x16x32_bf16 v[16:19], v[144:147], v[208:211], v[16:19]
	v_mfma_f32_16x16x32_bf16 v[8:11], v[152:155], v[208:211], v[8:11]
	v_mfma_f32_16x16x32_bf16 v[60:63], v[148:151], v[188:191], v[60:63]
	v_mfma_f32_16x16x32_bf16 v[56:59], v[156:159], v[188:191], v[56:59]
	v_mfma_f32_16x16x32_bf16 v[48:51], v[148:151], v[196:199], v[48:51]
	v_mfma_f32_16x16x32_bf16 v[40:43], v[156:159], v[196:199], v[40:43]
	v_mfma_f32_16x16x32_bf16 v[28:31], v[148:151], v[204:207], v[28:31]
	v_mfma_f32_16x16x32_bf16 v[24:27], v[156:159], v[204:207], v[24:27]
	v_mfma_f32_16x16x32_bf16 v[16:19], v[148:151], v[212:215], v[16:19]
	v_mfma_f32_16x16x32_bf16 v[8:11], v[156:159], v[212:215], v[8:11]
	v_mfma_f32_16x16x32_bf16 v[52:55], v[160:163], v[176:179], v[52:55]
	v_mfma_f32_16x16x32_bf16 v[44:47], v[168:171], v[176:179], v[44:47]
	v_mfma_f32_16x16x32_bf16 v[36:39], v[160:163], v[192:195], v[36:39]
	v_mfma_f32_16x16x32_bf16 v[32:35], v[168:171], v[192:195], v[32:35]
	v_mfma_f32_16x16x32_bf16 v[20:23], v[160:163], v[200:203], v[20:23]
	v_mfma_f32_16x16x32_bf16 v[12:15], v[168:171], v[200:203], v[12:15]
	v_mfma_f32_16x16x32_bf16 v[4:7], v[160:163], v[208:211], v[4:7]
	v_mfma_f32_16x16x32_bf16 v[0:3], v[168:171], v[208:211], v[0:3]
	v_mfma_f32_16x16x32_bf16 v[52:55], v[164:167], v[188:191], v[52:55]
	v_mfma_f32_16x16x32_bf16 v[44:47], v[172:175], v[188:191], v[44:47]
	v_mfma_f32_16x16x32_bf16 v[36:39], v[164:167], v[196:199], v[36:39]
	v_mfma_f32_16x16x32_bf16 v[32:35], v[172:175], v[196:199], v[32:35]
	v_mfma_f32_16x16x32_bf16 v[20:23], v[164:167], v[204:207], v[20:23]
	v_mfma_f32_16x16x32_bf16 v[12:15], v[172:175], v[204:207], v[12:15]
	v_mfma_f32_16x16x32_bf16 v[4:7], v[164:167], v[212:215], v[4:7]
	v_mfma_f32_16x16x32_bf16 v[0:3], v[172:175], v[212:215], v[0:3]
	s_setprio 0
	s_barrier
; #define PG8_STAGE(bufoff, gbase, voff) do { _Pragma("unroll") for (int _i = 0; _i < 2; ++_i) \
;         __builtin_amdgcn_global_load_lds((const unsigned*)((const char*)(gbase) + (voff)[_i]), (LAS unsigned*)(lds + (bufoff) + ldsw + _i * 8192), 16, 0, 0); } while (0)
; #define PG8_LDA(dst, b, h) do { _Pragma("unroll") for (int m = 0; m < 4; ++m) _Pragma("unroll") for (int k = 0; k < 2; ++k) dst[m][k] = *(const LAS bf16x8*)(lds + PG8_SA(b, h) + aoff + m * 2048 + k * 1024); } while (0)
; #define PG8_LDB(dst, b, h) do { _Pragma("unroll") for (int n = 0; n < 2; ++n) _Pragma("unroll") for (int k = 0; k < 2; ++k) dst[n][k] = *(const LAS bf16x8*)(lds + PG8_SB(b, h) + boff + n * 2048 + k * 1024); } while (0)
; #define PG8_MMA(ai, bj, At, Bt) do { __builtin_amdgcn_s_setprio(1); _Pragma("unroll") for (int m = 0; m < 4; ++m) _Pragma("unroll") for (int n = 0; n < 2; ++n) _Pragma("unroll") for (int k = 0; k < 2; ++k) \
;         acc[ai][bj][m][n] = __builtin_amdgcn_mfma_f32_16x16x32_bf16(Bt[n][k], At[m][k], acc[ai][bj][m][n], 0, 0, 0); __builtin_amdgcn_s_setprio(0); } while (0)
; #define PG8_WAIT_V(n) asm volatile("s_waitcnt vmcnt(" #n ")" ::: "memory")
; #define PG8_WAIT_L(n) asm volatile("s_waitcnt lgkmcnt(" #n ")" ::: "memory")
; #define PG8_BAR __builtin_amdgcn_s_barrier()
; #define PG8_SCHED __builtin_amdgcn_sched_barrier(0)
; template <int K, int LDA, int LDB, class Epi, class Sched>
; __device__ __forceinline__ void gemm_phase(LAS unsigned char* lds, const Gemm g, const Sched& S, const Epi& E, int wv) {
;     ...
;             PG8_LDB(B0, 1, 0); PG8_LDB(B1, 1, 1); PG8_SCHED; PG8_LDA(At, 1, 0); PG8_STAGE(PG8_SA(0, 1), a2 + hstepA, voffA);
;             PG8_WAIT_V(8); PG8_WAIT_L(0); PG8_BAR; PG8_MMA(0, 0, At, B0); PG8_MMA(0, 1, At, B1); PG8_BAR; PG8_SCHED;
;             PG8_LDA(At, 1, 1); PG8_STAGE(PG8_SB(1, 0), b3, voffB); PG8_STAGE(PG8_SB(1, 1), b3 + hstepB, voffB); PG8_STAGE(PG8_SA(1, 0), a3, voffA);
;             PG8_WAIT_V(8); PG8_WAIT_L(0); PG8_BAR; PG8_MMA(1, 0, At, B0); PG8_MMA(1, 1, At, B1); PG8_BAR; PG8_SCHED;
;         }
;         if (wr == 0) PG8_BAR;
	s_add_i32 s14, 0, 0x18000
	v_add_u32_e32 v140, s14, v183
	s_add_i32 s15, 0, 0x1c000
	ds_read_b128 v[144:147], v140
	ds_read_b128 v[148:151], v140 offset:1024
	ds_read_b128 v[152:155], v140 offset:2048
	ds_read_b128 v[156:159], v140 offset:3072
	v_add_u32_e32 v140, s15, v183
	ds_read_b128 v[160:163], v140
	ds_read_b128 v[164:167], v140 offset:1024
	ds_read_b128 v[168:171], v140 offset:2048
	ds_read_b128 v[172:175], v140 offset:3072
	s_add_u32 s8, s70, 0x80000
	s_addc_u32 s9, s71, 0
	s_mov_b32 m0, s55
	ds_read_b128 v[176:179], v187 offset:32768
	ds_read_b128 v[188:191], v187 offset:33792
	ds_read_b128 v[192:195], v187 offset:34816
	ds_read_b128 v[196:199], v187 offset:35840
	ds_read_b128 v[200:203], v187 offset:36864
	ds_read_b128 v[204:207], v187 offset:37888
	ds_read_b128 v[208:211], v187 offset:38912
	ds_read_b128 v[212:215], v187 offset:39936
	global_load_lds_dwordx4 v134, s[8:9]
	s_mov_b32 m0, s65
	s_nop 0
	global_load_lds_dwordx4 v130, s[8:9]
	s_waitcnt vmcnt(8)
	s_waitcnt lgkmcnt(0)
	s_barrier
	s_setprio 1
	v_mfma_f32_16x16x32_bf16 v[124:127], v[144:147], v[176:179], v[124:127]
	v_mfma_f32_16x16x32_bf16 v[120:123], v[152:155], v[176:179], v[120:123]
	v_mfma_f32_16x16x32_bf16 v[112:115], v[144:147], v[192:195], v[112:115]
	v_mfma_f32_16x16x32_bf16 v[104:107], v[152:155], v[192:195], v[104:107]
	v_mfma_f32_16x16x32_bf16 v[92:95], v[144:147], v[200:203], v[92:95]
	v_mfma_f32_16x16x32_bf16 v[88:91], v[152:155], v[200:203], v[88:91]
	v_mfma_f32_16x16x32_bf16 v[80:83], v[144:147], v[208:211], v[80:83]
	v_mfma_f32_16x16x32_bf16 v[72:75], v[152:155], v[208:211], v[72:75]
	v_mfma_f32_16x16x32_bf16 v[124:127], v[148:151], v[188:191], v[124:127]
	v_mfma_f32_16x16x32_bf16 v[120:123], v[156:159], v[188:191], v[120:123]
	v_mfma_f32_16x16x32_bf16 v[112:115], v[148:151], v[196:199], v[112:115]
	v_mfma_f32_16x16x32_bf16 v[104:107], v[156:159], v[196:199], v[104:107]
	v_mfma_f32_16x16x32_bf16 v[92:95], v[148:151], v[204:207], v[92:95]
	v_mfma_f32_16x16x32_bf16 v[88:91], v[156:159], v[204:207], v[88:91]
	v_mfma_f32_16x16x32_bf16 v[80:83], v[148:151], v[212:215], v[80:83]
	v_mfma_f32_16x16x32_bf16 v[72:75], v[156:159], v[212:215], v[72:75]
	v_mfma_f32_16x16x32_bf16 v[116:119], v[160:163], v[176:179], v[116:119]
	v_mfma_f32_16x16x32_bf16 v[108:111], v[168:171], v[176:179], v[108:111]
	v_mfma_f32_16x16x32_bf16 v[100:103], v[160:163], v[192:195], v[100:103]
	v_mfma_f32_16x16x32_bf16 v[96:99], v[168:171], v[192:195], v[96:99]
	v_mfma_f32_16x16x32_bf16 v[84:87], v[160:163], v[200:203], v[84:87]
	v_mfma_f32_16x16x32_bf16 v[76:79], v[168:171], v[200:203], v[76:79]
	v_mfma_f32_16x16x32_bf16 v[68:71], v[160:163], v[208:211], v[68:71]
	v_mfma_f32_16x16x32_bf16 v[64:67], v[168:171], v[208:211], v[64:67]
	v_mfma_f32_16x16x32_bf16 v[116:119], v[164:167], v[188:191], v[116:119]
	v_mfma_f32_16x16x32_bf16 v[108:111], v[172:175], v[188:191], v[108:111]
	v_mfma_f32_16x16x32_bf16 v[100:103], v[164:167], v[196:199], v[100:103]
	v_mfma_f32_16x16x32_bf16 v[96:99], v[172:175], v[196:199], v[96:99]
	v_mfma_f32_16x16x32_bf16 v[84:87], v[164:167], v[204:207], v[84:87]
	v_mfma_f32_16x16x32_bf16 v[76:79], v[172:175], v[204:207], v[76:79]
	v_mfma_f32_16x16x32_bf16 v[68:71], v[164:167], v[212:215], v[68:71]
	v_mfma_f32_16x16x32_bf16 v[64:67], v[172:175], v[212:215], v[64:67]
	s_setprio 0
	s_barrier
	s_add_i32 s8, s14, s24
	s_mov_b32 m0, s8
	ds_read_b128 v[176:179], v187 offset:49152
	ds_read_b128 v[188:191], v187 offset:50176
	ds_read_b128 v[192:195], v187 offset:51200
	ds_read_b128 v[196:199], v187 offset:52224
	ds_read_b128 v[200:203], v187 offset:53248
	ds_read_b128 v[204:207], v187 offset:54272
	ds_read_b128 v[208:211], v187 offset:55296
	ds_read_b128 v[212:215], v187 offset:56320
	s_add_u32 s98, s68, s52
	s_addc_u32 s99, s69, s53
	global_load_lds_dwordx4 v132, s[98:99]
	s_add_i32 m0, s8, 0x2000
	s_add_u32 s8, s68, 0x80080
	s_addc_u32 s9, s69, 0
	s_add_i32 s14, s15, s24
	global_load_lds_dwordx4 v128, s[98:99]
	s_mov_b32 m0, s14
	s_nop 0
	global_load_lds_dwordx4 v132, s[8:9]
	s_add_i32 m0, s14, 0x2000
	s_nop 0
	global_load_lds_dwordx4 v128, s[8:9]
	s_mov_b32 m0, s73
	s_nop 0
	s_add_u32 s100, s70, s52
	s_addc_u32 s101, s71, s53
	global_load_lds_dwordx4 v134, s[100:101]
	s_mov_b32 m0, s74
	s_nop 0
	global_load_lds_dwordx4 v130, s[100:101]
	s_waitcnt vmcnt(8)
	s_waitcnt lgkmcnt(0)
	s_barrier
	s_setprio 1
	v_mfma_f32_16x16x32_bf16 v[60:63], v[144:147], v[176:179], v[60:63]
	v_mfma_f32_16x16x32_bf16 v[56:59], v[152:155], v[176:179], v[56:59]
	v_mfma_f32_16x16x32_bf16 v[48:51], v[144:147], v[192:195], v[48:51]
	v_mfma_f32_16x16x32_bf16 v[40:43], v[152:155], v[192:195], v[40:43]
	v_mfma_f32_16x16x32_bf16 v[28:31], v[144:147], v[200:203], v[28:31]
	v_mfma_f32_16x16x32_bf16 v[24:27], v[152:155], v[200:203], v[24:27]
	v_mfma_f32_16x16x32_bf16 v[16:19], v[144:147], v[208:211], v[16:19]
	v_mfma_f32_16x16x32_bf16 v[8:11], v[152:155], v[208:211], v[8:11]
	v_mfma_f32_16x16x32_bf16 v[60:63], v[148:151], v[188:191], v[60:63]
	v_mfma_f32_16x16x32_bf16 v[56:59], v[156:159], v[188:191], v[56:59]
	v_mfma_f32_16x16x32_bf16 v[48:51], v[148:151], v[196:199], v[48:51]
	v_mfma_f32_16x16x32_bf16 v[40:43], v[156:159], v[196:199], v[40:43]
	v_mfma_f32_16x16x32_bf16 v[28:31], v[148:151], v[204:207], v[28:31]
	v_mfma_f32_16x16x32_bf16 v[24:27], v[156:159], v[204:207], v[24:27]
	v_mfma_f32_16x16x32_bf16 v[16:19], v[148:151], v[212:215], v[16:19]
	v_mfma_f32_16x16x32_bf16 v[8:11], v[156:159], v[212:215], v[8:11]
	v_mfma_f32_16x16x32_bf16 v[52:55], v[160:163], v[176:179], v[52:55]
	v_mfma_f32_16x16x32_bf16 v[44:47], v[168:171], v[176:179], v[44:47]
	v_mfma_f32_16x16x32_bf16 v[36:39], v[160:163], v[192:195], v[36:39]
	v_mfma_f32_16x16x32_bf16 v[32:35], v[168:171], v[192:195], v[32:35]
	v_mfma_f32_16x16x32_bf16 v[20:23], v[160:163], v[200:203], v[20:23]
	v_mfma_f32_16x16x32_bf16 v[12:15], v[168:171], v[200:203], v[12:15]
	v_mfma_f32_16x16x32_bf16 v[4:7], v[160:163], v[208:211], v[4:7]
	v_mfma_f32_16x16x32_bf16 v[0:3], v[168:171], v[208:211], v[0:3]
	v_mfma_f32_16x16x32_bf16 v[52:55], v[164:167], v[188:191], v[52:55]
	v_mfma_f32_16x16x32_bf16 v[44:47], v[172:175], v[188:191], v[44:47]
	v_mfma_f32_16x16x32_bf16 v[36:39], v[164:167], v[196:199], v[36:39]
	v_mfma_f32_16x16x32_bf16 v[32:35], v[172:175], v[196:199], v[32:35]
	v_mfma_f32_16x16x32_bf16 v[20:23], v[164:167], v[204:207], v[20:23]
	v_mfma_f32_16x16x32_bf16 v[12:15], v[172:175], v[204:207], v[12:15]
	v_mfma_f32_16x16x32_bf16 v[4:7], v[164:167], v[212:215], v[4:7]
	v_mfma_f32_16x16x32_bf16 v[0:3], v[172:175], v[212:215], v[0:3]
	s_setprio 0
	s_barrier
	s_add_i32 s82, s82, 2
	s_add_u32 s66, s66, 0x100
	s_addc_u32 s67, s67, 0
	s_add_u32 s80, s80, 0x100
	s_addc_u32 s81, s81, 0
	s_cmp_gt_u32 s82, 29
	s_cbranch_scc0 .LBB0_700
	s_and_b64 vcc, exec, s[28:29]
	s_cbranch_vccz .LBB0_703
	s_barrier

; #define PG8_STAGE(bufoff, gbase, voff) do { _Pragma("unroll") for (int _i = 0; _i < 2; ++_i) \
;         __builtin_amdgcn_global_load_lds((const unsigned*)((const char*)(gbase) + (voff)[_i]), (LAS unsigned*)(lds + (bufoff) + ldsw + _i * 8192), 16, 0, 0); } while (0)
; #define PG8_LDA(dst, b, h) do { _Pragma("unroll") for (int m = 0; m < 4; ++m) _Pragma("unroll") for (int k = 0; k < 2; ++k) dst[m][k] = *(const LAS bf16x8*)(lds + PG8_SA(b, h) + aoff + m * 2048 + k * 1024); } while (0)
; #define PG8_LDB(dst, b, h) do { _Pragma("unroll") for (int n = 0; n < 2; ++n) _Pragma("unroll") for (int k = 0; k < 2; ++k) dst[n][k] = *(const LAS bf16x8*)(lds + PG8_SB(b, h) + boff + n * 2048 + k * 1024); } while (0)
; #define PG8_MMA(ai, bj, At, Bt) do { __builtin_amdgcn_s_setprio(1); _Pragma("unroll") for (int m = 0; m < 4; ++m) _Pragma("unroll") for (int n = 0; n < 2; ++n) _Pragma("unroll") for (int k = 0; k < 2; ++k) \
;         acc[ai][bj][m][n] = __builtin_amdgcn_mfma_f32_16x16x32_bf16(Bt[n][k], At[m][k], acc[ai][bj][m][n], 0, 0, 0); __builtin_amdgcn_s_setprio(0); } while (0)
; #define PG8_WAIT_V(n) asm volatile("s_waitcnt vmcnt(" #n ")" ::: "memory")
; template <int K, int LDA, int LDB, class Epi, class Sched>
; __device__ __forceinline__ void gemm_phase(LAS unsigned char* lds, const Gemm g, const Sched& S, const Epi& E, int wv) {
;     ...
;             PG8_LDB(B0, 0, 0); PG8_LDB(B1, 0, 1); PG8_SCHED; PG8_LDA(At, 0, 0); PG8_STAGE(PG8_SA(1, 1), a1 + hstepA, voffA);
;             PG8_WAIT_V(8); PG8_WAIT_L(0); PG8_BAR; PG8_MMA(0, 0, At, B0); PG8_MMA(0, 1, At, B1); PG8_BAR; PG8_SCHED;
;             PG8_LDA(At, 0, 1); PG8_STAGE(PG8_SB(0, 0), b2, voffB); PG8_STAGE(PG8_SB(0, 1), b2 + hstepB, voffB); PG8_STAGE(PG8_SA(0, 0), a2, voffA);
;             PG8_WAIT_V(8); PG8_WAIT_L(0); PG8_BAR; PG8_MMA(1, 0, At, B0); PG8_MMA(1, 1, At, B1); PG8_BAR; PG8_SCHED;
;             PG8_LDB(B0, 1, 0); PG8_LDB(B1, 1, 1); PG8_SCHED; PG8_LDA(At, 1, 0); PG8_STAGE(PG8_SA(0, 1), a2 + hstepA, voffA);
;             PG8_WAIT_V(8); PG8_WAIT_L(0); PG8_BAR; PG8_MMA(0, 0, At, B0); PG8_MMA(0, 1, At, B1); PG8_BAR; PG8_SCHED;
;             PG8_LDA(At, 1, 1); PG8_STAGE(PG8_SB(1, 0), b3, voffB); PG8_STAGE(PG8_SB(1, 1), b3 + hstepB, voffB); PG8_STAGE(PG8_SA(1, 0), a3, voffA);
;             PG8_WAIT_V(8); PG8_WAIT_L(0); PG8_BAR; PG8_MMA(1, 0, At, B0); PG8_MMA(1, 1, At, B1); PG8_BAR; PG8_SCHED;
.LBB0_838:
	s_waitcnt lgkmcnt(0)
	ds_read_b128 v[152:155], v163
	ds_read_b128 v[156:159], v163 offset:1024
	ds_read_b128 v[166:169], v163 offset:2048
	ds_read_b128 v[170:173], v163 offset:3072
	ds_read_b128 v[174:177], v164
	ds_read_b128 v[178:181], v164 offset:1024
	ds_read_b128 v[182:185], v164 offset:2048
	ds_read_b128 v[186:189], v164 offset:3072
	s_add_u32 s9, s92, 0xfff80080
	s_addc_u32 s34, s93, -1
	s_cmp_eq_u32 s8, 28
	s_cselect_b32 s97, s45, s34
	s_cselect_b32 s96, s62, s9
	s_cselect_b32 s95, s81, vcc_hi
	s_cselect_b32 s94, s83, vcc_lo
	s_add_i32 m0, s71, 0xc000
	ds_read_b128 v[190:193], v165
	ds_read_b128 v[194:197], v165 offset:1024
	ds_read_b128 v[198:201], v165 offset:2048
	ds_read_b128 v[202:205], v165 offset:3072
	ds_read_b128 v[206:209], v165 offset:4096
	ds_read_b128 v[210:213], v165 offset:5120
	ds_read_b128 v[214:217], v165 offset:6144
	ds_read_b128 v[218:221], v165 offset:7168
	global_load_lds_dwordx4 v144, s[92:93]
	s_add_i32 m0, s71, 0xe000
	s_nop 0
	global_load_lds_dwordx4 v146, s[92:93]
	s_waitcnt vmcnt(8)
	s_waitcnt lgkmcnt(0)
	s_barrier
	s_setprio 1
	v_mfma_f32_16x16x32_bf16 v[64:67], v[152:155], v[190:193], v[64:67]
	v_mfma_f32_16x16x32_bf16 v[60:63], v[166:169], v[190:193], v[60:63]
	v_mfma_f32_16x16x32_bf16 v[56:59], v[152:155], v[198:201], v[56:59]
	v_mfma_f32_16x16x32_bf16 v[48:51], v[166:169], v[198:201], v[48:51]
	v_mfma_f32_16x16x32_bf16 v[44:47], v[152:155], v[206:209], v[44:47]
	v_mfma_f32_16x16x32_bf16 v[40:43], v[166:169], v[206:209], v[40:43]
	v_mfma_f32_16x16x32_bf16 v[36:39], v[152:155], v[214:217], v[36:39]
	v_mfma_f32_16x16x32_bf16 v[32:35], v[166:169], v[214:217], v[32:35]
	v_mfma_f32_16x16x32_bf16 v[64:67], v[156:159], v[194:197], v[64:67]
	v_mfma_f32_16x16x32_bf16 v[60:63], v[170:173], v[194:197], v[60:63]
	v_mfma_f32_16x16x32_bf16 v[56:59], v[156:159], v[202:205], v[56:59]
	v_mfma_f32_16x16x32_bf16 v[48:51], v[170:173], v[202:205], v[48:51]
	v_mfma_f32_16x16x32_bf16 v[44:47], v[156:159], v[210:213], v[44:47]
	v_mfma_f32_16x16x32_bf16 v[40:43], v[170:173], v[210:213], v[40:43]
	v_mfma_f32_16x16x32_bf16 v[36:39], v[156:159], v[218:221], v[36:39]
	v_mfma_f32_16x16x32_bf16 v[32:35], v[170:173], v[218:221], v[32:35]
	v_mfma_f32_16x16x32_bf16 v[124:127], v[174:177], v[190:193], v[124:127]
	v_mfma_f32_16x16x32_bf16 v[120:123], v[182:185], v[190:193], v[120:123]
	v_mfma_f32_16x16x32_bf16 v[116:119], v[174:177], v[198:201], v[116:119]
	v_mfma_f32_16x16x32_bf16 v[112:115], v[182:185], v[198:201], v[112:115]
	v_mfma_f32_16x16x32_bf16 v[108:111], v[174:177], v[206:209], v[108:111]
	v_mfma_f32_16x16x32_bf16 v[104:107], v[182:185], v[206:209], v[104:107]
	v_mfma_f32_16x16x32_bf16 v[100:103], v[174:177], v[214:217], v[100:103]
	v_mfma_f32_16x16x32_bf16 v[96:99], v[182:185], v[214:217], v[96:99]
	v_mfma_f32_16x16x32_bf16 v[124:127], v[178:181], v[194:197], v[124:127]
	v_mfma_f32_16x16x32_bf16 v[120:123], v[186:189], v[194:197], v[120:123]
	v_mfma_f32_16x16x32_bf16 v[116:119], v[178:181], v[202:205], v[116:119]
	v_mfma_f32_16x16x32_bf16 v[112:115], v[186:189], v[202:205], v[112:115]
	v_mfma_f32_16x16x32_bf16 v[108:111], v[178:181], v[210:213], v[108:111]
	v_mfma_f32_16x16x32_bf16 v[104:107], v[186:189], v[210:213], v[104:107]
	v_mfma_f32_16x16x32_bf16 v[100:103], v[178:181], v[218:221], v[100:103]
	v_mfma_f32_16x16x32_bf16 v[96:99], v[186:189], v[218:221], v[96:99]
	s_setprio 0
	s_barrier
	s_add_i32 s9, s91, s24
	s_mov_b32 m0, s9
	ds_read_b128 v[190:193], v165 offset:16384
	ds_read_b128 v[194:197], v165 offset:17408
	ds_read_b128 v[198:201], v165 offset:18432
	ds_read_b128 v[202:205], v165 offset:19456
	ds_read_b128 v[206:209], v165 offset:20480
	ds_read_b128 v[210:213], v165 offset:21504
	ds_read_b128 v[214:217], v165 offset:22528
	ds_read_b128 v[218:221], v165 offset:23552
	global_load_lds_dwordx4 v130, s[94:95]
	s_add_i32 m0, s9, 0x2000
	s_add_u32 s34, s94, 0x80000
	s_addc_u32 s35, s95, 0
	s_add_i32 s9, s42, s24
	global_load_lds_dwordx4 v134, s[94:95]
	s_mov_b32 m0, s9
	s_nop 0
	global_load_lds_dwordx4 v130, s[34:35]
	s_add_i32 m0, s9, 0x2000
	s_nop 0
	global_load_lds_dwordx4 v134, s[34:35]
	s_mov_b32 m0, s71
	s_nop 0
	global_load_lds_dwordx4 v128, s[96:97]
	s_mov_b32 m0, s73
	s_nop 0
	global_load_lds_dwordx4 v132, s[96:97]
	s_waitcnt vmcnt(8)
	s_waitcnt lgkmcnt(0)
	s_barrier
	s_setprio 1
	v_mfma_f32_16x16x32_bf16 v[28:31], v[152:155], v[190:193], v[28:31]
	v_mfma_f32_16x16x32_bf16 v[24:27], v[166:169], v[190:193], v[24:27]
	v_mfma_f32_16x16x32_bf16 v[20:23], v[152:155], v[198:201], v[20:23]
	v_mfma_f32_16x16x32_bf16 v[16:19], v[166:169], v[198:201], v[16:19]
	v_mfma_f32_16x16x32_bf16 v[12:15], v[152:155], v[206:209], v[12:15]
	v_mfma_f32_16x16x32_bf16 v[8:11], v[166:169], v[206:209], v[8:11]
	v_mfma_f32_16x16x32_bf16 v[4:7], v[152:155], v[214:217], v[4:7]
	v_mfma_f32_16x16x32_bf16 v[0:3], v[166:169], v[214:217], v[0:3]
	v_mfma_f32_16x16x32_bf16 v[28:31], v[156:159], v[194:197], v[28:31]
	v_mfma_f32_16x16x32_bf16 v[24:27], v[170:173], v[194:197], v[24:27]
	v_mfma_f32_16x16x32_bf16 v[20:23], v[156:159], v[202:205], v[20:23]
	v_mfma_f32_16x16x32_bf16 v[16:19], v[170:173], v[202:205], v[16:19]
	v_mfma_f32_16x16x32_bf16 v[12:15], v[156:159], v[210:213], v[12:15]
	v_mfma_f32_16x16x32_bf16 v[8:11], v[170:173], v[210:213], v[8:11]
	v_mfma_f32_16x16x32_bf16 v[4:7], v[156:159], v[218:221], v[4:7]
	v_mfma_f32_16x16x32_bf16 v[0:3], v[170:173], v[218:221], v[0:3]
	v_mfma_f32_16x16x32_bf16 v[92:95], v[174:177], v[190:193], v[92:95]
	v_mfma_f32_16x16x32_bf16 v[88:91], v[182:185], v[190:193], v[88:91]
	v_mfma_f32_16x16x32_bf16 v[84:87], v[174:177], v[198:201], v[84:87]
	v_mfma_f32_16x16x32_bf16 v[80:83], v[182:185], v[198:201], v[80:83]
	v_mfma_f32_16x16x32_bf16 v[76:79], v[174:177], v[206:209], v[76:79]
	v_mfma_f32_16x16x32_bf16 v[72:75], v[182:185], v[206:209], v[72:75]
	v_mfma_f32_16x16x32_bf16 v[68:71], v[174:177], v[214:217], v[68:71]
	v_mfma_f32_16x16x32_bf16 v[52:55], v[182:185], v[214:217], v[52:55]
	v_mfma_f32_16x16x32_bf16 v[92:95], v[178:181], v[194:197], v[92:95]
	v_mfma_f32_16x16x32_bf16 v[88:91], v[186:189], v[194:197], v[88:91]
	v_mfma_f32_16x16x32_bf16 v[84:87], v[178:181], v[202:205], v[84:87]
	v_mfma_f32_16x16x32_bf16 v[80:83], v[186:189], v[202:205], v[80:83]
	v_mfma_f32_16x16x32_bf16 v[76:79], v[178:181], v[210:213], v[76:79]
	v_mfma_f32_16x16x32_bf16 v[72:75], v[186:189], v[210:213], v[72:75]
	v_mfma_f32_16x16x32_bf16 v[68:71], v[178:181], v[218:221], v[68:71]
	v_mfma_f32_16x16x32_bf16 v[52:55], v[186:189], v[218:221], v[52:55]
	s_setprio 0
	s_barrier
; #define PG8_STAGE(bufoff, gbase, voff) do { _Pragma("unroll") for (int _i = 0; _i < 2; ++_i) \
;         __builtin_amdgcn_global_load_lds((const unsigned*)((const char*)(gbase) + (voff)[_i]), (LAS unsigned*)(lds + (bufoff) + ldsw + _i * 8192), 16, 0, 0); } while (0)
; #define PG8_LDA(dst, b, h) do { _Pragma("unroll") for (int m = 0; m < 4; ++m) _Pragma("unroll") for (int k = 0; k < 2; ++k) dst[m][k] = *(const LAS bf16x8*)(lds + PG8_SA(b, h) + aoff + m * 2048 + k * 1024); } while (0)
; #define PG8_LDB(dst, b, h) do { _Pragma("unroll") for (int n = 0; n < 2; ++n) _Pragma("unroll") for (int k = 0; k < 2; ++k) dst[n][k] = *(const LAS bf16x8*)(lds + PG8_SB(b, h) + boff + n * 2048 + k * 1024); } while (0)
; #define PG8_MMA(ai, bj, At, Bt) do { __builtin_amdgcn_s_setprio(1); _Pragma("unroll") for (int m = 0; m < 4; ++m) _Pragma("unroll") for (int n = 0; n < 2; ++n) _Pragma("unroll") for (int k = 0; k < 2; ++k) \
;         acc[ai][bj][m][n] = __builtin_amdgcn_mfma_f32_16x16x32_bf16(Bt[n][k], At[m][k], acc[ai][bj][m][n], 0, 0, 0); __builtin_amdgcn_s_setprio(0); } while (0)
; #define PG8_WAIT_V(n) asm volatile("s_waitcnt vmcnt(" #n ")" ::: "memory")
; #define PG8_WAIT_L(n) asm volatile("s_waitcnt lgkmcnt(" #n ")" ::: "memory")
; #define PG8_BAR __builtin_amdgcn_s_barrier()
; #define PG8_SCHED __builtin_amdgcn_sched_barrier(0)
; template <int K, int LDA, int LDB, class Epi, class Sched>
; __device__ __forceinline__ void gemm_phase(LAS unsigned char* lds, const Gemm g, const Sched& S, const Epi& E, int wv) {
;     ...
;             PG8_LDB(B0, 1, 0); PG8_LDB(B1, 1, 1); PG8_SCHED; PG8_LDA(At, 1, 0); PG8_STAGE(PG8_SA(0, 1), a2 + hstepA, voffA);
;             PG8_WAIT_V(8); PG8_WAIT_L(0); PG8_BAR; PG8_MMA(0, 0, At, B0); PG8_MMA(0, 1, At, B1); PG8_BAR; PG8_SCHED;
;             PG8_LDA(At, 1, 1); PG8_STAGE(PG8_SB(1, 0), b3, voffB); PG8_STAGE(PG8_SB(1, 1), b3 + hstepB, voffB); PG8_STAGE(PG8_SA(1, 0), a3, voffA);
;             PG8_WAIT_V(8); PG8_WAIT_L(0); PG8_BAR; PG8_MMA(1, 0, At, B0); PG8_MMA(1, 1, At, B1); PG8_BAR; PG8_SCHED;
;         }
;         if (wr == 0) PG8_BAR;
	s_add_i32 s9, 0, 0x18000
	v_add_u32_e32 v136, s9, v161
	s_add_i32 s10, 0, 0x1c000
	ds_read_b128 v[152:155], v136
	ds_read_b128 v[156:159], v136 offset:1024
	ds_read_b128 v[166:169], v136 offset:2048
	ds_read_b128 v[170:173], v136 offset:3072
	v_add_u32_e32 v136, s10, v161
	ds_read_b128 v[174:177], v136
	ds_read_b128 v[178:181], v136 offset:1024
	ds_read_b128 v[182:185], v136 offset:2048
	ds_read_b128 v[186:189], v136 offset:3072
	s_add_u32 s34, s96, 0x80000
	s_addc_u32 s35, s97, 0
	s_mov_b32 m0, s75
	ds_read_b128 v[190:193], v165 offset:32768
	ds_read_b128 v[194:197], v165 offset:33792
	ds_read_b128 v[198:201], v165 offset:34816
	ds_read_b128 v[202:205], v165 offset:35840
	ds_read_b128 v[206:209], v165 offset:36864
	ds_read_b128 v[210:213], v165 offset:37888
	ds_read_b128 v[214:217], v165 offset:38912
	ds_read_b128 v[218:221], v165 offset:39936
	global_load_lds_dwordx4 v128, s[34:35]
	s_mov_b32 m0, s77
	s_nop 0
	global_load_lds_dwordx4 v132, s[34:35]
	s_waitcnt vmcnt(8)
	s_waitcnt lgkmcnt(0)
	s_barrier
	s_setprio 1
	v_mfma_f32_16x16x32_bf16 v[64:67], v[152:155], v[190:193], v[64:67]
	v_mfma_f32_16x16x32_bf16 v[60:63], v[166:169], v[190:193], v[60:63]
	v_mfma_f32_16x16x32_bf16 v[56:59], v[152:155], v[198:201], v[56:59]
	v_mfma_f32_16x16x32_bf16 v[48:51], v[166:169], v[198:201], v[48:51]
	v_mfma_f32_16x16x32_bf16 v[44:47], v[152:155], v[206:209], v[44:47]
	v_mfma_f32_16x16x32_bf16 v[40:43], v[166:169], v[206:209], v[40:43]
	v_mfma_f32_16x16x32_bf16 v[36:39], v[152:155], v[214:217], v[36:39]
	v_mfma_f32_16x16x32_bf16 v[32:35], v[166:169], v[214:217], v[32:35]
	v_mfma_f32_16x16x32_bf16 v[64:67], v[156:159], v[194:197], v[64:67]
	v_mfma_f32_16x16x32_bf16 v[60:63], v[170:173], v[194:197], v[60:63]
	v_mfma_f32_16x16x32_bf16 v[56:59], v[156:159], v[202:205], v[56:59]
	v_mfma_f32_16x16x32_bf16 v[48:51], v[170:173], v[202:205], v[48:51]
	v_mfma_f32_16x16x32_bf16 v[44:47], v[156:159], v[210:213], v[44:47]
	v_mfma_f32_16x16x32_bf16 v[40:43], v[170:173], v[210:213], v[40:43]
	v_mfma_f32_16x16x32_bf16 v[36:39], v[156:159], v[218:221], v[36:39]
	v_mfma_f32_16x16x32_bf16 v[32:35], v[170:173], v[218:221], v[32:35]
	v_mfma_f32_16x16x32_bf16 v[124:127], v[174:177], v[190:193], v[124:127]
	v_mfma_f32_16x16x32_bf16 v[120:123], v[182:185], v[190:193], v[120:123]
	v_mfma_f32_16x16x32_bf16 v[116:119], v[174:177], v[198:201], v[116:119]
	v_mfma_f32_16x16x32_bf16 v[112:115], v[182:185], v[198:201], v[112:115]
	v_mfma_f32_16x16x32_bf16 v[108:111], v[174:177], v[206:209], v[108:111]
	v_mfma_f32_16x16x32_bf16 v[104:107], v[182:185], v[206:209], v[104:107]
	v_mfma_f32_16x16x32_bf16 v[100:103], v[174:177], v[214:217], v[100:103]
	v_mfma_f32_16x16x32_bf16 v[96:99], v[182:185], v[214:217], v[96:99]
	v_mfma_f32_16x16x32_bf16 v[124:127], v[178:181], v[194:197], v[124:127]
	v_mfma_f32_16x16x32_bf16 v[120:123], v[186:189], v[194:197], v[120:123]
	v_mfma_f32_16x16x32_bf16 v[116:119], v[178:181], v[202:205], v[116:119]
	v_mfma_f32_16x16x32_bf16 v[112:115], v[186:189], v[202:205], v[112:115]
	v_mfma_f32_16x16x32_bf16 v[108:111], v[178:181], v[210:213], v[108:111]
	v_mfma_f32_16x16x32_bf16 v[104:107], v[186:189], v[210:213], v[104:107]
	v_mfma_f32_16x16x32_bf16 v[100:103], v[178:181], v[218:221], v[100:103]
	v_mfma_f32_16x16x32_bf16 v[96:99], v[186:189], v[218:221], v[96:99]
	s_setprio 0
	s_barrier
	s_add_i32 s9, s9, s24
	s_mov_b32 m0, s9
	ds_read_b128 v[190:193], v165 offset:49152
	ds_read_b128 v[194:197], v165 offset:50176
	ds_read_b128 v[198:201], v165 offset:51200
	ds_read_b128 v[202:205], v165 offset:52224
	ds_read_b128 v[206:209], v165 offset:53248
	ds_read_b128 v[210:213], v165 offset:54272
	ds_read_b128 v[214:217], v165 offset:55296
	ds_read_b128 v[218:221], v165 offset:56320
	s_add_u32 s98, s94, s64
	s_addc_u32 s99, s95, s65
	global_load_lds_dwordx4 v130, s[98:99]
	s_add_i32 m0, s9, 0x2000
	s_add_u32 s34, s94, 0x80080
	s_addc_u32 s35, s95, 0
	s_add_i32 s9, s10, s24
	global_load_lds_dwordx4 v134, s[98:99]
	s_mov_b32 m0, s9
	s_nop 0
	global_load_lds_dwordx4 v130, s[34:35]
	s_add_i32 m0, s9, 0x2000
	s_nop 0
	global_load_lds_dwordx4 v134, s[34:35]
	s_mov_b32 m0, s79
	s_nop 0
	s_add_u32 s100, s96, s64
	s_addc_u32 s101, s97, s65
	global_load_lds_dwordx4 v128, s[100:101]
	s_mov_b32 m0, s89
	s_nop 0
	global_load_lds_dwordx4 v132, s[100:101]
	s_waitcnt vmcnt(8)
	s_waitcnt lgkmcnt(0)
	s_barrier
	s_setprio 1
	v_mfma_f32_16x16x32_bf16 v[28:31], v[152:155], v[190:193], v[28:31]
	v_mfma_f32_16x16x32_bf16 v[24:27], v[166:169], v[190:193], v[24:27]
	v_mfma_f32_16x16x32_bf16 v[20:23], v[152:155], v[198:201], v[20:23]
	v_mfma_f32_16x16x32_bf16 v[16:19], v[166:169], v[198:201], v[16:19]
	v_mfma_f32_16x16x32_bf16 v[12:15], v[152:155], v[206:209], v[12:15]
	v_mfma_f32_16x16x32_bf16 v[8:11], v[166:169], v[206:209], v[8:11]
	v_mfma_f32_16x16x32_bf16 v[4:7], v[152:155], v[214:217], v[4:7]
	v_mfma_f32_16x16x32_bf16 v[0:3], v[166:169], v[214:217], v[0:3]
	v_mfma_f32_16x16x32_bf16 v[28:31], v[156:159], v[194:197], v[28:31]
	v_mfma_f32_16x16x32_bf16 v[24:27], v[170:173], v[194:197], v[24:27]
	v_mfma_f32_16x16x32_bf16 v[20:23], v[156:159], v[202:205], v[20:23]
	v_mfma_f32_16x16x32_bf16 v[16:19], v[170:173], v[202:205], v[16:19]
	v_mfma_f32_16x16x32_bf16 v[12:15], v[156:159], v[210:213], v[12:15]
	v_mfma_f32_16x16x32_bf16 v[8:11], v[170:173], v[210:213], v[8:11]
	v_mfma_f32_16x16x32_bf16 v[4:7], v[156:159], v[218:221], v[4:7]
	v_mfma_f32_16x16x32_bf16 v[0:3], v[170:173], v[218:221], v[0:3]
	v_mfma_f32_16x16x32_bf16 v[92:95], v[174:177], v[190:193], v[92:95]
	v_mfma_f32_16x16x32_bf16 v[88:91], v[182:185], v[190:193], v[88:91]
	v_mfma_f32_16x16x32_bf16 v[84:87], v[174:177], v[198:201], v[84:87]
	v_mfma_f32_16x16x32_bf16 v[80:83], v[182:185], v[198:201], v[80:83]
	v_mfma_f32_16x16x32_bf16 v[76:79], v[174:177], v[206:209], v[76:79]
	v_mfma_f32_16x16x32_bf16 v[72:75], v[182:185], v[206:209], v[72:75]
	v_mfma_f32_16x16x32_bf16 v[68:71], v[174:177], v[214:217], v[68:71]
	v_mfma_f32_16x16x32_bf16 v[52:55], v[182:185], v[214:217], v[52:55]
	v_mfma_f32_16x16x32_bf16 v[92:95], v[178:181], v[194:197], v[92:95]
	v_mfma_f32_16x16x32_bf16 v[88:91], v[186:189], v[194:197], v[88:91]
	v_mfma_f32_16x16x32_bf16 v[84:87], v[178:181], v[202:205], v[84:87]
	v_mfma_f32_16x16x32_bf16 v[80:83], v[186:189], v[202:205], v[80:83]
	v_mfma_f32_16x16x32_bf16 v[76:79], v[178:181], v[210:213], v[76:79]
	v_mfma_f32_16x16x32_bf16 v[72:75], v[186:189], v[210:213], v[72:75]
	v_mfma_f32_16x16x32_bf16 v[68:71], v[178:181], v[218:221], v[68:71]
	v_mfma_f32_16x16x32_bf16 v[52:55], v[186:189], v[218:221], v[52:55]
	s_setprio 0
	s_barrier
	s_add_i32 s8, s8, 2
	s_add_u32 s92, s92, 0x100
	s_addc_u32 s93, s93, 0
	s_add_u32 vcc_lo, vcc_lo, 0x100
	s_addc_u32 vcc_hi, vcc_hi, 0
	s_cmp_gt_u32 s8, 29
	s_cbranch_scc0 .LBB0_838
	s_and_b64 vcc, exec, s[28:29]
	s_cbranch_vccz .LBB0_841
	s_barrier

; #define PG8_STAGE(bufoff, gbase, voff) do { _Pragma("unroll") for (int _i = 0; _i < 2; ++_i) \
;         __builtin_amdgcn_global_load_lds((const unsigned*)((const char*)(gbase) + (voff)[_i]), (LAS unsigned*)(lds + (bufoff) + ldsw + _i * 8192), 16, 0, 0); } while (0)
; #define PG8_LDA(dst, b, h) do { _Pragma("unroll") for (int m = 0; m < 4; ++m) _Pragma("unroll") for (int k = 0; k < 2; ++k) dst[m][k] = *(const LAS bf16x8*)(lds + PG8_SA(b, h) + aoff + m * 2048 + k * 1024); } while (0)
; #define PG8_LDB(dst, b, h) do { _Pragma("unroll") for (int n = 0; n < 2; ++n) _Pragma("unroll") for (int k = 0; k < 2; ++k) dst[n][k] = *(const LAS bf16x8*)(lds + PG8_SB(b, h) + boff + n * 2048 + k * 1024); } while (0)
; #define PG8_MMA(ai, bj, At, Bt) do { __builtin_amdgcn_s_setprio(1); _Pragma("unroll") for (int m = 0; m < 4; ++m) _Pragma("unroll") for (int n = 0; n < 2; ++n) _Pragma("unroll") for (int k = 0; k < 2; ++k) \
;         acc[ai][bj][m][n] = __builtin_amdgcn_mfma_f32_16x16x32_bf16(Bt[n][k], At[m][k], acc[ai][bj][m][n], 0, 0, 0); __builtin_amdgcn_s_setprio(0); } while (0)
; #define PG8_WAIT_V(n) asm volatile("s_waitcnt vmcnt(" #n ")" ::: "memory")
; template <int K, int LDA, int LDB, class Epi, class Sched>
; __device__ __forceinline__ void gemm_phase(LAS unsigned char* lds, const Gemm g, const Sched& S, const Epi& E, int wv) {
;     ...
;             PG8_LDB(B0, 0, 0); PG8_LDB(B1, 0, 1); PG8_SCHED; PG8_LDA(At, 0, 0); PG8_STAGE(PG8_SA(1, 1), a1 + hstepA, voffA);
;             PG8_WAIT_V(8); PG8_WAIT_L(0); PG8_BAR; PG8_MMA(0, 0, At, B0); PG8_MMA(0, 1, At, B1); PG8_BAR; PG8_SCHED;
;             PG8_LDA(At, 0, 1); PG8_STAGE(PG8_SB(0, 0), b2, voffB); PG8_STAGE(PG8_SB(0, 1), b2 + hstepB, voffB); PG8_STAGE(PG8_SA(0, 0), a2, voffA);
;             PG8_WAIT_V(8); PG8_WAIT_L(0); PG8_BAR; PG8_MMA(1, 0, At, B0); PG8_MMA(1, 1, At, B1); PG8_BAR; PG8_SCHED;
;             PG8_LDB(B0, 1, 0); PG8_LDB(B1, 1, 1); PG8_SCHED; PG8_LDA(At, 1, 0); PG8_STAGE(PG8_SA(0, 1), a2 + hstepA, voffA);
;             PG8_WAIT_V(8); PG8_WAIT_L(0); PG8_BAR; PG8_MMA(0, 0, At, B0); PG8_MMA(0, 1, At, B1); PG8_BAR; PG8_SCHED;
;             PG8_LDA(At, 1, 1); PG8_STAGE(PG8_SB(1, 0), b3, voffB); PG8_STAGE(PG8_SB(1, 1), b3 + hstepB, voffB); PG8_STAGE(PG8_SA(1, 0), a3, voffA);
;             PG8_WAIT_V(8); PG8_WAIT_L(0); PG8_BAR; PG8_MMA(1, 0, At, B0); PG8_MMA(1, 1, At, B1); PG8_BAR; PG8_SCHED;
.LBB0_1030:
	ds_read_b128 v[128:131], v201
	ds_read_b128 v[132:135], v201 offset:1024
	ds_read_b128 v[136:139], v201 offset:2048
	ds_read_b128 v[140:143], v201 offset:3072
	ds_read_b128 v[144:147], v205
	ds_read_b128 v[148:151], v205 offset:1024
	ds_read_b128 v[152:155], v205 offset:2048
	ds_read_b128 v[156:159], v205 offset:3072
	s_add_u32 s8, s42, 0x100
	s_addc_u32 s9, s43, 0
	s_cmp_eq_u32 s77, 4
	s_cselect_b32 s59, s37, s9
	s_cselect_b32 s58, s36, s8
	s_cselect_b32 s57, s35, s76
	s_cselect_b32 s56, s41, s75
	s_add_i32 m0, s45, 0xc000
	ds_read_b128 v[186:189], v209
	ds_read_b128 v[194:197], v209 offset:1024
	ds_read_b128 v[214:217], v209 offset:2048
	ds_read_b128 v[218:221], v209 offset:3072
	ds_read_b128 v[224:227], v209 offset:4096
	ds_read_b128 v[228:231], v209 offset:5120
	ds_read_b128 v[232:235], v209 offset:6144
	ds_read_b128 v[236:239], v209 offset:7168
	global_load_lds_dwordx4 v170, s[42:43]
	s_add_i32 m0, s45, 0xe000
	s_nop 0
	global_load_lds_dwordx4 v172, s[42:43]
	s_waitcnt vmcnt(8)
	s_waitcnt lgkmcnt(0)
	s_barrier
	s_setprio 1
	v_mfma_f32_16x16x32_bf16 v[124:127], v[128:131], v[186:189], v[124:127]
	v_mfma_f32_16x16x32_bf16 v[120:123], v[136:139], v[186:189], v[120:123]
	v_mfma_f32_16x16x32_bf16 v[108:111], v[128:131], v[214:217], v[108:111]
	v_mfma_f32_16x16x32_bf16 v[104:107], v[136:139], v[214:217], v[104:107]
	v_mfma_f32_16x16x32_bf16 v[92:95], v[128:131], v[224:227], v[92:95]
	v_mfma_f32_16x16x32_bf16 v[88:91], v[136:139], v[224:227], v[88:91]
	v_mfma_f32_16x16x32_bf16 v[76:79], v[128:131], v[232:235], v[76:79]
	v_mfma_f32_16x16x32_bf16 v[72:75], v[136:139], v[232:235], v[72:75]
	v_mfma_f32_16x16x32_bf16 v[124:127], v[132:135], v[194:197], v[124:127]
	v_mfma_f32_16x16x32_bf16 v[120:123], v[140:143], v[194:197], v[120:123]
	v_mfma_f32_16x16x32_bf16 v[108:111], v[132:135], v[218:221], v[108:111]
	v_mfma_f32_16x16x32_bf16 v[104:107], v[140:143], v[218:221], v[104:107]
	v_mfma_f32_16x16x32_bf16 v[92:95], v[132:135], v[228:231], v[92:95]
	v_mfma_f32_16x16x32_bf16 v[88:91], v[140:143], v[228:231], v[88:91]
	v_mfma_f32_16x16x32_bf16 v[76:79], v[132:135], v[236:239], v[76:79]
	v_mfma_f32_16x16x32_bf16 v[72:75], v[140:143], v[236:239], v[72:75]
	v_mfma_f32_16x16x32_bf16 v[116:119], v[144:147], v[186:189], v[116:119]
	v_mfma_f32_16x16x32_bf16 v[112:115], v[152:155], v[186:189], v[112:115]
	v_mfma_f32_16x16x32_bf16 v[100:103], v[144:147], v[214:217], v[100:103]
	v_mfma_f32_16x16x32_bf16 v[96:99], v[152:155], v[214:217], v[96:99]
	v_mfma_f32_16x16x32_bf16 v[84:87], v[144:147], v[224:227], v[84:87]
	v_mfma_f32_16x16x32_bf16 v[80:83], v[152:155], v[224:227], v[80:83]
	v_mfma_f32_16x16x32_bf16 v[68:71], v[144:147], v[232:235], v[68:71]
	v_mfma_f32_16x16x32_bf16 v[64:67], v[152:155], v[232:235], v[64:67]
	v_mfma_f32_16x16x32_bf16 v[116:119], v[148:151], v[194:197], v[116:119]
	v_mfma_f32_16x16x32_bf16 v[112:115], v[156:159], v[194:197], v[112:115]
	v_mfma_f32_16x16x32_bf16 v[100:103], v[148:151], v[218:221], v[100:103]
	v_mfma_f32_16x16x32_bf16 v[96:99], v[156:159], v[218:221], v[96:99]
	v_mfma_f32_16x16x32_bf16 v[84:87], v[148:151], v[228:231], v[84:87]
	v_mfma_f32_16x16x32_bf16 v[80:83], v[156:159], v[228:231], v[80:83]
	v_mfma_f32_16x16x32_bf16 v[68:71], v[148:151], v[236:239], v[68:71]
	v_mfma_f32_16x16x32_bf16 v[64:67], v[156:159], v[236:239], v[64:67]
	s_setprio 0
	s_barrier
	s_add_i32 s10, s69, s24
	s_mov_b32 m0, s10
	ds_read_b128 v[186:189], v209 offset:16384
	ds_read_b128 v[194:197], v209 offset:17408
	ds_read_b128 v[214:217], v209 offset:18432
	ds_read_b128 v[218:221], v209 offset:19456
	ds_read_b128 v[224:227], v209 offset:20480
	ds_read_b128 v[228:231], v209 offset:21504
	ds_read_b128 v[232:235], v209 offset:22528
	ds_read_b128 v[236:239], v209 offset:23552
	global_load_lds_dwordx4 v162, s[56:57]
	s_add_i32 m0, s10, 0x2000
	s_add_u32 s42, s56, 0x20000
	s_addc_u32 s43, s57, 0
	s_add_i32 s10, s70, s24
	global_load_lds_dwordx4 v166, s[56:57]
	s_mov_b32 m0, s10
	s_nop 0
	global_load_lds_dwordx4 v162, s[42:43]
	s_add_i32 m0, s10, 0x2000
	s_nop 0
	global_load_lds_dwordx4 v166, s[42:43]
	s_mov_b32 m0, s45
	s_nop 0
	global_load_lds_dwordx4 v160, s[58:59]
	s_mov_b32 m0, s60
	s_nop 0
	global_load_lds_dwordx4 v164, s[58:59]
	s_waitcnt vmcnt(8)
	s_waitcnt lgkmcnt(0)
	s_barrier
	s_setprio 1
	v_mfma_f32_16x16x32_bf16 v[60:63], v[128:131], v[186:189], v[60:63]
	v_mfma_f32_16x16x32_bf16 v[56:59], v[136:139], v[186:189], v[56:59]
	v_mfma_f32_16x16x32_bf16 v[44:47], v[128:131], v[214:217], v[44:47]
	v_mfma_f32_16x16x32_bf16 v[40:43], v[136:139], v[214:217], v[40:43]
	v_mfma_f32_16x16x32_bf16 v[28:31], v[128:131], v[224:227], v[28:31]
	v_mfma_f32_16x16x32_bf16 v[24:27], v[136:139], v[224:227], v[24:27]
	v_mfma_f32_16x16x32_bf16 v[12:15], v[128:131], v[232:235], v[12:15]
	v_mfma_f32_16x16x32_bf16 v[8:11], v[136:139], v[232:235], v[8:11]
	v_mfma_f32_16x16x32_bf16 v[60:63], v[132:135], v[194:197], v[60:63]
	v_mfma_f32_16x16x32_bf16 v[56:59], v[140:143], v[194:197], v[56:59]
	v_mfma_f32_16x16x32_bf16 v[44:47], v[132:135], v[218:221], v[44:47]
	v_mfma_f32_16x16x32_bf16 v[40:43], v[140:143], v[218:221], v[40:43]
	v_mfma_f32_16x16x32_bf16 v[28:31], v[132:135], v[228:231], v[28:31]
	v_mfma_f32_16x16x32_bf16 v[24:27], v[140:143], v[228:231], v[24:27]
	v_mfma_f32_16x16x32_bf16 v[12:15], v[132:135], v[236:239], v[12:15]
	v_mfma_f32_16x16x32_bf16 v[8:11], v[140:143], v[236:239], v[8:11]
	v_mfma_f32_16x16x32_bf16 v[52:55], v[144:147], v[186:189], v[52:55]
	v_mfma_f32_16x16x32_bf16 v[48:51], v[152:155], v[186:189], v[48:51]
	v_mfma_f32_16x16x32_bf16 v[36:39], v[144:147], v[214:217], v[36:39]
	v_mfma_f32_16x16x32_bf16 v[32:35], v[152:155], v[214:217], v[32:35]
	v_mfma_f32_16x16x32_bf16 v[20:23], v[144:147], v[224:227], v[20:23]
	v_mfma_f32_16x16x32_bf16 v[16:19], v[152:155], v[224:227], v[16:19]
	v_mfma_f32_16x16x32_bf16 v[4:7], v[144:147], v[232:235], v[4:7]
	v_mfma_f32_16x16x32_bf16 v[0:3], v[152:155], v[232:235], v[0:3]
	v_mfma_f32_16x16x32_bf16 v[52:55], v[148:151], v[194:197], v[52:55]
	v_mfma_f32_16x16x32_bf16 v[48:51], v[156:159], v[194:197], v[48:51]
	v_mfma_f32_16x16x32_bf16 v[36:39], v[148:151], v[218:221], v[36:39]
	v_mfma_f32_16x16x32_bf16 v[32:35], v[156:159], v[218:221], v[32:35]
	v_mfma_f32_16x16x32_bf16 v[20:23], v[148:151], v[228:231], v[20:23]
	v_mfma_f32_16x16x32_bf16 v[16:19], v[156:159], v[228:231], v[16:19]
	v_mfma_f32_16x16x32_bf16 v[4:7], v[148:151], v[236:239], v[4:7]
	v_mfma_f32_16x16x32_bf16 v[0:3], v[156:159], v[236:239], v[0:3]
	s_setprio 0
	s_barrier
; #define PG8_STAGE(bufoff, gbase, voff) do { _Pragma("unroll") for (int _i = 0; _i < 2; ++_i) \
;         __builtin_amdgcn_global_load_lds((const unsigned*)((const char*)(gbase) + (voff)[_i]), (LAS unsigned*)(lds + (bufoff) + ldsw + _i * 8192), 16, 0, 0); } while (0)
; #define PG8_LDA(dst, b, h) do { _Pragma("unroll") for (int m = 0; m < 4; ++m) _Pragma("unroll") for (int k = 0; k < 2; ++k) dst[m][k] = *(const LAS bf16x8*)(lds + PG8_SA(b, h) + aoff + m * 2048 + k * 1024); } while (0)
; #define PG8_LDB(dst, b, h) do { _Pragma("unroll") for (int n = 0; n < 2; ++n) _Pragma("unroll") for (int k = 0; k < 2; ++k) dst[n][k] = *(const LAS bf16x8*)(lds + PG8_SB(b, h) + boff + n * 2048 + k * 1024); } while (0)
; #define PG8_MMA(ai, bj, At, Bt) do { __builtin_amdgcn_s_setprio(1); _Pragma("unroll") for (int m = 0; m < 4; ++m) _Pragma("unroll") for (int n = 0; n < 2; ++n) _Pragma("unroll") for (int k = 0; k < 2; ++k) \
;         acc[ai][bj][m][n] = __builtin_amdgcn_mfma_f32_16x16x32_bf16(Bt[n][k], At[m][k], acc[ai][bj][m][n], 0, 0, 0); __builtin_amdgcn_s_setprio(0); } while (0)
; #define PG8_WAIT_V(n) asm volatile("s_waitcnt vmcnt(" #n ")" ::: "memory")
; #define PG8_WAIT_L(n) asm volatile("s_waitcnt lgkmcnt(" #n ")" ::: "memory")
; #define PG8_BAR __builtin_amdgcn_s_barrier()
; #define PG8_SCHED __builtin_amdgcn_sched_barrier(0)
; template <int K, int LDA, int LDB, class Epi, class Sched>
; __device__ __forceinline__ void gemm_phase(LAS unsigned char* lds, const Gemm g, const Sched& S, const Epi& E, int wv) {
;     ...
;             PG8_LDB(B0, 1, 0); PG8_LDB(B1, 1, 1); PG8_SCHED; PG8_LDA(At, 1, 0); PG8_STAGE(PG8_SA(0, 1), a2 + hstepA, voffA);
;             PG8_WAIT_V(8); PG8_WAIT_L(0); PG8_BAR; PG8_MMA(0, 0, At, B0); PG8_MMA(0, 1, At, B1); PG8_BAR; PG8_SCHED;
;             PG8_LDA(At, 1, 1); PG8_STAGE(PG8_SB(1, 0), b3, voffB); PG8_STAGE(PG8_SB(1, 1), b3 + hstepB, voffB); PG8_STAGE(PG8_SA(1, 0), a3, voffA);
;             PG8_WAIT_V(8); PG8_WAIT_L(0); PG8_BAR; PG8_MMA(1, 0, At, B0); PG8_MMA(1, 1, At, B1); PG8_BAR; PG8_SCHED;
;         }
;         if (wr == 0) PG8_BAR;
	s_add_i32 s10, 0, 0x18000
	s_add_i32 s11, 0, 0x1c000
	v_add_u32_e32 v140, s10, v185
	v_add_u32_e32 v156, s11, v185
	ds_read_b128 v[128:131], v140
	ds_read_b128 v[132:135], v140 offset:1024
	ds_read_b128 v[136:139], v140 offset:2048
	ds_read_b128 v[140:143], v140 offset:3072
	ds_read_b128 v[144:147], v156
	ds_read_b128 v[148:151], v156 offset:1024
	ds_read_b128 v[152:155], v156 offset:2048
	ds_read_b128 v[156:159], v156 offset:3072
	s_add_u32 s42, s58, 0x120000
	s_addc_u32 s43, s59, 0
	s_mov_b32 m0, s61
	ds_read_b128 v[186:189], v209 offset:32768
	ds_read_b128 v[194:197], v209 offset:33792
	ds_read_b128 v[214:217], v209 offset:34816
	ds_read_b128 v[218:221], v209 offset:35840
	ds_read_b128 v[224:227], v209 offset:36864
	ds_read_b128 v[228:231], v209 offset:37888
	ds_read_b128 v[232:235], v209 offset:38912
	ds_read_b128 v[236:239], v209 offset:39936
	global_load_lds_dwordx4 v160, s[42:43]
	s_mov_b32 m0, s62
	s_nop 0
	global_load_lds_dwordx4 v164, s[42:43]
	s_waitcnt vmcnt(8)
	s_waitcnt lgkmcnt(0)
	s_barrier
	s_setprio 1
	v_mfma_f32_16x16x32_bf16 v[124:127], v[128:131], v[186:189], v[124:127]
	v_mfma_f32_16x16x32_bf16 v[120:123], v[136:139], v[186:189], v[120:123]
	v_mfma_f32_16x16x32_bf16 v[108:111], v[128:131], v[214:217], v[108:111]
	v_mfma_f32_16x16x32_bf16 v[104:107], v[136:139], v[214:217], v[104:107]
	v_mfma_f32_16x16x32_bf16 v[92:95], v[128:131], v[224:227], v[92:95]
	v_mfma_f32_16x16x32_bf16 v[88:91], v[136:139], v[224:227], v[88:91]
	v_mfma_f32_16x16x32_bf16 v[76:79], v[128:131], v[232:235], v[76:79]
	v_mfma_f32_16x16x32_bf16 v[72:75], v[136:139], v[232:235], v[72:75]
	v_mfma_f32_16x16x32_bf16 v[124:127], v[132:135], v[194:197], v[124:127]
	v_mfma_f32_16x16x32_bf16 v[120:123], v[140:143], v[194:197], v[120:123]
	v_mfma_f32_16x16x32_bf16 v[108:111], v[132:135], v[218:221], v[108:111]
	v_mfma_f32_16x16x32_bf16 v[104:107], v[140:143], v[218:221], v[104:107]
	v_mfma_f32_16x16x32_bf16 v[92:95], v[132:135], v[228:231], v[92:95]
	v_mfma_f32_16x16x32_bf16 v[88:91], v[140:143], v[228:231], v[88:91]
	v_mfma_f32_16x16x32_bf16 v[76:79], v[132:135], v[236:239], v[76:79]
	v_mfma_f32_16x16x32_bf16 v[72:75], v[140:143], v[236:239], v[72:75]
	v_mfma_f32_16x16x32_bf16 v[116:119], v[144:147], v[186:189], v[116:119]
	v_mfma_f32_16x16x32_bf16 v[112:115], v[152:155], v[186:189], v[112:115]
	v_mfma_f32_16x16x32_bf16 v[100:103], v[144:147], v[214:217], v[100:103]
	v_mfma_f32_16x16x32_bf16 v[96:99], v[152:155], v[214:217], v[96:99]
	v_mfma_f32_16x16x32_bf16 v[84:87], v[144:147], v[224:227], v[84:87]
	v_mfma_f32_16x16x32_bf16 v[80:83], v[152:155], v[224:227], v[80:83]
	v_mfma_f32_16x16x32_bf16 v[68:71], v[144:147], v[232:235], v[68:71]
	v_mfma_f32_16x16x32_bf16 v[64:67], v[152:155], v[232:235], v[64:67]
	v_mfma_f32_16x16x32_bf16 v[116:119], v[148:151], v[194:197], v[116:119]
	v_mfma_f32_16x16x32_bf16 v[112:115], v[156:159], v[194:197], v[112:115]
	v_mfma_f32_16x16x32_bf16 v[100:103], v[148:151], v[218:221], v[100:103]
	v_mfma_f32_16x16x32_bf16 v[96:99], v[156:159], v[218:221], v[96:99]
	v_mfma_f32_16x16x32_bf16 v[84:87], v[148:151], v[228:231], v[84:87]
	v_mfma_f32_16x16x32_bf16 v[80:83], v[156:159], v[228:231], v[80:83]
	v_mfma_f32_16x16x32_bf16 v[68:71], v[148:151], v[236:239], v[68:71]
	v_mfma_f32_16x16x32_bf16 v[64:67], v[156:159], v[236:239], v[64:67]
	s_setprio 0
	s_barrier
	s_add_i32 s10, s10, s24
	s_mov_b32 m0, s10
	ds_read_b128 v[186:189], v209 offset:49152
	ds_read_b128 v[194:197], v209 offset:50176
	ds_read_b128 v[214:217], v209 offset:51200
	ds_read_b128 v[218:221], v209 offset:52224
	ds_read_b128 v[224:227], v209 offset:53248
	ds_read_b128 v[228:231], v209 offset:54272
	ds_read_b128 v[232:235], v209 offset:55296
	ds_read_b128 v[236:239], v209 offset:56320
	s_add_u32 s98, s56, s14
	s_addc_u32 s99, s57, s15
	global_load_lds_dwordx4 v162, s[98:99]
	s_add_i32 m0, s10, 0x2000
	s_add_u32 s42, s56, 0x20080
	s_addc_u32 s43, s57, 0
	s_add_i32 s10, s11, s24
	global_load_lds_dwordx4 v166, s[98:99]
	s_mov_b32 m0, s10
	s_nop 0
	global_load_lds_dwordx4 v162, s[42:43]
	s_add_i32 m0, s10, 0x2000
	s_nop 0
	global_load_lds_dwordx4 v166, s[42:43]
	s_mov_b32 m0, s65
	s_nop 0
	s_add_u32 s100, s58, s14
	s_addc_u32 s101, s59, s15
	global_load_lds_dwordx4 v160, s[100:101]
	s_mov_b32 m0, s66
	s_nop 0
	global_load_lds_dwordx4 v164, s[100:101]
	s_waitcnt vmcnt(8)
	s_waitcnt lgkmcnt(0)
	s_barrier
	s_setprio 1
	v_mfma_f32_16x16x32_bf16 v[60:63], v[128:131], v[186:189], v[60:63]
	v_mfma_f32_16x16x32_bf16 v[56:59], v[136:139], v[186:189], v[56:59]
	v_mfma_f32_16x16x32_bf16 v[44:47], v[128:131], v[214:217], v[44:47]
	v_mfma_f32_16x16x32_bf16 v[40:43], v[136:139], v[214:217], v[40:43]
	v_mfma_f32_16x16x32_bf16 v[28:31], v[128:131], v[224:227], v[28:31]
	v_mfma_f32_16x16x32_bf16 v[24:27], v[136:139], v[224:227], v[24:27]
	v_mfma_f32_16x16x32_bf16 v[12:15], v[128:131], v[232:235], v[12:15]
	v_mfma_f32_16x16x32_bf16 v[8:11], v[136:139], v[232:235], v[8:11]
	v_mfma_f32_16x16x32_bf16 v[60:63], v[132:135], v[194:197], v[60:63]
	v_mfma_f32_16x16x32_bf16 v[56:59], v[140:143], v[194:197], v[56:59]
	v_mfma_f32_16x16x32_bf16 v[44:47], v[132:135], v[218:221], v[44:47]
	v_mfma_f32_16x16x32_bf16 v[40:43], v[140:143], v[218:221], v[40:43]
	v_mfma_f32_16x16x32_bf16 v[28:31], v[132:135], v[228:231], v[28:31]
	v_mfma_f32_16x16x32_bf16 v[24:27], v[140:143], v[228:231], v[24:27]
	v_mfma_f32_16x16x32_bf16 v[12:15], v[132:135], v[236:239], v[12:15]
	v_mfma_f32_16x16x32_bf16 v[8:11], v[140:143], v[236:239], v[8:11]
	v_mfma_f32_16x16x32_bf16 v[52:55], v[144:147], v[186:189], v[52:55]
	v_mfma_f32_16x16x32_bf16 v[48:51], v[152:155], v[186:189], v[48:51]
	v_mfma_f32_16x16x32_bf16 v[36:39], v[144:147], v[214:217], v[36:39]
	v_mfma_f32_16x16x32_bf16 v[32:35], v[152:155], v[214:217], v[32:35]
	v_mfma_f32_16x16x32_bf16 v[20:23], v[144:147], v[224:227], v[20:23]
	v_mfma_f32_16x16x32_bf16 v[16:19], v[152:155], v[224:227], v[16:19]
	v_mfma_f32_16x16x32_bf16 v[4:7], v[144:147], v[232:235], v[4:7]
	v_mfma_f32_16x16x32_bf16 v[0:3], v[152:155], v[232:235], v[0:3]
	v_mfma_f32_16x16x32_bf16 v[52:55], v[148:151], v[194:197], v[52:55]
	v_mfma_f32_16x16x32_bf16 v[48:51], v[156:159], v[194:197], v[48:51]
	v_mfma_f32_16x16x32_bf16 v[36:39], v[148:151], v[218:221], v[36:39]
	v_mfma_f32_16x16x32_bf16 v[32:35], v[156:159], v[218:221], v[32:35]
	v_mfma_f32_16x16x32_bf16 v[20:23], v[148:151], v[228:231], v[20:23]
	v_mfma_f32_16x16x32_bf16 v[16:19], v[156:159], v[228:231], v[16:19]
	v_mfma_f32_16x16x32_bf16 v[4:7], v[148:151], v[236:239], v[4:7]
	v_mfma_f32_16x16x32_bf16 v[0:3], v[156:159], v[236:239], v[0:3]
	s_setprio 0
	s_barrier
	s_add_i32 s77, s77, 2
	s_add_u32 s75, s75, 0x100
	s_addc_u32 s76, s76, 0
	s_cmp_gt_u32 s77, 5
	s_mov_b64 s[42:43], s[8:9]
	s_cbranch_scc0 .LBB0_1030
	s_and_b64 vcc, exec, s[28:29]
	s_cbranch_vccz .LBB0_1033
	s_barrier

; #define PG8_STAGE(bufoff, gbase, voff) do { _Pragma("unroll") for (int _i = 0; _i < 2; ++_i) \
;         __builtin_amdgcn_global_load_lds((const unsigned*)((const char*)(gbase) + (voff)[_i]), (LAS unsigned*)(lds + (bufoff) + ldsw + _i * 8192), 16, 0, 0); } while (0)
; #define PG8_LDA(dst, b, h) do { _Pragma("unroll") for (int m = 0; m < 4; ++m) _Pragma("unroll") for (int k = 0; k < 2; ++k) dst[m][k] = *(const LAS bf16x8*)(lds + PG8_SA(b, h) + aoff + m * 2048 + k * 1024); } while (0)
; #define PG8_LDB(dst, b, h) do { _Pragma("unroll") for (int n = 0; n < 2; ++n) _Pragma("unroll") for (int k = 0; k < 2; ++k) dst[n][k] = *(const LAS bf16x8*)(lds + PG8_SB(b, h) + boff + n * 2048 + k * 1024); } while (0)
; #define PG8_MMA(ai, bj, At, Bt) do { __builtin_amdgcn_s_setprio(1); _Pragma("unroll") for (int m = 0; m < 4; ++m) _Pragma("unroll") for (int n = 0; n < 2; ++n) _Pragma("unroll") for (int k = 0; k < 2; ++k) \
;         acc[ai][bj][m][n] = __builtin_amdgcn_mfma_f32_16x16x32_bf16(Bt[n][k], At[m][k], acc[ai][bj][m][n], 0, 0, 0); __builtin_amdgcn_s_setprio(0); } while (0)
; #define PG8_WAIT_V(n) asm volatile("s_waitcnt vmcnt(" #n ")" ::: "memory")
; #define PG8_BAR __builtin_amdgcn_s_barrier()
; template <int K, int LDA, int LDB, class Epi, class Sched>
; __device__ __forceinline__ void gemm_phase(LAS unsigned char* lds, const Gemm g, const Sched& S, const Epi& E, int wv) {
;     ...
;         for (int t = 0; t < nt; t += 2) {
;             const bool last = (t == nt - 2);
;             const char* a1 = cA + (size_t)(t + 1) * kstep;
;             const char* a2 = last ? nA : cA + (size_t)(t + 2) * kstep; const char* b2 = last ? nB : cB + (size_t)(t + 2) * kstep;
;             const char* a3 = a2 + kstep; const char* b3 = b2 + kstep;
;             PG8_LDB(B0, 0, 0); PG8_LDB(B1, 0, 1); PG8_SCHED; PG8_LDA(At, 0, 0); PG8_STAGE(PG8_SA(1, 1), a1 + hstepA, voffA);
;             PG8_WAIT_V(8); PG8_WAIT_L(0); PG8_BAR; PG8_MMA(0, 0, At, B0); PG8_MMA(0, 1, At, B1); PG8_BAR; PG8_SCHED;
;             PG8_LDA(At, 0, 1); PG8_STAGE(PG8_SB(0, 0), b2, voffB); PG8_STAGE(PG8_SB(0, 1), b2 + hstepB, voffB); PG8_STAGE(PG8_SA(0, 0), a2, voffA);
;             PG8_WAIT_V(8); PG8_WAIT_L(0); PG8_BAR; PG8_MMA(1, 0, At, B0); PG8_MMA(1, 1, At, B1); PG8_BAR; PG8_SCHED;
;             PG8_LDB(B0, 1, 0); PG8_LDB(B1, 1, 1); PG8_SCHED; PG8_LDA(At, 1, 0); PG8_STAGE(PG8_SA(0, 1), a2 + hstepA, voffA);
.LBB0_1084:
	s_add_u32 s10, s54, s58
	s_addc_u32 s11, s55, s59
	s_add_u32 s62, s10, 0x100
	s_addc_u32 s63, s11, 0
	s_and_b64 s[60:61], s[56:57], exec
	s_cselect_b32 s61, s41, s63
	s_cselect_b32 s60, s40, s62
	s_add_u32 s58, s52, s58
	s_addc_u32 s59, s53, s59
	s_add_u32 s58, s58, 0x100
	s_addc_u32 s59, s59, 0
	s_and_b64 s[56:57], s[56:57], exec
	s_cselect_b32 s63, s39, s59
	s_cselect_b32 s62, s81, s58
	s_add_u32 s66, s10, 0x120080
	ds_read_b128 v[144:147], v157
	ds_read_b128 v[164:167], v157 offset:1024
	ds_read_b128 v[168:171], v157 offset:2048
	ds_read_b128 v[172:175], v157 offset:3072
	ds_read_b128 v[176:179], v160
	ds_read_b128 v[180:183], v160 offset:1024
	ds_read_b128 v[184:187], v160 offset:2048
	ds_read_b128 v[188:191], v160 offset:3072
	s_addc_u32 s67, s11, 0
	s_add_i32 s91, s76, s24
	s_add_i32 m0, s69, 0xc000
	s_add_i32 s10, s69, 0xe000
	s_add_i32 s88, s91, 0x2000
	s_add_u32 s64, s62, 0x10000
	s_addc_u32 s65, s63, 0
	s_add_i32 s90, s77, s24
	s_add_i32 s89, s90, 0x2000
	s_add_i32 s87, 0, 0x18000
	s_add_i32 s86, 0, 0x1c000
	s_add_u32 s58, s60, 0x120000
	s_addc_u32 s59, s61, 0
	s_add_i32 s85, s87, s24
	s_add_i32 s83, s85, 0x2000
	s_add_u32 s56, s62, 0x10080
	s_addc_u32 s57, s63, 0
	s_add_i32 s84, s86, s24
	s_add_i32 s82, s84, 0x2000
	ds_read_b128 v[192:195], v161
	ds_read_b128 v[196:199], v161 offset:1024
	ds_read_b128 v[200:203], v161 offset:2048
	ds_read_b128 v[204:207], v161 offset:3072
	ds_read_b128 v[208:211], v161 offset:4096
	ds_read_b128 v[212:215], v161 offset:5120
	ds_read_b128 v[216:219], v161 offset:6144
	ds_read_b128 v[224:227], v161 offset:7168
	global_load_lds_dwordx4 v134, s[66:67]
	s_mov_b32 m0, s10
	s_nop 0
	global_load_lds_dwordx4 v130, s[66:67]
	s_waitcnt vmcnt(8)
	s_waitcnt lgkmcnt(0)
	s_barrier
	s_setprio 1
	v_mfma_f32_16x16x32_bf16 v[124:127], v[144:147], v[192:195], v[124:127]
	v_mfma_f32_16x16x32_bf16 v[120:123], v[168:171], v[192:195], v[120:123]
	v_mfma_f32_16x16x32_bf16 v[112:115], v[144:147], v[200:203], v[112:115]
	v_mfma_f32_16x16x32_bf16 v[104:107], v[168:171], v[200:203], v[104:107]
	v_mfma_f32_16x16x32_bf16 v[96:99], v[144:147], v[208:211], v[96:99]
	v_mfma_f32_16x16x32_bf16 v[88:91], v[168:171], v[208:211], v[88:91]
	v_mfma_f32_16x16x32_bf16 v[80:83], v[144:147], v[216:219], v[80:83]
	v_mfma_f32_16x16x32_bf16 v[72:75], v[168:171], v[216:219], v[72:75]
	v_mfma_f32_16x16x32_bf16 v[124:127], v[164:167], v[196:199], v[124:127]
	v_mfma_f32_16x16x32_bf16 v[120:123], v[172:175], v[196:199], v[120:123]
	v_mfma_f32_16x16x32_bf16 v[112:115], v[164:167], v[204:207], v[112:115]
	v_mfma_f32_16x16x32_bf16 v[104:107], v[172:175], v[204:207], v[104:107]
	v_mfma_f32_16x16x32_bf16 v[96:99], v[164:167], v[212:215], v[96:99]
	v_mfma_f32_16x16x32_bf16 v[88:91], v[172:175], v[212:215], v[88:91]
	v_mfma_f32_16x16x32_bf16 v[80:83], v[164:167], v[224:227], v[80:83]
	v_mfma_f32_16x16x32_bf16 v[72:75], v[172:175], v[224:227], v[72:75]
	v_mfma_f32_16x16x32_bf16 v[116:119], v[176:179], v[192:195], v[116:119]
	v_mfma_f32_16x16x32_bf16 v[108:111], v[184:187], v[192:195], v[108:111]
	v_mfma_f32_16x16x32_bf16 v[100:103], v[176:179], v[200:203], v[100:103]
	v_mfma_f32_16x16x32_bf16 v[92:95], v[184:187], v[200:203], v[92:95]
	v_mfma_f32_16x16x32_bf16 v[84:87], v[176:179], v[208:211], v[84:87]
	v_mfma_f32_16x16x32_bf16 v[76:79], v[184:187], v[208:211], v[76:79]
	v_mfma_f32_16x16x32_bf16 v[68:71], v[176:179], v[216:219], v[68:71]
	v_mfma_f32_16x16x32_bf16 v[64:67], v[184:187], v[216:219], v[64:67]
	v_mfma_f32_16x16x32_bf16 v[116:119], v[180:183], v[196:199], v[116:119]
	v_mfma_f32_16x16x32_bf16 v[108:111], v[188:191], v[196:199], v[108:111]
	v_mfma_f32_16x16x32_bf16 v[100:103], v[180:183], v[204:207], v[100:103]
	v_mfma_f32_16x16x32_bf16 v[92:95], v[188:191], v[204:207], v[92:95]
	v_mfma_f32_16x16x32_bf16 v[84:87], v[180:183], v[212:215], v[84:87]
	v_mfma_f32_16x16x32_bf16 v[76:79], v[188:191], v[212:215], v[76:79]
	v_mfma_f32_16x16x32_bf16 v[68:71], v[180:183], v[224:227], v[68:71]
	v_mfma_f32_16x16x32_bf16 v[64:67], v[188:191], v[224:227], v[64:67]
	s_setprio 0
	s_barrier
	s_mov_b32 m0, s91
	ds_read_b128 v[192:195], v161 offset:16384
	ds_read_b128 v[196:199], v161 offset:17408
	ds_read_b128 v[200:203], v161 offset:18432
	ds_read_b128 v[204:207], v161 offset:19456
	ds_read_b128 v[208:211], v161 offset:20480
	ds_read_b128 v[212:215], v161 offset:21504
	ds_read_b128 v[216:219], v161 offset:22528
	ds_read_b128 v[224:227], v161 offset:23552
	global_load_lds_dwordx4 v132, s[62:63]
	s_mov_b32 m0, s88
	s_nop 0
	global_load_lds_dwordx4 v128, s[62:63]
	s_mov_b32 m0, s90
	s_nop 0
	global_load_lds_dwordx4 v132, s[64:65]
	s_mov_b32 m0, s89
	s_nop 0
	global_load_lds_dwordx4 v128, s[64:65]
	s_mov_b32 m0, s69
	s_nop 0
	global_load_lds_dwordx4 v134, s[60:61]
	s_mov_b32 m0, s70
	s_nop 0
	global_load_lds_dwordx4 v130, s[60:61]
	s_waitcnt vmcnt(8)
	s_waitcnt lgkmcnt(0)
	s_barrier
; #define PG8_STAGE(bufoff, gbase, voff) do { _Pragma("unroll") for (int _i = 0; _i < 2; ++_i) \
;         __builtin_amdgcn_global_load_lds((const unsigned*)((const char*)(gbase) + (voff)[_i]), (LAS unsigned*)(lds + (bufoff) + ldsw + _i * 8192), 16, 0, 0); } while (0)
; #define PG8_LDA(dst, b, h) do { _Pragma("unroll") for (int m = 0; m < 4; ++m) _Pragma("unroll") for (int k = 0; k < 2; ++k) dst[m][k] = *(const LAS bf16x8*)(lds + PG8_SA(b, h) + aoff + m * 2048 + k * 1024); } while (0)
; #define PG8_LDB(dst, b, h) do { _Pragma("unroll") for (int n = 0; n < 2; ++n) _Pragma("unroll") for (int k = 0; k < 2; ++k) dst[n][k] = *(const LAS bf16x8*)(lds + PG8_SB(b, h) + boff + n * 2048 + k * 1024); } while (0)
; #define PG8_MMA(ai, bj, At, Bt) do { __builtin_amdgcn_s_setprio(1); _Pragma("unroll") for (int m = 0; m < 4; ++m) _Pragma("unroll") for (int n = 0; n < 2; ++n) _Pragma("unroll") for (int k = 0; k < 2; ++k) \
;         acc[ai][bj][m][n] = __builtin_amdgcn_mfma_f32_16x16x32_bf16(Bt[n][k], At[m][k], acc[ai][bj][m][n], 0, 0, 0); __builtin_amdgcn_s_setprio(0); } while (0)
; #define PG8_WAIT_V(n) asm volatile("s_waitcnt vmcnt(" #n ")" ::: "memory")
; #define PG8_WAIT_L(n) asm volatile("s_waitcnt lgkmcnt(" #n ")" ::: "memory")
; #define PG8_BAR __builtin_amdgcn_s_barrier()
; #define PG8_SCHED __builtin_amdgcn_sched_barrier(0)
; template <int K, int LDA, int LDB, class Epi, class Sched>
; __device__ __forceinline__ void gemm_phase(LAS unsigned char* lds, const Gemm g, const Sched& S, const Epi& E, int wv) {
;     ...
;             PG8_WAIT_V(8); PG8_WAIT_L(0); PG8_BAR; PG8_MMA(1, 0, At, B0); PG8_MMA(1, 1, At, B1); PG8_BAR; PG8_SCHED;
;             PG8_LDB(B0, 1, 0); PG8_LDB(B1, 1, 1); PG8_SCHED; PG8_LDA(At, 1, 0); PG8_STAGE(PG8_SA(0, 1), a2 + hstepA, voffA);
;             PG8_WAIT_V(8); PG8_WAIT_L(0); PG8_BAR; PG8_MMA(0, 0, At, B0); PG8_MMA(0, 1, At, B1); PG8_BAR; PG8_SCHED;
;             PG8_LDA(At, 1, 1); PG8_STAGE(PG8_SB(1, 0), b3, voffB); PG8_STAGE(PG8_SB(1, 1), b3 + hstepB, voffB); PG8_STAGE(PG8_SA(1, 0), a3, voffA);
	s_setprio 1
	v_mfma_f32_16x16x32_bf16 v[60:63], v[144:147], v[192:195], v[60:63]
	v_mfma_f32_16x16x32_bf16 v[56:59], v[168:171], v[192:195], v[56:59]
	v_mfma_f32_16x16x32_bf16 v[48:51], v[144:147], v[200:203], v[48:51]
	v_mfma_f32_16x16x32_bf16 v[40:43], v[168:171], v[200:203], v[40:43]
	v_mfma_f32_16x16x32_bf16 v[32:35], v[144:147], v[208:211], v[32:35]
	v_mfma_f32_16x16x32_bf16 v[24:27], v[168:171], v[208:211], v[24:27]
	v_mfma_f32_16x16x32_bf16 v[16:19], v[144:147], v[216:219], v[16:19]
	v_mfma_f32_16x16x32_bf16 v[8:11], v[168:171], v[216:219], v[8:11]
	v_mfma_f32_16x16x32_bf16 v[60:63], v[164:167], v[196:199], v[60:63]
	v_mfma_f32_16x16x32_bf16 v[56:59], v[172:175], v[196:199], v[56:59]
	v_mfma_f32_16x16x32_bf16 v[48:51], v[164:167], v[204:207], v[48:51]
	v_mfma_f32_16x16x32_bf16 v[40:43], v[172:175], v[204:207], v[40:43]
	v_mfma_f32_16x16x32_bf16 v[32:35], v[164:167], v[212:215], v[32:35]
	v_mfma_f32_16x16x32_bf16 v[24:27], v[172:175], v[212:215], v[24:27]
	v_mfma_f32_16x16x32_bf16 v[16:19], v[164:167], v[224:227], v[16:19]
	v_mfma_f32_16x16x32_bf16 v[8:11], v[172:175], v[224:227], v[8:11]
	v_mfma_f32_16x16x32_bf16 v[52:55], v[176:179], v[192:195], v[52:55]
	v_mfma_f32_16x16x32_bf16 v[44:47], v[184:187], v[192:195], v[44:47]
	v_mfma_f32_16x16x32_bf16 v[36:39], v[176:179], v[200:203], v[36:39]
	v_mfma_f32_16x16x32_bf16 v[28:31], v[184:187], v[200:203], v[28:31]
	v_mfma_f32_16x16x32_bf16 v[20:23], v[176:179], v[208:211], v[20:23]
	v_mfma_f32_16x16x32_bf16 v[12:15], v[184:187], v[208:211], v[12:15]
	v_mfma_f32_16x16x32_bf16 v[4:7], v[176:179], v[216:219], v[4:7]
	v_mfma_f32_16x16x32_bf16 v[0:3], v[184:187], v[216:219], v[0:3]
	v_mfma_f32_16x16x32_bf16 v[52:55], v[180:183], v[196:199], v[52:55]
	v_mfma_f32_16x16x32_bf16 v[44:47], v[188:191], v[196:199], v[44:47]
	v_mfma_f32_16x16x32_bf16 v[36:39], v[180:183], v[204:207], v[36:39]
	v_mfma_f32_16x16x32_bf16 v[28:31], v[188:191], v[204:207], v[28:31]
	v_mfma_f32_16x16x32_bf16 v[20:23], v[180:183], v[212:215], v[20:23]
	v_mfma_f32_16x16x32_bf16 v[12:15], v[188:191], v[212:215], v[12:15]
	v_mfma_f32_16x16x32_bf16 v[4:7], v[180:183], v[224:227], v[4:7]
	v_mfma_f32_16x16x32_bf16 v[0:3], v[188:191], v[224:227], v[0:3]
	s_setprio 0
	s_barrier
	v_add_u32_e32 v142, s87, v149
	ds_read_b128 v[144:147], v142
	ds_read_b128 v[164:167], v142 offset:1024
	ds_read_b128 v[168:171], v142 offset:2048
	ds_read_b128 v[172:175], v142 offset:3072
	v_add_u32_e32 v142, s86, v149
	ds_read_b128 v[176:179], v142
	ds_read_b128 v[180:183], v142 offset:1024
	ds_read_b128 v[184:187], v142 offset:2048
	ds_read_b128 v[188:191], v142 offset:3072
	s_mov_b32 m0, s71
	ds_read_b128 v[192:195], v161 offset:32768
	ds_read_b128 v[196:199], v161 offset:33792
	ds_read_b128 v[200:203], v161 offset:34816
	ds_read_b128 v[204:207], v161 offset:35840
	ds_read_b128 v[208:211], v161 offset:36864
	ds_read_b128 v[212:215], v161 offset:37888
	ds_read_b128 v[216:219], v161 offset:38912
	ds_read_b128 v[224:227], v161 offset:39936
	global_load_lds_dwordx4 v134, s[58:59]
	s_mov_b32 m0, s72
	s_nop 0
	global_load_lds_dwordx4 v130, s[58:59]
	s_waitcnt vmcnt(8)
	s_waitcnt lgkmcnt(0)
	s_barrier
	s_setprio 1
	v_mfma_f32_16x16x32_bf16 v[124:127], v[144:147], v[192:195], v[124:127]
	v_mfma_f32_16x16x32_bf16 v[120:123], v[168:171], v[192:195], v[120:123]
	v_mfma_f32_16x16x32_bf16 v[112:115], v[144:147], v[200:203], v[112:115]
	v_mfma_f32_16x16x32_bf16 v[104:107], v[168:171], v[200:203], v[104:107]
	v_mfma_f32_16x16x32_bf16 v[96:99], v[144:147], v[208:211], v[96:99]
	v_mfma_f32_16x16x32_bf16 v[88:91], v[168:171], v[208:211], v[88:91]
	v_mfma_f32_16x16x32_bf16 v[80:83], v[144:147], v[216:219], v[80:83]
	v_mfma_f32_16x16x32_bf16 v[72:75], v[168:171], v[216:219], v[72:75]
	v_mfma_f32_16x16x32_bf16 v[124:127], v[164:167], v[196:199], v[124:127]
	v_mfma_f32_16x16x32_bf16 v[120:123], v[172:175], v[196:199], v[120:123]
	v_mfma_f32_16x16x32_bf16 v[112:115], v[164:167], v[204:207], v[112:115]
	v_mfma_f32_16x16x32_bf16 v[104:107], v[172:175], v[204:207], v[104:107]
	v_mfma_f32_16x16x32_bf16 v[96:99], v[164:167], v[212:215], v[96:99]
	v_mfma_f32_16x16x32_bf16 v[88:91], v[172:175], v[212:215], v[88:91]
	v_mfma_f32_16x16x32_bf16 v[80:83], v[164:167], v[224:227], v[80:83]
	v_mfma_f32_16x16x32_bf16 v[72:75], v[172:175], v[224:227], v[72:75]
	v_mfma_f32_16x16x32_bf16 v[116:119], v[176:179], v[192:195], v[116:119]
	v_mfma_f32_16x16x32_bf16 v[108:111], v[184:187], v[192:195], v[108:111]
	v_mfma_f32_16x16x32_bf16 v[100:103], v[176:179], v[200:203], v[100:103]
	v_mfma_f32_16x16x32_bf16 v[92:95], v[184:187], v[200:203], v[92:95]
	v_mfma_f32_16x16x32_bf16 v[84:87], v[176:179], v[208:211], v[84:87]
	v_mfma_f32_16x16x32_bf16 v[76:79], v[184:187], v[208:211], v[76:79]
	v_mfma_f32_16x16x32_bf16 v[68:71], v[176:179], v[216:219], v[68:71]
	v_mfma_f32_16x16x32_bf16 v[64:67], v[184:187], v[216:219], v[64:67]
	v_mfma_f32_16x16x32_bf16 v[116:119], v[180:183], v[196:199], v[116:119]
	v_mfma_f32_16x16x32_bf16 v[108:111], v[188:191], v[196:199], v[108:111]
	v_mfma_f32_16x16x32_bf16 v[100:103], v[180:183], v[204:207], v[100:103]
	v_mfma_f32_16x16x32_bf16 v[92:95], v[188:191], v[204:207], v[92:95]
	v_mfma_f32_16x16x32_bf16 v[84:87], v[180:183], v[212:215], v[84:87]
	v_mfma_f32_16x16x32_bf16 v[76:79], v[188:191], v[212:215], v[76:79]
	v_mfma_f32_16x16x32_bf16 v[68:71], v[180:183], v[224:227], v[68:71]
	v_mfma_f32_16x16x32_bf16 v[64:67], v[188:191], v[224:227], v[64:67]
	s_setprio 0
	s_barrier
; #define PG8_STAGE(bufoff, gbase, voff) do { _Pragma("unroll") for (int _i = 0; _i < 2; ++_i) \
;         __builtin_amdgcn_global_load_lds((const unsigned*)((const char*)(gbase) + (voff)[_i]), (LAS unsigned*)(lds + (bufoff) + ldsw + _i * 8192), 16, 0, 0); } while (0)
; #define PG8_LDA(dst, b, h) do { _Pragma("unroll") for (int m = 0; m < 4; ++m) _Pragma("unroll") for (int k = 0; k < 2; ++k) dst[m][k] = *(const LAS bf16x8*)(lds + PG8_SA(b, h) + aoff + m * 2048 + k * 1024); } while (0)
; #define PG8_MMA(ai, bj, At, Bt) do { __builtin_amdgcn_s_setprio(1); _Pragma("unroll") for (int m = 0; m < 4; ++m) _Pragma("unroll") for (int n = 0; n < 2; ++n) _Pragma("unroll") for (int k = 0; k < 2; ++k) \
;         acc[ai][bj][m][n] = __builtin_amdgcn_mfma_f32_16x16x32_bf16(Bt[n][k], At[m][k], acc[ai][bj][m][n], 0, 0, 0); __builtin_amdgcn_s_setprio(0); } while (0)
; #define PG8_WAIT_V(n) asm volatile("s_waitcnt vmcnt(" #n ")" ::: "memory")
; #define PG8_WAIT_L(n) asm volatile("s_waitcnt lgkmcnt(" #n ")" ::: "memory")
; #define PG8_BAR __builtin_amdgcn_s_barrier()
; #define PG8_SCHED __builtin_amdgcn_sched_barrier(0)
; template <int K, int LDA, int LDB, class Epi, class Sched>
; __device__ __forceinline__ void gemm_phase(LAS unsigned char* lds, const Gemm g, const Sched& S, const Epi& E, int wv) {
;     ...
;             PG8_LDA(At, 1, 1); PG8_STAGE(PG8_SB(1, 0), b3, voffB); PG8_STAGE(PG8_SB(1, 1), b3 + hstepB, voffB); PG8_STAGE(PG8_SA(1, 0), a3, voffA);
;             PG8_WAIT_V(8); PG8_WAIT_L(0); PG8_BAR; PG8_MMA(1, 0, At, B0); PG8_MMA(1, 1, At, B1); PG8_BAR; PG8_SCHED;
;         }
;         if (wr == 0) PG8_BAR;
	s_mov_b32 m0, s85
	ds_read_b128 v[192:195], v161 offset:49152
	ds_read_b128 v[196:199], v161 offset:50176
	ds_read_b128 v[200:203], v161 offset:51200
	ds_read_b128 v[204:207], v161 offset:52224
	ds_read_b128 v[208:211], v161 offset:53248
	ds_read_b128 v[212:215], v161 offset:54272
	ds_read_b128 v[216:219], v161 offset:55296
	ds_read_b128 v[224:227], v161 offset:56320
	s_add_u32 s98, s62, s34
	s_addc_u32 s99, s63, s35
	global_load_lds_dwordx4 v132, s[98:99]
	s_mov_b32 m0, s83
	s_nop 0
	global_load_lds_dwordx4 v128, s[98:99]
	s_mov_b32 m0, s84
	s_nop 0
	global_load_lds_dwordx4 v132, s[56:57]
	s_mov_b32 m0, s82
	s_nop 0
	global_load_lds_dwordx4 v128, s[56:57]
	s_mov_b32 m0, s74
	s_nop 0
	s_add_u32 s100, s60, s34
	s_addc_u32 s101, s61, s35
	global_load_lds_dwordx4 v134, s[100:101]
	s_mov_b32 m0, s75
	s_nop 0
	global_load_lds_dwordx4 v130, s[100:101]
	s_waitcnt vmcnt(8)
	s_waitcnt lgkmcnt(0)
	s_barrier
	s_setprio 1
	v_mfma_f32_16x16x32_bf16 v[60:63], v[144:147], v[192:195], v[60:63]
	v_mfma_f32_16x16x32_bf16 v[56:59], v[168:171], v[192:195], v[56:59]
	v_mfma_f32_16x16x32_bf16 v[48:51], v[144:147], v[200:203], v[48:51]
	v_mfma_f32_16x16x32_bf16 v[40:43], v[168:171], v[200:203], v[40:43]
	v_mfma_f32_16x16x32_bf16 v[32:35], v[144:147], v[208:211], v[32:35]
	v_mfma_f32_16x16x32_bf16 v[24:27], v[168:171], v[208:211], v[24:27]
	v_mfma_f32_16x16x32_bf16 v[16:19], v[144:147], v[216:219], v[16:19]
	v_mfma_f32_16x16x32_bf16 v[8:11], v[168:171], v[216:219], v[8:11]
	v_mfma_f32_16x16x32_bf16 v[60:63], v[164:167], v[196:199], v[60:63]
	v_mfma_f32_16x16x32_bf16 v[56:59], v[172:175], v[196:199], v[56:59]
	v_mfma_f32_16x16x32_bf16 v[48:51], v[164:167], v[204:207], v[48:51]
	v_mfma_f32_16x16x32_bf16 v[40:43], v[172:175], v[204:207], v[40:43]
	v_mfma_f32_16x16x32_bf16 v[32:35], v[164:167], v[212:215], v[32:35]
	v_mfma_f32_16x16x32_bf16 v[24:27], v[172:175], v[212:215], v[24:27]
	v_mfma_f32_16x16x32_bf16 v[16:19], v[164:167], v[224:227], v[16:19]
	v_mfma_f32_16x16x32_bf16 v[8:11], v[172:175], v[224:227], v[8:11]
	v_mfma_f32_16x16x32_bf16 v[52:55], v[176:179], v[192:195], v[52:55]
	v_mfma_f32_16x16x32_bf16 v[44:47], v[184:187], v[192:195], v[44:47]
	v_mfma_f32_16x16x32_bf16 v[36:39], v[176:179], v[200:203], v[36:39]
	v_mfma_f32_16x16x32_bf16 v[28:31], v[184:187], v[200:203], v[28:31]
	v_mfma_f32_16x16x32_bf16 v[20:23], v[176:179], v[208:211], v[20:23]
	v_mfma_f32_16x16x32_bf16 v[12:15], v[184:187], v[208:211], v[12:15]
	v_mfma_f32_16x16x32_bf16 v[4:7], v[176:179], v[216:219], v[4:7]
	v_mfma_f32_16x16x32_bf16 v[0:3], v[184:187], v[216:219], v[0:3]
	v_mfma_f32_16x16x32_bf16 v[52:55], v[180:183], v[196:199], v[52:55]
	v_mfma_f32_16x16x32_bf16 v[44:47], v[188:191], v[196:199], v[44:47]
	v_mfma_f32_16x16x32_bf16 v[36:39], v[180:183], v[204:207], v[36:39]
	v_mfma_f32_16x16x32_bf16 v[28:31], v[188:191], v[204:207], v[28:31]
	v_mfma_f32_16x16x32_bf16 v[20:23], v[180:183], v[212:215], v[20:23]
	v_mfma_f32_16x16x32_bf16 v[12:15], v[188:191], v[212:215], v[12:15]
	v_mfma_f32_16x16x32_bf16 v[4:7], v[180:183], v[224:227], v[4:7]
	v_mfma_f32_16x16x32_bf16 v[0:3], v[188:191], v[224:227], v[0:3]
	s_setprio 0
	s_barrier
	s_andn2_b64 vcc, exec, s[8:9]
	s_mov_b64 s[56:57], -1
	s_mov_b64 s[8:9], 0
	s_mov_b64 s[58:59], 0x100
	s_cbranch_vccz .LBB0_1084
	s_and_b64 vcc, exec, s[28:29]
	s_cbranch_vccz .LBB0_1087
	s_barrier

; #define PG8_STAGE(bufoff, gbase, voff) do { _Pragma("unroll") for (int _i = 0; _i < 2; ++_i) \
;         __builtin_amdgcn_global_load_lds((const unsigned*)((const char*)(gbase) + (voff)[_i]), (LAS unsigned*)(lds + (bufoff) + ldsw + _i * 8192), 16, 0, 0); } while (0)
; #define PG8_LDA(dst, b, h) do { _Pragma("unroll") for (int m = 0; m < 4; ++m) _Pragma("unroll") for (int k = 0; k < 2; ++k) dst[m][k] = *(const LAS bf16x8*)(lds + PG8_SA(b, h) + aoff + m * 2048 + k * 1024); } while (0)
; #define PG8_LDB(dst, b, h) do { _Pragma("unroll") for (int n = 0; n < 2; ++n) _Pragma("unroll") for (int k = 0; k < 2; ++k) dst[n][k] = *(const LAS bf16x8*)(lds + PG8_SB(b, h) + boff + n * 2048 + k * 1024); } while (0)
; #define PG8_MMA(ai, bj, At, Bt) do { __builtin_amdgcn_s_setprio(1); _Pragma("unroll") for (int m = 0; m < 4; ++m) _Pragma("unroll") for (int n = 0; n < 2; ++n) _Pragma("unroll") for (int k = 0; k < 2; ++k) \
;         acc[ai][bj][m][n] = __builtin_amdgcn_mfma_f32_16x16x32_bf16(Bt[n][k], At[m][k], acc[ai][bj][m][n], 0, 0, 0); __builtin_amdgcn_s_setprio(0); } while (0)
; #define PG8_BAR __builtin_amdgcn_s_barrier()
; template <int K, int LDA, int LDB, class Epi, class Sched>
; __device__ __forceinline__ void gemm_phase(LAS unsigned char* lds, const Gemm g, const Sched& S, const Epi& E, int wv) {
;     ...
;         const bool has_next = S.next(ui + 1, nxt);
;         const char* nA = has_next ? gA + (size_t)nxt.pm * tstepA : cA; const char* nB = has_next ? gB + (size_t)nxt.pn * tstepB : cB;
; #pragma nounroll
;         for (int t = 0; t < nt; t += 2) {
;             const bool last = (t == nt - 2);
;             const char* a1 = cA + (size_t)(t + 1) * kstep;
;             const char* a2 = last ? nA : cA + (size_t)(t + 2) * kstep; const char* b2 = last ? nB : cB + (size_t)(t + 2) * kstep;
;             const char* a3 = a2 + kstep; const char* b3 = b2 + kstep;
;             PG8_LDB(B0, 0, 0); PG8_LDB(B1, 0, 1); PG8_SCHED; PG8_LDA(At, 0, 0); PG8_STAGE(PG8_SA(1, 1), a1 + hstepA, voffA);
;             PG8_WAIT_V(8); PG8_WAIT_L(0); PG8_BAR; PG8_MMA(0, 0, At, B0); PG8_MMA(0, 1, At, B1); PG8_BAR; PG8_SCHED;
;             PG8_LDA(At, 0, 1); PG8_STAGE(PG8_SB(0, 0), b2, voffB); PG8_STAGE(PG8_SB(0, 1), b2 + hstepB, voffB); PG8_STAGE(PG8_SA(0, 0), a2, voffA);
;             PG8_WAIT_V(8); PG8_WAIT_L(0); PG8_BAR; PG8_MMA(1, 0, At, B0); PG8_MMA(1, 1, At, B1); PG8_BAR; PG8_SCHED;
.LBB0_1106:
	s_add_u32 s64, s54, s58
	s_addc_u32 s65, s55, s59
	s_add_u32 s62, s64, 0x100
	s_addc_u32 s63, s65, 0
	s_and_b64 s[60:61], s[56:57], exec
	s_cselect_b32 s61, s37, s63
	s_cselect_b32 s60, s77, s62
	s_add_u32 s58, s52, s58
	s_addc_u32 s59, s53, s59
	s_add_u32 s58, s58, 0x100
	s_addc_u32 s59, s59, 0
	s_and_b64 s[56:57], s[56:57], exec
	s_cselect_b32 s63, s39, s59
	s_cselect_b32 s62, s38, s58
	s_add_u32 s66, s64, 0x10080
	ds_read_b128 v[140:143], v161
	ds_read_b128 v[144:147], v161 offset:1024
	ds_read_b128 v[148:151], v161 offset:2048
	ds_read_b128 v[152:155], v161 offset:3072
	ds_read_b128 v[166:169], v162
	ds_read_b128 v[170:173], v162 offset:1024
	ds_read_b128 v[174:177], v162 offset:2048
	ds_read_b128 v[178:181], v162 offset:3072
	s_addc_u32 s67, s65, 0
	s_add_i32 s87, s73, s24
	s_add_i32 m0, s43, 0xc000
	s_add_i32 s88, s43, 0xe000
	s_add_i32 s84, s87, 0x2000
	s_add_u32 s64, s62, 0x120000
	s_addc_u32 s65, s63, 0
	s_add_i32 s86, s74, s24
	s_add_i32 s85, s86, 0x2000
	s_add_i32 s83, 0, 0x18000
	s_add_i32 s82, 0, 0x1c000
	s_add_u32 s58, s60, 0x10000
	s_addc_u32 s59, s61, 0
	s_add_i32 s81, s83, s24
	s_add_i32 s79, s81, 0x2000
	s_add_u32 s56, s62, 0x120080
	s_addc_u32 s57, s63, 0
	s_add_i32 s80, s82, s24
	s_add_i32 s78, s80, 0x2000
	ds_read_b128 v[182:185], v163
	ds_read_b128 v[186:189], v163 offset:1024
	ds_read_b128 v[190:193], v163 offset:2048
	ds_read_b128 v[194:197], v163 offset:3072
	ds_read_b128 v[198:201], v163 offset:4096
	ds_read_b128 v[202:205], v163 offset:5120
	ds_read_b128 v[206:209], v163 offset:6144
	ds_read_b128 v[210:213], v163 offset:7168
	global_load_lds_dwordx4 v134, s[66:67]
	s_mov_b32 m0, s88
	s_nop 0
	global_load_lds_dwordx4 v130, s[66:67]
	s_waitcnt vmcnt(8)
	s_waitcnt lgkmcnt(0)
	s_barrier
	s_setprio 1
	v_mfma_f32_16x16x32_bf16 v[124:127], v[140:143], v[182:185], v[124:127]
	v_mfma_f32_16x16x32_bf16 v[120:123], v[148:151], v[182:185], v[120:123]
	v_mfma_f32_16x16x32_bf16 v[112:115], v[140:143], v[190:193], v[112:115]
	v_mfma_f32_16x16x32_bf16 v[104:107], v[148:151], v[190:193], v[104:107]
	v_mfma_f32_16x16x32_bf16 v[96:99], v[140:143], v[198:201], v[96:99]
	v_mfma_f32_16x16x32_bf16 v[88:91], v[148:151], v[198:201], v[88:91]
	v_mfma_f32_16x16x32_bf16 v[80:83], v[140:143], v[206:209], v[80:83]
	v_mfma_f32_16x16x32_bf16 v[72:75], v[148:151], v[206:209], v[72:75]
	v_mfma_f32_16x16x32_bf16 v[124:127], v[144:147], v[186:189], v[124:127]
	v_mfma_f32_16x16x32_bf16 v[120:123], v[152:155], v[186:189], v[120:123]
	v_mfma_f32_16x16x32_bf16 v[112:115], v[144:147], v[194:197], v[112:115]
	v_mfma_f32_16x16x32_bf16 v[104:107], v[152:155], v[194:197], v[104:107]
	v_mfma_f32_16x16x32_bf16 v[96:99], v[144:147], v[202:205], v[96:99]
	v_mfma_f32_16x16x32_bf16 v[88:91], v[152:155], v[202:205], v[88:91]
	v_mfma_f32_16x16x32_bf16 v[80:83], v[144:147], v[210:213], v[80:83]
	v_mfma_f32_16x16x32_bf16 v[72:75], v[152:155], v[210:213], v[72:75]
	v_mfma_f32_16x16x32_bf16 v[116:119], v[166:169], v[182:185], v[116:119]
	v_mfma_f32_16x16x32_bf16 v[108:111], v[174:177], v[182:185], v[108:111]
	v_mfma_f32_16x16x32_bf16 v[100:103], v[166:169], v[190:193], v[100:103]
	v_mfma_f32_16x16x32_bf16 v[92:95], v[174:177], v[190:193], v[92:95]
	v_mfma_f32_16x16x32_bf16 v[84:87], v[166:169], v[198:201], v[84:87]
	v_mfma_f32_16x16x32_bf16 v[76:79], v[174:177], v[198:201], v[76:79]
	v_mfma_f32_16x16x32_bf16 v[68:71], v[166:169], v[206:209], v[68:71]
	v_mfma_f32_16x16x32_bf16 v[64:67], v[174:177], v[206:209], v[64:67]
	v_mfma_f32_16x16x32_bf16 v[116:119], v[170:173], v[186:189], v[116:119]
	v_mfma_f32_16x16x32_bf16 v[108:111], v[178:181], v[186:189], v[108:111]
	v_mfma_f32_16x16x32_bf16 v[100:103], v[170:173], v[194:197], v[100:103]
	v_mfma_f32_16x16x32_bf16 v[92:95], v[178:181], v[194:197], v[92:95]
	v_mfma_f32_16x16x32_bf16 v[84:87], v[170:173], v[202:205], v[84:87]
	v_mfma_f32_16x16x32_bf16 v[76:79], v[178:181], v[202:205], v[76:79]
	v_mfma_f32_16x16x32_bf16 v[68:71], v[170:173], v[210:213], v[68:71]
	v_mfma_f32_16x16x32_bf16 v[64:67], v[178:181], v[210:213], v[64:67]
	s_setprio 0
	s_barrier
	s_mov_b32 m0, s87
	ds_read_b128 v[182:185], v163 offset:16384
	ds_read_b128 v[186:189], v163 offset:17408
	ds_read_b128 v[190:193], v163 offset:18432
	ds_read_b128 v[194:197], v163 offset:19456
	ds_read_b128 v[198:201], v163 offset:20480
	ds_read_b128 v[202:205], v163 offset:21504
	ds_read_b128 v[206:209], v163 offset:22528
	ds_read_b128 v[210:213], v163 offset:23552
	global_load_lds_dwordx4 v132, s[62:63]
	s_mov_b32 m0, s84
	s_nop 0
	global_load_lds_dwordx4 v128, s[62:63]
	s_mov_b32 m0, s86
	s_nop 0
	global_load_lds_dwordx4 v132, s[64:65]
	s_mov_b32 m0, s85
	s_nop 0
	global_load_lds_dwordx4 v128, s[64:65]
	s_mov_b32 m0, s43
	s_nop 0
	global_load_lds_dwordx4 v134, s[60:61]
	s_mov_b32 m0, s45
	s_nop 0
	global_load_lds_dwordx4 v130, s[60:61]
	s_waitcnt vmcnt(8)
	s_waitcnt lgkmcnt(0)
	s_barrier
; #define PG8_STAGE(bufoff, gbase, voff) do { _Pragma("unroll") for (int _i = 0; _i < 2; ++_i) \
;         __builtin_amdgcn_global_load_lds((const unsigned*)((const char*)(gbase) + (voff)[_i]), (LAS unsigned*)(lds + (bufoff) + ldsw + _i * 8192), 16, 0, 0); } while (0)
; #define PG8_LDA(dst, b, h) do { _Pragma("unroll") for (int m = 0; m < 4; ++m) _Pragma("unroll") for (int k = 0; k < 2; ++k) dst[m][k] = *(const LAS bf16x8*)(lds + PG8_SA(b, h) + aoff + m * 2048 + k * 1024); } while (0)
; #define PG8_LDB(dst, b, h) do { _Pragma("unroll") for (int n = 0; n < 2; ++n) _Pragma("unroll") for (int k = 0; k < 2; ++k) dst[n][k] = *(const LAS bf16x8*)(lds + PG8_SB(b, h) + boff + n * 2048 + k * 1024); } while (0)
; #define PG8_MMA(ai, bj, At, Bt) do { __builtin_amdgcn_s_setprio(1); _Pragma("unroll") for (int m = 0; m < 4; ++m) _Pragma("unroll") for (int n = 0; n < 2; ++n) _Pragma("unroll") for (int k = 0; k < 2; ++k) \
;         acc[ai][bj][m][n] = __builtin_amdgcn_mfma_f32_16x16x32_bf16(Bt[n][k], At[m][k], acc[ai][bj][m][n], 0, 0, 0); __builtin_amdgcn_s_setprio(0); } while (0)
; #define PG8_WAIT_V(n) asm volatile("s_waitcnt vmcnt(" #n ")" ::: "memory")
; #define PG8_WAIT_L(n) asm volatile("s_waitcnt lgkmcnt(" #n ")" ::: "memory")
; #define PG8_BAR __builtin_amdgcn_s_barrier()
; #define PG8_SCHED __builtin_amdgcn_sched_barrier(0)
; template <int K, int LDA, int LDB, class Epi, class Sched>
; __device__ __forceinline__ void gemm_phase(LAS unsigned char* lds, const Gemm g, const Sched& S, const Epi& E, int wv) {
;     ...
;             PG8_WAIT_V(8); PG8_WAIT_L(0); PG8_BAR; PG8_MMA(1, 0, At, B0); PG8_MMA(1, 1, At, B1); PG8_BAR; PG8_SCHED;
;             PG8_LDB(B0, 1, 0); PG8_LDB(B1, 1, 1); PG8_SCHED; PG8_LDA(At, 1, 0); PG8_STAGE(PG8_SA(0, 1), a2 + hstepA, voffA);
;             PG8_WAIT_V(8); PG8_WAIT_L(0); PG8_BAR; PG8_MMA(0, 0, At, B0); PG8_MMA(0, 1, At, B1); PG8_BAR; PG8_SCHED;
	s_setprio 1
	v_mfma_f32_16x16x32_bf16 v[60:63], v[140:143], v[182:185], v[60:63]
	v_mfma_f32_16x16x32_bf16 v[56:59], v[148:151], v[182:185], v[56:59]
	v_mfma_f32_16x16x32_bf16 v[48:51], v[140:143], v[190:193], v[48:51]
	v_mfma_f32_16x16x32_bf16 v[40:43], v[148:151], v[190:193], v[40:43]
	v_mfma_f32_16x16x32_bf16 v[32:35], v[140:143], v[198:201], v[32:35]
	v_mfma_f32_16x16x32_bf16 v[24:27], v[148:151], v[198:201], v[24:27]
	v_mfma_f32_16x16x32_bf16 v[16:19], v[140:143], v[206:209], v[16:19]
	v_mfma_f32_16x16x32_bf16 v[8:11], v[148:151], v[206:209], v[8:11]
	v_mfma_f32_16x16x32_bf16 v[60:63], v[144:147], v[186:189], v[60:63]
	v_mfma_f32_16x16x32_bf16 v[56:59], v[152:155], v[186:189], v[56:59]
	v_mfma_f32_16x16x32_bf16 v[48:51], v[144:147], v[194:197], v[48:51]
	v_mfma_f32_16x16x32_bf16 v[40:43], v[152:155], v[194:197], v[40:43]
	v_mfma_f32_16x16x32_bf16 v[32:35], v[144:147], v[202:205], v[32:35]
	v_mfma_f32_16x16x32_bf16 v[24:27], v[152:155], v[202:205], v[24:27]
	v_mfma_f32_16x16x32_bf16 v[16:19], v[144:147], v[210:213], v[16:19]
	v_mfma_f32_16x16x32_bf16 v[8:11], v[152:155], v[210:213], v[8:11]
	v_mfma_f32_16x16x32_bf16 v[52:55], v[166:169], v[182:185], v[52:55]
	v_mfma_f32_16x16x32_bf16 v[44:47], v[174:177], v[182:185], v[44:47]
	v_mfma_f32_16x16x32_bf16 v[36:39], v[166:169], v[190:193], v[36:39]
	v_mfma_f32_16x16x32_bf16 v[28:31], v[174:177], v[190:193], v[28:31]
	v_mfma_f32_16x16x32_bf16 v[20:23], v[166:169], v[198:201], v[20:23]
	v_mfma_f32_16x16x32_bf16 v[12:15], v[174:177], v[198:201], v[12:15]
	v_mfma_f32_16x16x32_bf16 v[4:7], v[166:169], v[206:209], v[4:7]
	v_mfma_f32_16x16x32_bf16 v[0:3], v[174:177], v[206:209], v[0:3]
	v_mfma_f32_16x16x32_bf16 v[52:55], v[170:173], v[186:189], v[52:55]
	v_mfma_f32_16x16x32_bf16 v[44:47], v[178:181], v[186:189], v[44:47]
	v_mfma_f32_16x16x32_bf16 v[36:39], v[170:173], v[194:197], v[36:39]
	v_mfma_f32_16x16x32_bf16 v[28:31], v[178:181], v[194:197], v[28:31]
	v_mfma_f32_16x16x32_bf16 v[20:23], v[170:173], v[202:205], v[20:23]
	v_mfma_f32_16x16x32_bf16 v[12:15], v[178:181], v[202:205], v[12:15]
	v_mfma_f32_16x16x32_bf16 v[4:7], v[170:173], v[210:213], v[4:7]
	v_mfma_f32_16x16x32_bf16 v[0:3], v[178:181], v[210:213], v[0:3]
	s_setprio 0
	s_barrier
	v_add_u32_e32 v152, s83, v159
	v_add_u32_e32 v165, s82, v159
	ds_read_b128 v[140:143], v152
	ds_read_b128 v[144:147], v152 offset:1024
	ds_read_b128 v[148:151], v152 offset:2048
	ds_read_b128 v[152:155], v152 offset:3072
	ds_read_b128 v[166:169], v165
	ds_read_b128 v[170:173], v165 offset:1024
	ds_read_b128 v[174:177], v165 offset:2048
	ds_read_b128 v[178:181], v165 offset:3072
	s_mov_b32 m0, s68
	ds_read_b128 v[182:185], v163 offset:32768
	ds_read_b128 v[186:189], v163 offset:33792
	ds_read_b128 v[190:193], v163 offset:34816
	ds_read_b128 v[194:197], v163 offset:35840
	ds_read_b128 v[198:201], v163 offset:36864
	ds_read_b128 v[202:205], v163 offset:37888
	ds_read_b128 v[206:209], v163 offset:38912
	ds_read_b128 v[210:213], v163 offset:39936
	global_load_lds_dwordx4 v134, s[58:59]
	s_mov_b32 m0, s69
	s_nop 0
	global_load_lds_dwordx4 v130, s[58:59]
	s_waitcnt vmcnt(8)
	s_waitcnt lgkmcnt(0)
	s_barrier
	s_setprio 1
	v_mfma_f32_16x16x32_bf16 v[124:127], v[140:143], v[182:185], v[124:127]
	v_mfma_f32_16x16x32_bf16 v[120:123], v[148:151], v[182:185], v[120:123]
	v_mfma_f32_16x16x32_bf16 v[112:115], v[140:143], v[190:193], v[112:115]
	v_mfma_f32_16x16x32_bf16 v[104:107], v[148:151], v[190:193], v[104:107]
	v_mfma_f32_16x16x32_bf16 v[96:99], v[140:143], v[198:201], v[96:99]
	v_mfma_f32_16x16x32_bf16 v[88:91], v[148:151], v[198:201], v[88:91]
	v_mfma_f32_16x16x32_bf16 v[80:83], v[140:143], v[206:209], v[80:83]
	v_mfma_f32_16x16x32_bf16 v[72:75], v[148:151], v[206:209], v[72:75]
	v_mfma_f32_16x16x32_bf16 v[124:127], v[144:147], v[186:189], v[124:127]
	v_mfma_f32_16x16x32_bf16 v[120:123], v[152:155], v[186:189], v[120:123]
	v_mfma_f32_16x16x32_bf16 v[112:115], v[144:147], v[194:197], v[112:115]
	v_mfma_f32_16x16x32_bf16 v[104:107], v[152:155], v[194:197], v[104:107]
	v_mfma_f32_16x16x32_bf16 v[96:99], v[144:147], v[202:205], v[96:99]
	v_mfma_f32_16x16x32_bf16 v[88:91], v[152:155], v[202:205], v[88:91]
	v_mfma_f32_16x16x32_bf16 v[80:83], v[144:147], v[210:213], v[80:83]
	v_mfma_f32_16x16x32_bf16 v[72:75], v[152:155], v[210:213], v[72:75]
	v_mfma_f32_16x16x32_bf16 v[116:119], v[166:169], v[182:185], v[116:119]
	v_mfma_f32_16x16x32_bf16 v[108:111], v[174:177], v[182:185], v[108:111]
	v_mfma_f32_16x16x32_bf16 v[100:103], v[166:169], v[190:193], v[100:103]
	v_mfma_f32_16x16x32_bf16 v[92:95], v[174:177], v[190:193], v[92:95]
	v_mfma_f32_16x16x32_bf16 v[84:87], v[166:169], v[198:201], v[84:87]
	v_mfma_f32_16x16x32_bf16 v[76:79], v[174:177], v[198:201], v[76:79]
	v_mfma_f32_16x16x32_bf16 v[68:71], v[166:169], v[206:209], v[68:71]
	v_mfma_f32_16x16x32_bf16 v[64:67], v[174:177], v[206:209], v[64:67]
	v_mfma_f32_16x16x32_bf16 v[116:119], v[170:173], v[186:189], v[116:119]
	v_mfma_f32_16x16x32_bf16 v[108:111], v[178:181], v[186:189], v[108:111]
	v_mfma_f32_16x16x32_bf16 v[100:103], v[170:173], v[194:197], v[100:103]
	v_mfma_f32_16x16x32_bf16 v[92:95], v[178:181], v[194:197], v[92:95]
	v_mfma_f32_16x16x32_bf16 v[84:87], v[170:173], v[202:205], v[84:87]
	v_mfma_f32_16x16x32_bf16 v[76:79], v[178:181], v[202:205], v[76:79]
	v_mfma_f32_16x16x32_bf16 v[68:71], v[170:173], v[210:213], v[68:71]
	v_mfma_f32_16x16x32_bf16 v[64:67], v[178:181], v[210:213], v[64:67]
	s_setprio 0
	s_barrier
; #define PG8_STAGE(bufoff, gbase, voff) do { _Pragma("unroll") for (int _i = 0; _i < 2; ++_i) \
;         __builtin_amdgcn_global_load_lds((const unsigned*)((const char*)(gbase) + (voff)[_i]), (LAS unsigned*)(lds + (bufoff) + ldsw + _i * 8192), 16, 0, 0); } while (0)
; #define PG8_LDA(dst, b, h) do { _Pragma("unroll") for (int m = 0; m < 4; ++m) _Pragma("unroll") for (int k = 0; k < 2; ++k) dst[m][k] = *(const LAS bf16x8*)(lds + PG8_SA(b, h) + aoff + m * 2048 + k * 1024); } while (0)
; #define PG8_MMA(ai, bj, At, Bt) do { __builtin_amdgcn_s_setprio(1); _Pragma("unroll") for (int m = 0; m < 4; ++m) _Pragma("unroll") for (int n = 0; n < 2; ++n) _Pragma("unroll") for (int k = 0; k < 2; ++k) \
;         acc[ai][bj][m][n] = __builtin_amdgcn_mfma_f32_16x16x32_bf16(Bt[n][k], At[m][k], acc[ai][bj][m][n], 0, 0, 0); __builtin_amdgcn_s_setprio(0); } while (0)
; #define PG8_WAIT_V(n) asm volatile("s_waitcnt vmcnt(" #n ")" ::: "memory")
; #define PG8_WAIT_L(n) asm volatile("s_waitcnt lgkmcnt(" #n ")" ::: "memory")
; #define PG8_BAR __builtin_amdgcn_s_barrier()
; #define PG8_SCHED __builtin_amdgcn_sched_barrier(0)
; template <int K, int LDA, int LDB, class Epi, class Sched>
; __device__ __forceinline__ void gemm_phase(LAS unsigned char* lds, const Gemm g, const Sched& S, const Epi& E, int wv) {
;     ...
;             PG8_LDA(At, 1, 1); PG8_STAGE(PG8_SB(1, 0), b3, voffB); PG8_STAGE(PG8_SB(1, 1), b3 + hstepB, voffB); PG8_STAGE(PG8_SA(1, 0), a3, voffA);
;             PG8_WAIT_V(8); PG8_WAIT_L(0); PG8_BAR; PG8_MMA(1, 0, At, B0); PG8_MMA(1, 1, At, B1); PG8_BAR; PG8_SCHED;
;         }
;         if (wr == 0) PG8_BAR;
	s_mov_b32 m0, s81
	ds_read_b128 v[182:185], v163 offset:49152
	ds_read_b128 v[186:189], v163 offset:50176
	ds_read_b128 v[190:193], v163 offset:51200
	ds_read_b128 v[194:197], v163 offset:52224
	ds_read_b128 v[198:201], v163 offset:53248
	ds_read_b128 v[202:205], v163 offset:54272
	ds_read_b128 v[206:209], v163 offset:55296
	ds_read_b128 v[210:213], v163 offset:56320
	s_add_u32 s98, s62, s10
	s_addc_u32 s99, s63, s11
	global_load_lds_dwordx4 v132, s[98:99]
	s_mov_b32 m0, s79
	s_nop 0
	global_load_lds_dwordx4 v128, s[98:99]
	s_mov_b32 m0, s80
	s_nop 0
	global_load_lds_dwordx4 v132, s[56:57]
	s_mov_b32 m0, s78
	s_nop 0
	global_load_lds_dwordx4 v128, s[56:57]
	s_mov_b32 m0, s71
	s_nop 0
	s_add_u32 s100, s60, s10
	s_addc_u32 s101, s61, s11
	global_load_lds_dwordx4 v134, s[100:101]
	s_mov_b32 m0, s72
	s_nop 0
	global_load_lds_dwordx4 v130, s[100:101]
	s_waitcnt vmcnt(8)
	s_waitcnt lgkmcnt(0)
	s_barrier
	s_setprio 1
	v_mfma_f32_16x16x32_bf16 v[60:63], v[140:143], v[182:185], v[60:63]
	v_mfma_f32_16x16x32_bf16 v[56:59], v[148:151], v[182:185], v[56:59]
	v_mfma_f32_16x16x32_bf16 v[48:51], v[140:143], v[190:193], v[48:51]
	v_mfma_f32_16x16x32_bf16 v[40:43], v[148:151], v[190:193], v[40:43]
	v_mfma_f32_16x16x32_bf16 v[32:35], v[140:143], v[198:201], v[32:35]
	v_mfma_f32_16x16x32_bf16 v[24:27], v[148:151], v[198:201], v[24:27]
	v_mfma_f32_16x16x32_bf16 v[16:19], v[140:143], v[206:209], v[16:19]
	v_mfma_f32_16x16x32_bf16 v[8:11], v[148:151], v[206:209], v[8:11]
	v_mfma_f32_16x16x32_bf16 v[60:63], v[144:147], v[186:189], v[60:63]
	v_mfma_f32_16x16x32_bf16 v[56:59], v[152:155], v[186:189], v[56:59]
	v_mfma_f32_16x16x32_bf16 v[48:51], v[144:147], v[194:197], v[48:51]
	v_mfma_f32_16x16x32_bf16 v[40:43], v[152:155], v[194:197], v[40:43]
	v_mfma_f32_16x16x32_bf16 v[32:35], v[144:147], v[202:205], v[32:35]
	v_mfma_f32_16x16x32_bf16 v[24:27], v[152:155], v[202:205], v[24:27]
	v_mfma_f32_16x16x32_bf16 v[16:19], v[144:147], v[210:213], v[16:19]
	v_mfma_f32_16x16x32_bf16 v[8:11], v[152:155], v[210:213], v[8:11]
	v_mfma_f32_16x16x32_bf16 v[52:55], v[166:169], v[182:185], v[52:55]
	v_mfma_f32_16x16x32_bf16 v[44:47], v[174:177], v[182:185], v[44:47]
	v_mfma_f32_16x16x32_bf16 v[36:39], v[166:169], v[190:193], v[36:39]
	v_mfma_f32_16x16x32_bf16 v[28:31], v[174:177], v[190:193], v[28:31]
	v_mfma_f32_16x16x32_bf16 v[20:23], v[166:169], v[198:201], v[20:23]
	v_mfma_f32_16x16x32_bf16 v[12:15], v[174:177], v[198:201], v[12:15]
	v_mfma_f32_16x16x32_bf16 v[4:7], v[166:169], v[206:209], v[4:7]
	v_mfma_f32_16x16x32_bf16 v[0:3], v[174:177], v[206:209], v[0:3]
	v_mfma_f32_16x16x32_bf16 v[52:55], v[170:173], v[186:189], v[52:55]
	v_mfma_f32_16x16x32_bf16 v[44:47], v[178:181], v[186:189], v[44:47]
	v_mfma_f32_16x16x32_bf16 v[36:39], v[170:173], v[194:197], v[36:39]
	v_mfma_f32_16x16x32_bf16 v[28:31], v[178:181], v[194:197], v[28:31]
	v_mfma_f32_16x16x32_bf16 v[20:23], v[170:173], v[202:205], v[20:23]
	v_mfma_f32_16x16x32_bf16 v[12:15], v[178:181], v[202:205], v[12:15]
	v_mfma_f32_16x16x32_bf16 v[4:7], v[170:173], v[210:213], v[4:7]
	v_mfma_f32_16x16x32_bf16 v[0:3], v[178:181], v[210:213], v[0:3]
	s_setprio 0
	s_barrier
	s_andn2_b64 vcc, exec, s[8:9]
	s_mov_b64 s[56:57], -1
	s_mov_b64 s[8:9], 0
	s_mov_b64 s[58:59], 0x100
	s_cbranch_vccz .LBB0_1106
	s_and_b64 vcc, exec, s[28:29]
	s_cbranch_vccz .LBB0_1109
	s_barrier

; #define PG8_STAGE(bufoff, gbase, voff) do { _Pragma("unroll") for (int _i = 0; _i < 2; ++_i) \
;         __builtin_amdgcn_global_load_lds((const unsigned*)((const char*)(gbase) + (voff)[_i]), (LAS unsigned*)(lds + (bufoff) + ldsw + _i * 8192), 16, 0, 0); } while (0)
; #define PG8_LDA(dst, b, h) do { _Pragma("unroll") for (int m = 0; m < 4; ++m) _Pragma("unroll") for (int k = 0; k < 2; ++k) dst[m][k] = *(const LAS bf16x8*)(lds + PG8_SA(b, h) + aoff + m * 2048 + k * 1024); } while (0)
; #define PG8_LDB(dst, b, h) do { _Pragma("unroll") for (int n = 0; n < 2; ++n) _Pragma("unroll") for (int k = 0; k < 2; ++k) dst[n][k] = *(const LAS bf16x8*)(lds + PG8_SB(b, h) + boff + n * 2048 + k * 1024); } while (0)
; #define PG8_MMA(ai, bj, At, Bt) do { __builtin_amdgcn_s_setprio(1); _Pragma("unroll") for (int m = 0; m < 4; ++m) _Pragma("unroll") for (int n = 0; n < 2; ++n) _Pragma("unroll") for (int k = 0; k < 2; ++k) \
;         acc[ai][bj][m][n] = __builtin_amdgcn_mfma_f32_16x16x32_bf16(Bt[n][k], At[m][k], acc[ai][bj][m][n], 0, 0, 0); __builtin_amdgcn_s_setprio(0); } while (0)
; #define PG8_WAIT_V(n) asm volatile("s_waitcnt vmcnt(" #n ")" ::: "memory")
; #define PG8_WAIT_L(n) asm volatile("s_waitcnt lgkmcnt(" #n ")" ::: "memory")
; #define PG8_BAR __builtin_amdgcn_s_barrier()
; #define PG8_SCHED __builtin_amdgcn_sched_barrier(0)
; template <int K, int LDA, int LDB, class Epi, class Sched>
; __device__ __forceinline__ void gemm_phase(LAS unsigned char* lds, const Gemm g, const Sched& S, const Epi& E, int wv) {
;     ...
;         for (int t = 0; t < nt; t += 2) {
;             const bool last = (t == nt - 2);
;             const char* a1 = cA + (size_t)(t + 1) * kstep;
;             const char* a2 = last ? nA : cA + (size_t)(t + 2) * kstep; const char* b2 = last ? nB : cB + (size_t)(t + 2) * kstep;
;             const char* a3 = a2 + kstep; const char* b3 = b2 + kstep;
;             PG8_LDB(B0, 0, 0); PG8_LDB(B1, 0, 1); PG8_SCHED; PG8_LDA(At, 0, 0); PG8_STAGE(PG8_SA(1, 1), a1 + hstepA, voffA);
;             PG8_WAIT_V(8); PG8_WAIT_L(0); PG8_BAR; PG8_MMA(0, 0, At, B0); PG8_MMA(0, 1, At, B1); PG8_BAR; PG8_SCHED;
;             PG8_LDA(At, 0, 1); PG8_STAGE(PG8_SB(0, 0), b2, voffB); PG8_STAGE(PG8_SB(0, 1), b2 + hstepB, voffB); PG8_STAGE(PG8_SA(0, 0), a2, voffA);
;             PG8_WAIT_V(8); PG8_WAIT_L(0); PG8_BAR; PG8_MMA(1, 0, At, B0); PG8_MMA(1, 1, At, B1); PG8_BAR; PG8_SCHED;
.LBB0_1265:
	ds_read_b128 v[144:147], v185
	ds_read_b128 v[148:151], v185 offset:1024
	ds_read_b128 v[152:155], v185 offset:2048
	ds_read_b128 v[156:159], v185 offset:3072
	ds_read_b128 v[160:163], v186
	ds_read_b128 v[164:167], v186 offset:1024
	ds_read_b128 v[168:171], v186 offset:2048
	ds_read_b128 v[172:175], v186 offset:3072
	s_add_u32 s46, s44, 0xfff80080
	s_addc_u32 s47, s45, -1
	s_cmp_eq_u32 s62, 28
	s_cselect_b32 s49, s37, s47
	s_cselect_b32 s48, s58, s46
	s_cselect_b32 s47, s35, s61
	s_cselect_b32 s46, s59, s60
	v_lshl_add_u64 v[180:181], s[44:45], 0, v[136:137]
	s_add_i32 m0, s27, 0xc000
	ds_read_b128 v[176:179], v187
	ds_read_b128 v[188:191], v187 offset:1024
	ds_read_b128 v[192:195], v187 offset:2048
	ds_read_b128 v[196:199], v187 offset:3072
	ds_read_b128 v[200:203], v187 offset:4096
	ds_read_b128 v[204:207], v187 offset:5120
	ds_read_b128 v[208:211], v187 offset:6144
	ds_read_b128 v[212:215], v187 offset:7168
	global_load_lds_dwordx4 v136, s[44:45]
	v_lshl_add_u64 v[180:181], s[44:45], 0, v[138:139]
	s_add_i32 m0, s27, 0xe000
	s_nop 0
	global_load_lds_dwordx4 v138, s[44:45]
	s_waitcnt vmcnt(8)
	s_waitcnt lgkmcnt(0)
	s_barrier
	s_setprio 1
	v_mfma_f32_16x16x32_bf16 v[124:127], v[144:147], v[176:179], v[124:127]
	v_mfma_f32_16x16x32_bf16 v[120:123], v[152:155], v[176:179], v[120:123]
	v_mfma_f32_16x16x32_bf16 v[112:115], v[144:147], v[192:195], v[112:115]
	v_mfma_f32_16x16x32_bf16 v[104:107], v[152:155], v[192:195], v[104:107]
	v_mfma_f32_16x16x32_bf16 v[92:95], v[144:147], v[200:203], v[92:95]
	v_mfma_f32_16x16x32_bf16 v[88:91], v[152:155], v[200:203], v[88:91]
	v_mfma_f32_16x16x32_bf16 v[80:83], v[144:147], v[208:211], v[80:83]
	v_mfma_f32_16x16x32_bf16 v[72:75], v[152:155], v[208:211], v[72:75]
	v_mfma_f32_16x16x32_bf16 v[124:127], v[148:151], v[188:191], v[124:127]
	v_mfma_f32_16x16x32_bf16 v[120:123], v[156:159], v[188:191], v[120:123]
	v_mfma_f32_16x16x32_bf16 v[112:115], v[148:151], v[196:199], v[112:115]
	v_mfma_f32_16x16x32_bf16 v[104:107], v[156:159], v[196:199], v[104:107]
	v_mfma_f32_16x16x32_bf16 v[92:95], v[148:151], v[204:207], v[92:95]
	v_mfma_f32_16x16x32_bf16 v[88:91], v[156:159], v[204:207], v[88:91]
	v_mfma_f32_16x16x32_bf16 v[80:83], v[148:151], v[212:215], v[80:83]
	v_mfma_f32_16x16x32_bf16 v[72:75], v[156:159], v[212:215], v[72:75]
	v_mfma_f32_16x16x32_bf16 v[116:119], v[160:163], v[176:179], v[116:119]
	v_mfma_f32_16x16x32_bf16 v[108:111], v[168:171], v[176:179], v[108:111]
	v_mfma_f32_16x16x32_bf16 v[100:103], v[160:163], v[192:195], v[100:103]
	v_mfma_f32_16x16x32_bf16 v[96:99], v[168:171], v[192:195], v[96:99]
	v_mfma_f32_16x16x32_bf16 v[84:87], v[160:163], v[200:203], v[84:87]
	v_mfma_f32_16x16x32_bf16 v[76:79], v[168:171], v[200:203], v[76:79]
	v_mfma_f32_16x16x32_bf16 v[68:71], v[160:163], v[208:211], v[68:71]
	v_mfma_f32_16x16x32_bf16 v[64:67], v[168:171], v[208:211], v[64:67]
	v_mfma_f32_16x16x32_bf16 v[116:119], v[164:167], v[188:191], v[116:119]
	v_mfma_f32_16x16x32_bf16 v[108:111], v[172:175], v[188:191], v[108:111]
	v_mfma_f32_16x16x32_bf16 v[100:103], v[164:167], v[196:199], v[100:103]
	v_mfma_f32_16x16x32_bf16 v[96:99], v[172:175], v[196:199], v[96:99]
	v_mfma_f32_16x16x32_bf16 v[84:87], v[164:167], v[204:207], v[84:87]
	v_mfma_f32_16x16x32_bf16 v[76:79], v[172:175], v[204:207], v[76:79]
	v_mfma_f32_16x16x32_bf16 v[68:71], v[164:167], v[212:215], v[68:71]
	v_mfma_f32_16x16x32_bf16 v[64:67], v[172:175], v[212:215], v[64:67]
	s_setprio 0
	s_barrier
	s_add_i32 s63, s55, s24
	v_lshl_add_u64 v[180:181], s[46:47], 0, v[132:133]
	s_mov_b32 m0, s63
	ds_read_b128 v[176:179], v187 offset:16384
	ds_read_b128 v[188:191], v187 offset:17408
	ds_read_b128 v[192:195], v187 offset:18432
	ds_read_b128 v[196:199], v187 offset:19456
	ds_read_b128 v[200:203], v187 offset:20480
	ds_read_b128 v[204:207], v187 offset:21504
	ds_read_b128 v[208:211], v187 offset:22528
	ds_read_b128 v[212:215], v187 offset:23552
	global_load_lds_dwordx4 v132, s[46:47]
	s_add_i32 m0, s63, 0x2000
	s_add_u32 s64, s46, 0x80000
	v_lshl_add_u64 v[216:217], s[46:47], 0, v[128:129]
	s_addc_u32 s65, s47, 0
	s_add_i32 s63, s56, s24
	global_load_lds_dwordx4 v128, s[46:47]
	v_lshl_add_u64 v[218:219], s[64:65], 0, v[132:133]
	s_mov_b32 m0, s63
	v_lshl_add_u64 v[220:221], s[48:49], 0, v[130:131]
	global_load_lds_dwordx4 v132, s[64:65]
	v_lshl_add_u64 v[218:219], s[64:65], 0, v[128:129]
	s_add_i32 m0, s63, 0x2000
	s_nop 0
	global_load_lds_dwordx4 v128, s[64:65]
	v_lshl_add_u64 v[218:219], s[48:49], 0, v[134:135]
	s_mov_b32 m0, s27
	s_nop 0
	global_load_lds_dwordx4 v134, s[48:49]
	s_mov_b32 m0, s43
	s_nop 0
	global_load_lds_dwordx4 v130, s[48:49]
	s_waitcnt vmcnt(8)
	s_waitcnt lgkmcnt(0)
	s_barrier
; #define PG8_STAGE(bufoff, gbase, voff) do { _Pragma("unroll") for (int _i = 0; _i < 2; ++_i) \
;         __builtin_amdgcn_global_load_lds((const unsigned*)((const char*)(gbase) + (voff)[_i]), (LAS unsigned*)(lds + (bufoff) + ldsw + _i * 8192), 16, 0, 0); } while (0)
; #define PG8_LDA(dst, b, h) do { _Pragma("unroll") for (int m = 0; m < 4; ++m) _Pragma("unroll") for (int k = 0; k < 2; ++k) dst[m][k] = *(const LAS bf16x8*)(lds + PG8_SA(b, h) + aoff + m * 2048 + k * 1024); } while (0)
; #define PG8_LDB(dst, b, h) do { _Pragma("unroll") for (int n = 0; n < 2; ++n) _Pragma("unroll") for (int k = 0; k < 2; ++k) dst[n][k] = *(const LAS bf16x8*)(lds + PG8_SB(b, h) + boff + n * 2048 + k * 1024); } while (0)
; #define PG8_MMA(ai, bj, At, Bt) do { __builtin_amdgcn_s_setprio(1); _Pragma("unroll") for (int m = 0; m < 4; ++m) _Pragma("unroll") for (int n = 0; n < 2; ++n) _Pragma("unroll") for (int k = 0; k < 2; ++k) \
;         acc[ai][bj][m][n] = __builtin_amdgcn_mfma_f32_16x16x32_bf16(Bt[n][k], At[m][k], acc[ai][bj][m][n], 0, 0, 0); __builtin_amdgcn_s_setprio(0); } while (0)
; #define PG8_WAIT_V(n) asm volatile("s_waitcnt vmcnt(" #n ")" ::: "memory")
; #define PG8_WAIT_L(n) asm volatile("s_waitcnt lgkmcnt(" #n ")" ::: "memory")
; #define PG8_BAR __builtin_amdgcn_s_barrier()
; #define PG8_SCHED __builtin_amdgcn_sched_barrier(0)
; template <int K, int LDA, int LDB, class Epi, class Sched>
; __device__ __forceinline__ void gemm_phase(LAS unsigned char* lds, const Gemm g, const Sched& S, const Epi& E, int wv) {
;     ...
;             PG8_WAIT_V(8); PG8_WAIT_L(0); PG8_BAR; PG8_MMA(1, 0, At, B0); PG8_MMA(1, 1, At, B1); PG8_BAR; PG8_SCHED;
;             PG8_LDB(B0, 1, 0); PG8_LDB(B1, 1, 1); PG8_SCHED; PG8_LDA(At, 1, 0); PG8_STAGE(PG8_SA(0, 1), a2 + hstepA, voffA);
;             PG8_WAIT_V(8); PG8_WAIT_L(0); PG8_BAR; PG8_MMA(0, 0, At, B0); PG8_MMA(0, 1, At, B1); PG8_BAR; PG8_SCHED;
	s_setprio 1
	v_mfma_f32_16x16x32_bf16 v[60:63], v[144:147], v[176:179], v[60:63]
	v_mfma_f32_16x16x32_bf16 v[56:59], v[152:155], v[176:179], v[56:59]
	v_mfma_f32_16x16x32_bf16 v[48:51], v[144:147], v[192:195], v[48:51]
	v_mfma_f32_16x16x32_bf16 v[40:43], v[152:155], v[192:195], v[40:43]
	v_mfma_f32_16x16x32_bf16 v[28:31], v[144:147], v[200:203], v[28:31]
	v_mfma_f32_16x16x32_bf16 v[24:27], v[152:155], v[200:203], v[24:27]
	v_mfma_f32_16x16x32_bf16 v[16:19], v[144:147], v[208:211], v[16:19]
	v_mfma_f32_16x16x32_bf16 v[8:11], v[152:155], v[208:211], v[8:11]
	v_mfma_f32_16x16x32_bf16 v[60:63], v[148:151], v[188:191], v[60:63]
	v_mfma_f32_16x16x32_bf16 v[56:59], v[156:159], v[188:191], v[56:59]
	v_mfma_f32_16x16x32_bf16 v[48:51], v[148:151], v[196:199], v[48:51]
	v_mfma_f32_16x16x32_bf16 v[40:43], v[156:159], v[196:199], v[40:43]
	v_mfma_f32_16x16x32_bf16 v[28:31], v[148:151], v[204:207], v[28:31]
	v_mfma_f32_16x16x32_bf16 v[24:27], v[156:159], v[204:207], v[24:27]
	v_mfma_f32_16x16x32_bf16 v[16:19], v[148:151], v[212:215], v[16:19]
	v_mfma_f32_16x16x32_bf16 v[8:11], v[156:159], v[212:215], v[8:11]
	v_mfma_f32_16x16x32_bf16 v[52:55], v[160:163], v[176:179], v[52:55]
	v_mfma_f32_16x16x32_bf16 v[44:47], v[168:171], v[176:179], v[44:47]
	v_mfma_f32_16x16x32_bf16 v[36:39], v[160:163], v[192:195], v[36:39]
	v_mfma_f32_16x16x32_bf16 v[32:35], v[168:171], v[192:195], v[32:35]
	v_mfma_f32_16x16x32_bf16 v[20:23], v[160:163], v[200:203], v[20:23]
	v_mfma_f32_16x16x32_bf16 v[12:15], v[168:171], v[200:203], v[12:15]
	v_mfma_f32_16x16x32_bf16 v[4:7], v[160:163], v[208:211], v[4:7]
	v_mfma_f32_16x16x32_bf16 v[0:3], v[168:171], v[208:211], v[0:3]
	v_mfma_f32_16x16x32_bf16 v[52:55], v[164:167], v[188:191], v[52:55]
	v_mfma_f32_16x16x32_bf16 v[44:47], v[172:175], v[188:191], v[44:47]
	v_mfma_f32_16x16x32_bf16 v[36:39], v[164:167], v[196:199], v[36:39]
	v_mfma_f32_16x16x32_bf16 v[32:35], v[172:175], v[196:199], v[32:35]
	v_mfma_f32_16x16x32_bf16 v[20:23], v[164:167], v[204:207], v[20:23]
	v_mfma_f32_16x16x32_bf16 v[12:15], v[172:175], v[204:207], v[12:15]
	v_mfma_f32_16x16x32_bf16 v[4:7], v[164:167], v[212:215], v[4:7]
	v_mfma_f32_16x16x32_bf16 v[0:3], v[172:175], v[212:215], v[0:3]
	s_setprio 0
	s_barrier
	s_add_i32 s63, 0, 0x18000
	v_add_u32_e32 v140, s63, v183
	s_add_i32 s64, 0, 0x1c000
	ds_read_b128 v[144:147], v140
	ds_read_b128 v[148:151], v140 offset:1024
	ds_read_b128 v[152:155], v140 offset:2048
	ds_read_b128 v[156:159], v140 offset:3072
	v_add_u32_e32 v140, s64, v183
	ds_read_b128 v[160:163], v140
	ds_read_b128 v[164:167], v140 offset:1024
	ds_read_b128 v[168:171], v140 offset:2048
	ds_read_b128 v[172:175], v140 offset:3072
	s_add_u32 s48, s48, 0x80000
	s_addc_u32 s49, s49, 0
	s_mov_b32 m0, s50
	v_lshl_add_u64 v[224:225], s[48:49], 0, v[134:135]
	ds_read_b128 v[176:179], v187 offset:32768
	ds_read_b128 v[188:191], v187 offset:33792
	ds_read_b128 v[192:195], v187 offset:34816
	ds_read_b128 v[196:199], v187 offset:35840
	ds_read_b128 v[200:203], v187 offset:36864
	ds_read_b128 v[204:207], v187 offset:37888
	ds_read_b128 v[208:211], v187 offset:38912
	ds_read_b128 v[212:215], v187 offset:39936
	global_load_lds_dwordx4 v134, s[48:49]
	v_lshl_add_u64 v[224:225], s[48:49], 0, v[130:131]
	s_mov_b32 m0, s51
	s_nop 0
	global_load_lds_dwordx4 v130, s[48:49]
	s_waitcnt vmcnt(8)
	s_waitcnt lgkmcnt(0)
	s_barrier
	s_setprio 1
	v_mfma_f32_16x16x32_bf16 v[124:127], v[144:147], v[176:179], v[124:127]
	v_mfma_f32_16x16x32_bf16 v[120:123], v[152:155], v[176:179], v[120:123]
	v_mfma_f32_16x16x32_bf16 v[112:115], v[144:147], v[192:195], v[112:115]
	v_mfma_f32_16x16x32_bf16 v[104:107], v[152:155], v[192:195], v[104:107]
	v_mfma_f32_16x16x32_bf16 v[92:95], v[144:147], v[200:203], v[92:95]
	v_mfma_f32_16x16x32_bf16 v[88:91], v[152:155], v[200:203], v[88:91]
	v_mfma_f32_16x16x32_bf16 v[80:83], v[144:147], v[208:211], v[80:83]
	v_mfma_f32_16x16x32_bf16 v[72:75], v[152:155], v[208:211], v[72:75]
	v_mfma_f32_16x16x32_bf16 v[124:127], v[148:151], v[188:191], v[124:127]
	v_mfma_f32_16x16x32_bf16 v[120:123], v[156:159], v[188:191], v[120:123]
	v_mfma_f32_16x16x32_bf16 v[112:115], v[148:151], v[196:199], v[112:115]
	v_mfma_f32_16x16x32_bf16 v[104:107], v[156:159], v[196:199], v[104:107]
	v_mfma_f32_16x16x32_bf16 v[92:95], v[148:151], v[204:207], v[92:95]
	v_mfma_f32_16x16x32_bf16 v[88:91], v[156:159], v[204:207], v[88:91]
	v_mfma_f32_16x16x32_bf16 v[80:83], v[148:151], v[212:215], v[80:83]
	v_mfma_f32_16x16x32_bf16 v[72:75], v[156:159], v[212:215], v[72:75]
	v_mfma_f32_16x16x32_bf16 v[116:119], v[160:163], v[176:179], v[116:119]
	v_mfma_f32_16x16x32_bf16 v[108:111], v[168:171], v[176:179], v[108:111]
	v_mfma_f32_16x16x32_bf16 v[100:103], v[160:163], v[192:195], v[100:103]
	v_mfma_f32_16x16x32_bf16 v[96:99], v[168:171], v[192:195], v[96:99]
	v_mfma_f32_16x16x32_bf16 v[84:87], v[160:163], v[200:203], v[84:87]
	v_mfma_f32_16x16x32_bf16 v[76:79], v[168:171], v[200:203], v[76:79]
	v_mfma_f32_16x16x32_bf16 v[68:71], v[160:163], v[208:211], v[68:71]
	v_mfma_f32_16x16x32_bf16 v[64:67], v[168:171], v[208:211], v[64:67]
	v_mfma_f32_16x16x32_bf16 v[116:119], v[164:167], v[188:191], v[116:119]
	v_mfma_f32_16x16x32_bf16 v[108:111], v[172:175], v[188:191], v[108:111]
	v_mfma_f32_16x16x32_bf16 v[100:103], v[164:167], v[196:199], v[100:103]
	v_mfma_f32_16x16x32_bf16 v[96:99], v[172:175], v[196:199], v[96:99]
	v_mfma_f32_16x16x32_bf16 v[84:87], v[164:167], v[204:207], v[84:87]
	v_mfma_f32_16x16x32_bf16 v[76:79], v[172:175], v[204:207], v[76:79]
	v_mfma_f32_16x16x32_bf16 v[68:71], v[164:167], v[212:215], v[68:71]
	v_mfma_f32_16x16x32_bf16 v[64:67], v[172:175], v[212:215], v[64:67]
	s_setprio 0
	s_barrier
; #define PG8_STAGE(bufoff, gbase, voff) do { _Pragma("unroll") for (int _i = 0; _i < 2; ++_i) \
;         __builtin_amdgcn_global_load_lds((const unsigned*)((const char*)(gbase) + (voff)[_i]), (LAS unsigned*)(lds + (bufoff) + ldsw + _i * 8192), 16, 0, 0); } while (0)
; #define PG8_LDA(dst, b, h) do { _Pragma("unroll") for (int m = 0; m < 4; ++m) _Pragma("unroll") for (int k = 0; k < 2; ++k) dst[m][k] = *(const LAS bf16x8*)(lds + PG8_SA(b, h) + aoff + m * 2048 + k * 1024); } while (0)
; #define PG8_MMA(ai, bj, At, Bt) do { __builtin_amdgcn_s_setprio(1); _Pragma("unroll") for (int m = 0; m < 4; ++m) _Pragma("unroll") for (int n = 0; n < 2; ++n) _Pragma("unroll") for (int k = 0; k < 2; ++k) \
;         acc[ai][bj][m][n] = __builtin_amdgcn_mfma_f32_16x16x32_bf16(Bt[n][k], At[m][k], acc[ai][bj][m][n], 0, 0, 0); __builtin_amdgcn_s_setprio(0); } while (0)
; #define PG8_WAIT_V(n) asm volatile("s_waitcnt vmcnt(" #n ")" ::: "memory")
; #define PG8_WAIT_L(n) asm volatile("s_waitcnt lgkmcnt(" #n ")" ::: "memory")
; #define PG8_BAR __builtin_amdgcn_s_barrier()
; #define PG8_SCHED __builtin_amdgcn_sched_barrier(0)
; template <int K, int LDA, int LDB, class Epi, class Sched>
; __device__ __forceinline__ void gemm_phase(LAS unsigned char* lds, const Gemm g, const Sched& S, const Epi& E, int wv) {
;     ...
;             PG8_LDA(At, 1, 1); PG8_STAGE(PG8_SB(1, 0), b3, voffB); PG8_STAGE(PG8_SB(1, 1), b3 + hstepB, voffB); PG8_STAGE(PG8_SA(1, 0), a3, voffA);
;             PG8_WAIT_V(8); PG8_WAIT_L(0); PG8_BAR; PG8_MMA(1, 0, At, B0); PG8_MMA(1, 1, At, B1); PG8_BAR; PG8_SCHED;
;         }
;         if (wr == 0) PG8_BAR;
	s_add_i32 s48, s63, s24
	v_lshl_add_u64 v[180:181], v[180:181], 0, s[20:21]
	s_mov_b32 m0, s48
	ds_read_b128 v[176:179], v187 offset:49152
	ds_read_b128 v[188:191], v187 offset:50176
	ds_read_b128 v[192:195], v187 offset:51200
	ds_read_b128 v[196:199], v187 offset:52224
	ds_read_b128 v[200:203], v187 offset:53248
	ds_read_b128 v[204:207], v187 offset:54272
	ds_read_b128 v[208:211], v187 offset:55296
	ds_read_b128 v[212:215], v187 offset:56320
	s_add_u32 s98, s46, s20
	s_addc_u32 s99, s47, s21
	global_load_lds_dwordx4 v132, s[98:99]
	s_add_i32 m0, s48, 0x2000
	s_add_u32 s46, s46, 0x80080
	v_lshl_add_u64 v[180:181], v[216:217], 0, s[20:21]
	s_addc_u32 s47, s47, 0
	s_add_i32 s48, s64, s24
	global_load_lds_dwordx4 v[180:181], off
	v_lshl_add_u64 v[180:181], s[46:47], 0, v[132:133]
	s_mov_b32 m0, s48
	s_nop 0
	global_load_lds_dwordx4 v132, s[46:47]
	v_lshl_add_u64 v[180:181], s[46:47], 0, v[128:129]
	s_add_i32 m0, s48, 0x2000
	s_nop 0
	global_load_lds_dwordx4 v128, s[46:47]
	v_lshl_add_u64 v[180:181], v[218:219], 0, s[20:21]
	s_mov_b32 m0, s53
	s_nop 0
	global_load_lds_dwordx4 v[180:181], off
	v_lshl_add_u64 v[180:181], v[220:221], 0, s[20:21]
	s_mov_b32 m0, s54
	s_nop 0
	global_load_lds_dwordx4 v[180:181], off
	s_waitcnt vmcnt(8)
	s_waitcnt lgkmcnt(0)
	s_barrier
	s_setprio 1
	v_mfma_f32_16x16x32_bf16 v[60:63], v[144:147], v[176:179], v[60:63]
	v_mfma_f32_16x16x32_bf16 v[56:59], v[152:155], v[176:179], v[56:59]
	v_mfma_f32_16x16x32_bf16 v[48:51], v[144:147], v[192:195], v[48:51]
	v_mfma_f32_16x16x32_bf16 v[40:43], v[152:155], v[192:195], v[40:43]
	v_mfma_f32_16x16x32_bf16 v[28:31], v[144:147], v[200:203], v[28:31]
	v_mfma_f32_16x16x32_bf16 v[24:27], v[152:155], v[200:203], v[24:27]
	v_mfma_f32_16x16x32_bf16 v[16:19], v[144:147], v[208:211], v[16:19]
	v_mfma_f32_16x16x32_bf16 v[8:11], v[152:155], v[208:211], v[8:11]
	v_mfma_f32_16x16x32_bf16 v[60:63], v[148:151], v[188:191], v[60:63]
	v_mfma_f32_16x16x32_bf16 v[56:59], v[156:159], v[188:191], v[56:59]
	v_mfma_f32_16x16x32_bf16 v[48:51], v[148:151], v[196:199], v[48:51]
	v_mfma_f32_16x16x32_bf16 v[40:43], v[156:159], v[196:199], v[40:43]
	v_mfma_f32_16x16x32_bf16 v[28:31], v[148:151], v[204:207], v[28:31]
	v_mfma_f32_16x16x32_bf16 v[24:27], v[156:159], v[204:207], v[24:27]
	v_mfma_f32_16x16x32_bf16 v[16:19], v[148:151], v[212:215], v[16:19]
	v_mfma_f32_16x16x32_bf16 v[8:11], v[156:159], v[212:215], v[8:11]
	v_mfma_f32_16x16x32_bf16 v[52:55], v[160:163], v[176:179], v[52:55]
	v_mfma_f32_16x16x32_bf16 v[44:47], v[168:171], v[176:179], v[44:47]
	v_mfma_f32_16x16x32_bf16 v[36:39], v[160:163], v[192:195], v[36:39]
	v_mfma_f32_16x16x32_bf16 v[32:35], v[168:171], v[192:195], v[32:35]
	v_mfma_f32_16x16x32_bf16 v[20:23], v[160:163], v[200:203], v[20:23]
	v_mfma_f32_16x16x32_bf16 v[12:15], v[168:171], v[200:203], v[12:15]
	v_mfma_f32_16x16x32_bf16 v[4:7], v[160:163], v[208:211], v[4:7]
	v_mfma_f32_16x16x32_bf16 v[0:3], v[168:171], v[208:211], v[0:3]
	v_mfma_f32_16x16x32_bf16 v[52:55], v[164:167], v[188:191], v[52:55]
	v_mfma_f32_16x16x32_bf16 v[44:47], v[172:175], v[188:191], v[44:47]
	v_mfma_f32_16x16x32_bf16 v[36:39], v[164:167], v[196:199], v[36:39]
	v_mfma_f32_16x16x32_bf16 v[32:35], v[172:175], v[196:199], v[32:35]
	v_mfma_f32_16x16x32_bf16 v[20:23], v[164:167], v[204:207], v[20:23]
	v_mfma_f32_16x16x32_bf16 v[12:15], v[172:175], v[204:207], v[12:15]
	v_mfma_f32_16x16x32_bf16 v[4:7], v[164:167], v[212:215], v[4:7]
	v_mfma_f32_16x16x32_bf16 v[0:3], v[172:175], v[212:215], v[0:3]
	s_setprio 0
	s_barrier
	s_add_i32 s62, s62, 2
	s_add_u32 s44, s44, 0x100
	s_addc_u32 s45, s45, 0
	s_add_u32 s60, s60, 0x100
	s_addc_u32 s61, s61, 0
	s_cmp_gt_u32 s62, 29
	s_cbranch_scc0 .LBB0_1265
	s_and_b64 vcc, exec, s[28:29]
	s_cbranch_vccz .LBB0_1268
	s_barrier
